# hazard fix: wait states restored inside the memoised rstd slices (trans->VALU, v_cmp->v_cndmask)
# speedup vs baseline: 1.0033x; 1.0033x over previous
; DI float rstd_from16(const float* p, float inv_n) {
;   const f32x4 a = *(const f32x4*)p, b = *(const f32x4*)(p + 4), c = *(const f32x4*)(p + 8), d = *(const f32x4*)(p + 12);
;   const float s = ((a[0] + a[1]) + (a[2] + a[3])) + ((b[0] + b[1]) + (b[2] + b[3])) + ((c[0] + c[1]) + (c[2] + c[3])) + ((d[0] + d[1]) + (d[2] + d[3]));
;   return rsqrtf(s * inv_n + EPS_);
; template <bool SWAP> DI void inproj_tile(const Params& p, int layer, int tm, int tn, bf16_t* smem) {
;     ...
;       bf16_t* dbuf; int dld, dcol, kind = 0; float qs = 1.f; int cslot = 0;
;       if (slab < 8) { dbuf = (bf16_t*)(p.ws + O_NSAQ); dld = 512; dcol = slab * 64; qs = QS64_; }
;       else if (slab < 12) { dbuf = (bf16_t*)(p.ws + O_KVCMP); dld = 256; dcol = (slab - 8) * 64; }
;       else if (slab < 16) { dbuf = (bf16_t*)(p.ws + (slab < 14 ? O_KSLC : O_KWIN)); dld = 128; dcol = (slab & 1) * 64; kind = 1; }
;       else if (slab < 28) { dbuf = (bf16_t*)(p.ws + O_FOXQ); dld = 512; dcol = (slab - 20) * 64; qs = QS64_; }
;       else if (slab < 36) { dbuf = (bf16_t*)(p.ws + O_FOXK); dld = 512; dcol = (slab - 28) * 64; }
;       else if (slab < 50) { dbuf = (bf16_t*)(p.ws + O_CQ); dld = 384; dcol = (slab - 44) * 64; kind = 2; cslot = slab - 44; }
;       else { dbuf = (bf16_t*)(p.ws + O_CKV); dld = 256; dcol = (slab - 50) * 64; kind = 2; cslot = 8 + slab - 50; }
; #pragma unroll
;       for (int i = 0; i < 8; ++i) {
;         const int row = i * 16 + l15, t = trow0 + row; const float rs = rstd_from16(ssq + (size_t)t * 16, 1.f / 1024.f) * qs;
.LBB0_200:
.LBB0_201:
	s_or_saveexec_b64 s[0:1], s[0:1]
	v_mov_b32_e32 v131, s33
	s_xor_b64 exec, exec, s[0:1]
	v_lshlrev_b32_e32 v130, 6, v136
	v_mov_b32_e32 v132, 0
	v_mov_b32_e32 v131, 0x3e38aa3b
	v_mov_b64_e32 v[128:129], 0x200
	v_mov_b64_e32 v[134:135], s[28:29]
	s_andn2_b64 s[2:3], s[2:3], exec
	s_andn2_b64 s[46:47], s[46:47], exec
	s_or_b64 exec, exec, s[0:1]
	v_or_b32_e32 v138, v147, v146
	v_ashrrev_i32_e32 v139, 31, v138
	v_lshlrev_b64 v[136:137], 6, v[138:139]
	v_lshl_add_u64 v[136:137], s[8:9], 0, v[136:137]
	s_xor_b64 s[48:49], s[2:3], -1
	v_cmp_gt_u32_e32 vcc, 32, v145
	v_bfe_u32 v244, v136, 6, 8
	v_lshlrev_b32_e32 v244, 3, v244
	v_add_u32_e32 v244, 0x24010, v244
	v_or_b32_e32 v246, 1, v136
	ds_read_b64 v[248:249], v244
	s_waitcnt lgkmcnt(0)
	v_cmp_ne_u32_e64 s[100:101], v248, v246
	s_nop 1
	s_and_saveexec_b64 s[98:99], s[100:101]
	s_cbranch_execz .LrcA0_0
	global_load_dwordx4 v[140:143], v[136:137], off
	global_load_dwordx4 v[148:151], v[136:137], off offset:16
	global_load_dwordx4 v[152:155], v[136:137], off offset:32
	global_load_dwordx4 v[156:159], v[136:137], off offset:48
	s_waitcnt vmcnt(3)
	v_mov_b32_e32 v136, v141
	v_mov_b32_e32 v137, v142
	v_mov_b32_e32 v141, v143
	s_waitcnt vmcnt(2)
	v_mov_b32_e32 v142, v149
	v_mov_b32_e32 v143, v150
	v_mov_b32_e32 v149, v151
	v_pk_add_f32 v[136:137], v[136:137], v[140:141]
	v_pk_add_f32 v[140:141], v[142:143], v[148:149]
	v_pk_add_f32 v[136:137], v[136:137], v[136:137] op_sel:[0,1] op_sel_hi:[1,0]
	v_pk_add_f32 v[140:141], v[140:141], v[140:141] op_sel:[0,1] op_sel_hi:[1,0]
	s_waitcnt vmcnt(1)
	v_add_f32_e32 v150, v152, v153
	v_add_f32_e32 v152, v154, v155
	s_waitcnt vmcnt(0)
	v_mov_b32_e32 v151, v158
	v_mov_b32_e32 v153, v159
	v_mov_b32_e32 v137, v156
	v_mov_b32_e32 v141, v157
	v_pk_add_f32 v[142:143], v[150:151], v[152:153]
	v_pk_add_f32 v[136:137], v[136:137], v[140:141]
	s_nop 0
	v_pk_add_f32 v[136:137], v[136:137], v[142:143]
	s_nop 0
	v_add_f32_e32 v136, v136, v137
	v_fmamk_f32 v136, v136, 0x3a800000, v185
	v_mul_f32_e32 v137, 0x4b800000, v136
	v_cmp_gt_f32_e64 s[0:1], s60, v136
	s_nop 1
	s_nop 0
	v_cndmask_b32_e64 v136, v136, v137, s[0:1]
	v_rsq_f32_e32 v136, v136
	s_nop 0
	v_mul_f32_e32 v137, 0x45800000, v136
	v_cndmask_b32_e64 v136, v136, v137, s[0:1]
	s_nop 0
	v_mov_b32_e32 v247, v136
	ds_write_b64 v244, v[246:247]

; DI float rstd_from16(const float* p, float inv_n) {
;   const f32x4 a = *(const f32x4*)p, b = *(const f32x4*)(p + 4), c = *(const f32x4*)(p + 8), d = *(const f32x4*)(p + 12);
;   const float s = ((a[0] + a[1]) + (a[2] + a[3])) + ((b[0] + b[1]) + (b[2] + b[3])) + ((c[0] + c[1]) + (c[2] + c[3])) + ((d[0] + d[1]) + (d[2] + d[3]));
;   return rsqrtf(s * inv_n + EPS_);
; template <bool SWAP> DI void inproj_tile(const Params& p, int layer, int tm, int tn, bf16_t* smem) {
;     ...
;       for (int i = 0; i < 8; ++i) {
;         const int row = i * 16 + l15, t = trow0 + row; const float rs = rstd_from16(ssq + (size_t)t * 16, 1.f / 1024.f) * qs;
.LBB0_210:
	s_or_b64 exec, exec, s[50:51]
	v_or3_b32 v138, v146, v147, 16
	v_ashrrev_i32_e32 v139, 31, v138
	s_waitcnt lgkmcnt(0)
	v_lshlrev_b64 v[136:137], 6, v[138:139]
	v_lshl_add_u64 v[136:137], s[8:9], 0, v[136:137]
	v_bfe_u32 v244, v136, 6, 8
	v_lshlrev_b32_e32 v244, 3, v244
	v_add_u32_e32 v244, 0x24010, v244
	v_or_b32_e32 v246, 1, v136
	ds_read_b64 v[248:249], v244
	s_waitcnt lgkmcnt(0)
	v_cmp_ne_u32_e64 s[100:101], v248, v246
	s_nop 1
	s_and_saveexec_b64 s[98:99], s[100:101]
	s_cbranch_execz .LrcA0_1
	global_load_dwordx4 v[140:143], v[136:137], off
	global_load_dwordx4 v[152:155], v[136:137], off offset:16
	global_load_dwordx4 v[156:159], v[136:137], off offset:32
	global_load_dwordx4 v[160:163], v[136:137], off offset:48
	s_waitcnt vmcnt(3)
	v_mov_b32_e32 v136, v141
	v_mov_b32_e32 v137, v142
	v_mov_b32_e32 v141, v143
	s_waitcnt vmcnt(2)
	v_mov_b32_e32 v142, v153
	v_mov_b32_e32 v143, v154
	v_mov_b32_e32 v153, v155
	v_pk_add_f32 v[136:137], v[136:137], v[140:141]
	v_pk_add_f32 v[140:141], v[142:143], v[152:153]
	v_pk_add_f32 v[136:137], v[136:137], v[136:137] op_sel:[0,1] op_sel_hi:[1,0]
	v_pk_add_f32 v[140:141], v[140:141], v[140:141] op_sel:[0,1] op_sel_hi:[1,0]
	s_waitcnt vmcnt(1)
	v_add_f32_e32 v154, v156, v157
	v_add_f32_e32 v156, v158, v159
	s_waitcnt vmcnt(0)
	v_mov_b32_e32 v155, v162
	v_mov_b32_e32 v157, v163
	v_mov_b32_e32 v137, v160
	v_mov_b32_e32 v141, v161
	v_pk_add_f32 v[142:143], v[154:155], v[156:157]
	v_pk_add_f32 v[136:137], v[136:137], v[140:141]
	s_nop 0
	v_pk_add_f32 v[136:137], v[136:137], v[142:143]
	s_nop 0
	v_add_f32_e32 v136, v136, v137
	v_fmamk_f32 v136, v136, 0x3a800000, v185
	v_mul_f32_e32 v137, 0x4b800000, v136
	v_cmp_gt_f32_e64 s[2:3], s60, v136
	s_nop 1
	s_nop 0
	v_cndmask_b32_e64 v136, v136, v137, s[2:3]
	v_rsq_f32_e32 v136, v136
	s_nop 0
	v_mul_f32_e32 v137, 0x45800000, v136
	v_cndmask_b32_e64 v136, v136, v137, s[2:3]
	s_nop 0
	v_mov_b32_e32 v247, v136
	ds_write_b64 v244, v[246:247]

; DI float rstd_from16(const float* p, float inv_n) {
;   const f32x4 a = *(const f32x4*)p, b = *(const f32x4*)(p + 4), c = *(const f32x4*)(p + 8), d = *(const f32x4*)(p + 12);
;   const float s = ((a[0] + a[1]) + (a[2] + a[3])) + ((b[0] + b[1]) + (b[2] + b[3])) + ((c[0] + c[1]) + (c[2] + c[3])) + ((d[0] + d[1]) + (d[2] + d[3]));
;   return rsqrtf(s * inv_n + EPS_);
; template <bool SWAP> DI void inproj_tile(const Params& p, int layer, int tm, int tn, bf16_t* smem) {
;     ...
;       for (int i = 0; i < 8; ++i) {
;         const int row = i * 16 + l15, t = trow0 + row; const float rs = rstd_from16(ssq + (size_t)t * 16, 1.f / 1024.f) * qs;
.LBB0_217:
	s_or_b64 exec, exec, s[50:51]
	v_or3_b32 v138, v146, v147, 32
	v_ashrrev_i32_e32 v139, 31, v138
	s_waitcnt lgkmcnt(0)
	v_lshlrev_b64 v[136:137], 6, v[138:139]
	v_lshl_add_u64 v[136:137], s[8:9], 0, v[136:137]
	v_bfe_u32 v244, v136, 6, 8
	v_lshlrev_b32_e32 v244, 3, v244
	v_add_u32_e32 v244, 0x24010, v244
	v_or_b32_e32 v246, 1, v136
	ds_read_b64 v[248:249], v244
	s_waitcnt lgkmcnt(0)
	v_cmp_ne_u32_e64 s[100:101], v248, v246
	s_nop 1
	s_and_saveexec_b64 s[98:99], s[100:101]
	s_cbranch_execz .LrcA0_2
	global_load_dwordx4 v[140:143], v[136:137], off
	global_load_dwordx4 v[152:155], v[136:137], off offset:16
	global_load_dwordx4 v[156:159], v[136:137], off offset:32
	global_load_dwordx4 v[160:163], v[136:137], off offset:48
	s_waitcnt vmcnt(3)
	v_mov_b32_e32 v136, v141
	v_mov_b32_e32 v137, v142
	v_mov_b32_e32 v141, v143
	s_waitcnt vmcnt(2)
	v_mov_b32_e32 v142, v153
	v_mov_b32_e32 v143, v154
	v_mov_b32_e32 v153, v155
	v_pk_add_f32 v[136:137], v[136:137], v[140:141]
	v_pk_add_f32 v[140:141], v[142:143], v[152:153]
	v_pk_add_f32 v[136:137], v[136:137], v[136:137] op_sel:[0,1] op_sel_hi:[1,0]
	v_pk_add_f32 v[140:141], v[140:141], v[140:141] op_sel:[0,1] op_sel_hi:[1,0]
	s_waitcnt vmcnt(1)
	v_add_f32_e32 v154, v156, v157
	v_add_f32_e32 v156, v158, v159
	s_waitcnt vmcnt(0)
	v_mov_b32_e32 v155, v162
	v_mov_b32_e32 v157, v163
	v_mov_b32_e32 v137, v160
	v_mov_b32_e32 v141, v161
	v_pk_add_f32 v[142:143], v[154:155], v[156:157]
	v_pk_add_f32 v[136:137], v[136:137], v[140:141]
	s_nop 0
	v_pk_add_f32 v[136:137], v[136:137], v[142:143]
	s_nop 0
	v_add_f32_e32 v136, v136, v137
	v_fmamk_f32 v136, v136, 0x3a800000, v185
	v_mul_f32_e32 v137, 0x4b800000, v136
	v_cmp_gt_f32_e64 s[2:3], s60, v136
	s_nop 1
	s_nop 0
	v_cndmask_b32_e64 v136, v136, v137, s[2:3]
	v_rsq_f32_e32 v136, v136
	s_nop 0
	v_mul_f32_e32 v137, 0x45800000, v136
	v_cndmask_b32_e64 v136, v136, v137, s[2:3]
	s_nop 0
	v_mov_b32_e32 v247, v136
	ds_write_b64 v244, v[246:247]

; DI float rstd_from16(const float* p, float inv_n) {
;   const f32x4 a = *(const f32x4*)p, b = *(const f32x4*)(p + 4), c = *(const f32x4*)(p + 8), d = *(const f32x4*)(p + 12);
;   const float s = ((a[0] + a[1]) + (a[2] + a[3])) + ((b[0] + b[1]) + (b[2] + b[3])) + ((c[0] + c[1]) + (c[2] + c[3])) + ((d[0] + d[1]) + (d[2] + d[3]));
;   return rsqrtf(s * inv_n + EPS_);
; template <bool SWAP> DI void inproj_tile(const Params& p, int layer, int tm, int tn, bf16_t* smem) {
;     ...
;       for (int i = 0; i < 8; ++i) {
;         const int row = i * 16 + l15, t = trow0 + row; const float rs = rstd_from16(ssq + (size_t)t * 16, 1.f / 1024.f) * qs;
.LBB0_224:
	s_or_b64 exec, exec, s[50:51]
	v_or3_b32 v138, v146, v147, 48
	v_ashrrev_i32_e32 v139, 31, v138
	s_waitcnt lgkmcnt(0)
	v_lshlrev_b64 v[136:137], 6, v[138:139]
	v_lshl_add_u64 v[136:137], s[8:9], 0, v[136:137]
	v_bfe_u32 v244, v136, 6, 8
	v_lshlrev_b32_e32 v244, 3, v244
	v_add_u32_e32 v244, 0x24010, v244
	v_or_b32_e32 v246, 1, v136
	ds_read_b64 v[248:249], v244
	s_waitcnt lgkmcnt(0)
	v_cmp_ne_u32_e64 s[100:101], v248, v246
	s_nop 1
	s_and_saveexec_b64 s[98:99], s[100:101]
	s_cbranch_execz .LrcA0_3
	global_load_dwordx4 v[140:143], v[136:137], off
	global_load_dwordx4 v[152:155], v[136:137], off offset:16
	global_load_dwordx4 v[156:159], v[136:137], off offset:32
	global_load_dwordx4 v[160:163], v[136:137], off offset:48
	s_waitcnt vmcnt(3)
	v_mov_b32_e32 v136, v141
	v_mov_b32_e32 v137, v142
	v_mov_b32_e32 v141, v143
	s_waitcnt vmcnt(2)
	v_mov_b32_e32 v142, v153
	v_mov_b32_e32 v143, v154
	v_mov_b32_e32 v153, v155
	v_pk_add_f32 v[136:137], v[136:137], v[140:141]
	v_pk_add_f32 v[140:141], v[142:143], v[152:153]
	v_pk_add_f32 v[136:137], v[136:137], v[136:137] op_sel:[0,1] op_sel_hi:[1,0]
	v_pk_add_f32 v[140:141], v[140:141], v[140:141] op_sel:[0,1] op_sel_hi:[1,0]
	s_waitcnt vmcnt(1)
	v_add_f32_e32 v154, v156, v157
	v_add_f32_e32 v156, v158, v159
	s_waitcnt vmcnt(0)
	v_mov_b32_e32 v155, v162
	v_mov_b32_e32 v157, v163
	v_mov_b32_e32 v137, v160
	v_mov_b32_e32 v141, v161
	v_pk_add_f32 v[142:143], v[154:155], v[156:157]
	v_pk_add_f32 v[136:137], v[136:137], v[140:141]
	s_nop 0
	v_pk_add_f32 v[136:137], v[136:137], v[142:143]
	s_nop 0
	v_add_f32_e32 v136, v136, v137
	v_fmamk_f32 v136, v136, 0x3a800000, v185
	v_mul_f32_e32 v137, 0x4b800000, v136
	v_cmp_gt_f32_e64 s[2:3], s60, v136
	s_nop 1
	s_nop 0
	v_cndmask_b32_e64 v136, v136, v137, s[2:3]
	v_rsq_f32_e32 v136, v136
	s_nop 0
	v_mul_f32_e32 v137, 0x45800000, v136
	v_cndmask_b32_e64 v136, v136, v137, s[2:3]
	s_nop 0
	v_mov_b32_e32 v247, v136
	ds_write_b64 v244, v[246:247]

; DI float rstd_from16(const float* p, float inv_n) {
;   const f32x4 a = *(const f32x4*)p, b = *(const f32x4*)(p + 4), c = *(const f32x4*)(p + 8), d = *(const f32x4*)(p + 12);
;   const float s = ((a[0] + a[1]) + (a[2] + a[3])) + ((b[0] + b[1]) + (b[2] + b[3])) + ((c[0] + c[1]) + (c[2] + c[3])) + ((d[0] + d[1]) + (d[2] + d[3]));
;   return rsqrtf(s * inv_n + EPS_);
; template <bool SWAP> DI void inproj_tile(const Params& p, int layer, int tm, int tn, bf16_t* smem) {
;     ...
;       for (int i = 0; i < 8; ++i) {
;         const int row = i * 16 + l15, t = trow0 + row; const float rs = rstd_from16(ssq + (size_t)t * 16, 1.f / 1024.f) * qs;
.LBB0_231:
	s_or_b64 exec, exec, s[50:51]
	v_or3_b32 v138, v146, v147, 64
	v_ashrrev_i32_e32 v139, 31, v138
	s_waitcnt lgkmcnt(0)
	v_lshlrev_b64 v[136:137], 6, v[138:139]
	v_lshl_add_u64 v[136:137], s[8:9], 0, v[136:137]
	v_bfe_u32 v244, v136, 6, 8
	v_lshlrev_b32_e32 v244, 3, v244
	v_add_u32_e32 v244, 0x24010, v244
	v_or_b32_e32 v246, 1, v136
	ds_read_b64 v[248:249], v244
	s_waitcnt lgkmcnt(0)
	v_cmp_ne_u32_e64 s[100:101], v248, v246
	s_nop 1
	s_and_saveexec_b64 s[98:99], s[100:101]
	s_cbranch_execz .LrcA0_4
	global_load_dwordx4 v[140:143], v[136:137], off
	global_load_dwordx4 v[152:155], v[136:137], off offset:16
	global_load_dwordx4 v[156:159], v[136:137], off offset:32
	global_load_dwordx4 v[160:163], v[136:137], off offset:48
	s_waitcnt vmcnt(3)
	v_mov_b32_e32 v136, v141
	v_mov_b32_e32 v137, v142
	v_mov_b32_e32 v141, v143
	s_waitcnt vmcnt(2)
	v_mov_b32_e32 v142, v153
	v_mov_b32_e32 v143, v154
	v_mov_b32_e32 v153, v155
	v_pk_add_f32 v[136:137], v[136:137], v[140:141]
	v_pk_add_f32 v[140:141], v[142:143], v[152:153]
	v_pk_add_f32 v[136:137], v[136:137], v[136:137] op_sel:[0,1] op_sel_hi:[1,0]
	v_pk_add_f32 v[140:141], v[140:141], v[140:141] op_sel:[0,1] op_sel_hi:[1,0]
	s_waitcnt vmcnt(1)
	v_add_f32_e32 v154, v156, v157
	v_add_f32_e32 v156, v158, v159
	s_waitcnt vmcnt(0)
	v_mov_b32_e32 v155, v162
	v_mov_b32_e32 v157, v163
	v_mov_b32_e32 v137, v160
	v_mov_b32_e32 v141, v161
	v_pk_add_f32 v[142:143], v[154:155], v[156:157]
	v_pk_add_f32 v[136:137], v[136:137], v[140:141]
	s_nop 0
	v_pk_add_f32 v[136:137], v[136:137], v[142:143]
	s_nop 0
	v_add_f32_e32 v136, v136, v137
	v_fmamk_f32 v136, v136, 0x3a800000, v185
	v_mul_f32_e32 v137, 0x4b800000, v136
	v_cmp_gt_f32_e64 s[2:3], s60, v136
	s_nop 1
	s_nop 0
	v_cndmask_b32_e64 v136, v136, v137, s[2:3]
	v_rsq_f32_e32 v136, v136
	s_nop 0
	v_mul_f32_e32 v137, 0x45800000, v136
	v_cndmask_b32_e64 v136, v136, v137, s[2:3]
	s_nop 0
	v_mov_b32_e32 v247, v136
	ds_write_b64 v244, v[246:247]

; DI float rstd_from16(const float* p, float inv_n) {
;   const f32x4 a = *(const f32x4*)p, b = *(const f32x4*)(p + 4), c = *(const f32x4*)(p + 8), d = *(const f32x4*)(p + 12);
;   const float s = ((a[0] + a[1]) + (a[2] + a[3])) + ((b[0] + b[1]) + (b[2] + b[3])) + ((c[0] + c[1]) + (c[2] + c[3])) + ((d[0] + d[1]) + (d[2] + d[3]));
;   return rsqrtf(s * inv_n + EPS_);
; template <bool SWAP> DI void inproj_tile(const Params& p, int layer, int tm, int tn, bf16_t* smem) {
;     ...
;       for (int i = 0; i < 8; ++i) {
;         const int row = i * 16 + l15, t = trow0 + row; const float rs = rstd_from16(ssq + (size_t)t * 16, 1.f / 1024.f) * qs;
.LBB0_238:
	s_or_b64 exec, exec, s[50:51]
	v_or3_b32 v138, v146, v147, s62
	v_ashrrev_i32_e32 v139, 31, v138
	s_waitcnt lgkmcnt(0)
	v_lshlrev_b64 v[136:137], 6, v[138:139]
	v_lshl_add_u64 v[136:137], s[8:9], 0, v[136:137]
	v_bfe_u32 v244, v136, 6, 8
	v_lshlrev_b32_e32 v244, 3, v244
	v_add_u32_e32 v244, 0x24010, v244
	v_or_b32_e32 v246, 1, v136
	ds_read_b64 v[248:249], v244
	s_waitcnt lgkmcnt(0)
	v_cmp_ne_u32_e64 s[100:101], v248, v246
	s_nop 1
	s_and_saveexec_b64 s[98:99], s[100:101]
	s_cbranch_execz .LrcA0_5
	global_load_dwordx4 v[140:143], v[136:137], off
	global_load_dwordx4 v[152:155], v[136:137], off offset:16
	global_load_dwordx4 v[156:159], v[136:137], off offset:32
	global_load_dwordx4 v[160:163], v[136:137], off offset:48
	s_waitcnt vmcnt(3)
	v_mov_b32_e32 v136, v141
	v_mov_b32_e32 v137, v142
	v_mov_b32_e32 v141, v143
	s_waitcnt vmcnt(2)
	v_mov_b32_e32 v142, v153
	v_mov_b32_e32 v143, v154
	v_mov_b32_e32 v153, v155
	v_pk_add_f32 v[136:137], v[136:137], v[140:141]
	v_pk_add_f32 v[140:141], v[142:143], v[152:153]
	v_pk_add_f32 v[136:137], v[136:137], v[136:137] op_sel:[0,1] op_sel_hi:[1,0]
	v_pk_add_f32 v[140:141], v[140:141], v[140:141] op_sel:[0,1] op_sel_hi:[1,0]
	s_waitcnt vmcnt(1)
	v_add_f32_e32 v154, v156, v157
	v_add_f32_e32 v156, v158, v159
	s_waitcnt vmcnt(0)
	v_mov_b32_e32 v155, v162
	v_mov_b32_e32 v157, v163
	v_mov_b32_e32 v137, v160
	v_mov_b32_e32 v141, v161
	v_pk_add_f32 v[142:143], v[154:155], v[156:157]
	v_pk_add_f32 v[136:137], v[136:137], v[140:141]
	s_nop 0
	v_pk_add_f32 v[136:137], v[136:137], v[142:143]
	s_nop 0
	v_add_f32_e32 v136, v136, v137
	v_fmamk_f32 v136, v136, 0x3a800000, v185
	v_mul_f32_e32 v137, 0x4b800000, v136
	v_cmp_gt_f32_e64 s[2:3], s60, v136
	s_nop 1
	s_nop 0
	v_cndmask_b32_e64 v136, v136, v137, s[2:3]
	v_rsq_f32_e32 v136, v136
	s_nop 0
	v_mul_f32_e32 v137, 0x45800000, v136
	v_cndmask_b32_e64 v136, v136, v137, s[2:3]
	s_nop 0
	v_mov_b32_e32 v247, v136
	ds_write_b64 v244, v[246:247]

; DI float rstd_from16(const float* p, float inv_n) {
;   const f32x4 a = *(const f32x4*)p, b = *(const f32x4*)(p + 4), c = *(const f32x4*)(p + 8), d = *(const f32x4*)(p + 12);
;   const float s = ((a[0] + a[1]) + (a[2] + a[3])) + ((b[0] + b[1]) + (b[2] + b[3])) + ((c[0] + c[1]) + (c[2] + c[3])) + ((d[0] + d[1]) + (d[2] + d[3]));
;   return rsqrtf(s * inv_n + EPS_);
; template <bool SWAP> DI void inproj_tile(const Params& p, int layer, int tm, int tn, bf16_t* smem) {
;     ...
;       for (int i = 0; i < 8; ++i) {
;         const int row = i * 16 + l15, t = trow0 + row; const float rs = rstd_from16(ssq + (size_t)t * 16, 1.f / 1024.f) * qs;
.LBB0_245:
	s_or_b64 exec, exec, s[50:51]
	v_or3_b32 v138, v146, v147, s63
	v_ashrrev_i32_e32 v139, 31, v138
	s_waitcnt lgkmcnt(0)
	v_lshlrev_b64 v[136:137], 6, v[138:139]
	v_lshl_add_u64 v[136:137], s[8:9], 0, v[136:137]
	v_bfe_u32 v244, v136, 6, 8
	v_lshlrev_b32_e32 v244, 3, v244
	v_add_u32_e32 v244, 0x24010, v244
	v_or_b32_e32 v246, 1, v136
	ds_read_b64 v[248:249], v244
	s_waitcnt lgkmcnt(0)
	v_cmp_ne_u32_e64 s[100:101], v248, v246
	s_nop 1
	s_and_saveexec_b64 s[98:99], s[100:101]
	s_cbranch_execz .LrcA0_6
	global_load_dwordx4 v[140:143], v[136:137], off
	global_load_dwordx4 v[152:155], v[136:137], off offset:16
	global_load_dwordx4 v[156:159], v[136:137], off offset:32
	global_load_dwordx4 v[160:163], v[136:137], off offset:48
	s_waitcnt vmcnt(3)
	v_mov_b32_e32 v136, v141
	v_mov_b32_e32 v137, v142
	v_mov_b32_e32 v141, v143
	s_waitcnt vmcnt(2)
	v_mov_b32_e32 v142, v153
	v_mov_b32_e32 v143, v154
	v_mov_b32_e32 v153, v155
	v_pk_add_f32 v[136:137], v[136:137], v[140:141]
	v_pk_add_f32 v[140:141], v[142:143], v[152:153]
	v_pk_add_f32 v[136:137], v[136:137], v[136:137] op_sel:[0,1] op_sel_hi:[1,0]
	v_pk_add_f32 v[140:141], v[140:141], v[140:141] op_sel:[0,1] op_sel_hi:[1,0]
	s_waitcnt vmcnt(1)
	v_add_f32_e32 v154, v156, v157
	v_add_f32_e32 v156, v158, v159
	s_waitcnt vmcnt(0)
	v_mov_b32_e32 v155, v162
	v_mov_b32_e32 v157, v163
	v_mov_b32_e32 v137, v160
	v_mov_b32_e32 v141, v161
	v_pk_add_f32 v[142:143], v[154:155], v[156:157]
	v_pk_add_f32 v[136:137], v[136:137], v[140:141]
	s_nop 0
	v_pk_add_f32 v[136:137], v[136:137], v[142:143]
	s_nop 0
	v_add_f32_e32 v136, v136, v137
	v_fmamk_f32 v136, v136, 0x3a800000, v185
	v_mul_f32_e32 v137, 0x4b800000, v136
	v_cmp_gt_f32_e64 s[2:3], s60, v136
	s_nop 1
	s_nop 0
	v_cndmask_b32_e64 v136, v136, v137, s[2:3]
	v_rsq_f32_e32 v136, v136
	s_nop 0
	v_mul_f32_e32 v137, 0x45800000, v136
	v_cndmask_b32_e64 v136, v136, v137, s[2:3]
	s_nop 0
	v_mov_b32_e32 v247, v136
	ds_write_b64 v244, v[246:247]

; DI float rstd_from16(const float* p, float inv_n) {
;   const f32x4 a = *(const f32x4*)p, b = *(const f32x4*)(p + 4), c = *(const f32x4*)(p + 8), d = *(const f32x4*)(p + 12);
;   const float s = ((a[0] + a[1]) + (a[2] + a[3])) + ((b[0] + b[1]) + (b[2] + b[3])) + ((c[0] + c[1]) + (c[2] + c[3])) + ((d[0] + d[1]) + (d[2] + d[3]));
;   return rsqrtf(s * inv_n + EPS_);
; template <bool SWAP> DI void inproj_tile(const Params& p, int layer, int tm, int tn, bf16_t* smem) {
;     ...
;       for (int i = 0; i < 8; ++i) {
;         const int row = i * 16 + l15, t = trow0 + row; const float rs = rstd_from16(ssq + (size_t)t * 16, 1.f / 1024.f) * qs;
.LBB0_252:
	s_or_b64 exec, exec, s[50:51]
	v_or3_b32 v138, v146, v147, s41
	v_ashrrev_i32_e32 v139, 31, v138
	s_waitcnt lgkmcnt(0)
	v_lshlrev_b64 v[136:137], 6, v[138:139]
	v_lshl_add_u64 v[136:137], s[8:9], 0, v[136:137]
	v_bfe_u32 v244, v136, 6, 8
	v_lshlrev_b32_e32 v244, 3, v244
	v_add_u32_e32 v244, 0x24010, v244
	v_or_b32_e32 v246, 1, v136
	ds_read_b64 v[248:249], v244
	s_waitcnt lgkmcnt(0)
	v_cmp_ne_u32_e64 s[100:101], v248, v246
	s_nop 1
	s_and_saveexec_b64 s[98:99], s[100:101]
	s_cbranch_execz .LrcA0_7
	global_load_dwordx4 v[140:143], v[136:137], off
	global_load_dwordx4 v[150:153], v[136:137], off offset:16
	global_load_dwordx4 v[154:157], v[136:137], off offset:32
	global_load_dwordx4 v[158:161], v[136:137], off offset:48
	s_waitcnt vmcnt(3)
	v_mov_b32_e32 v136, v141
	v_mov_b32_e32 v137, v142
	v_mov_b32_e32 v141, v143
	s_waitcnt vmcnt(2)
	v_mov_b32_e32 v142, v151
	v_mov_b32_e32 v143, v152
	v_mov_b32_e32 v151, v153
	v_pk_add_f32 v[136:137], v[136:137], v[140:141]
	v_pk_add_f32 v[140:141], v[142:143], v[150:151]
	v_pk_add_f32 v[136:137], v[136:137], v[136:137] op_sel:[0,1] op_sel_hi:[1,0]
	v_pk_add_f32 v[140:141], v[140:141], v[140:141] op_sel:[0,1] op_sel_hi:[1,0]
	s_waitcnt vmcnt(1)
	v_add_f32_e32 v152, v154, v155
	v_add_f32_e32 v154, v156, v157
	s_waitcnt vmcnt(0)
	v_mov_b32_e32 v153, v160
	v_mov_b32_e32 v155, v161
	v_mov_b32_e32 v137, v158
	v_mov_b32_e32 v141, v159
	v_pk_add_f32 v[142:143], v[152:153], v[154:155]
	v_pk_add_f32 v[136:137], v[136:137], v[140:141]
	s_nop 0
	v_pk_add_f32 v[136:137], v[136:137], v[142:143]
	s_nop 0
	v_add_f32_e32 v136, v136, v137
	v_fmamk_f32 v136, v136, 0x3a800000, v185
	v_mul_f32_e32 v137, 0x4b800000, v136
	v_cmp_gt_f32_e64 s[2:3], s60, v136
	s_nop 1
	s_nop 0
	v_cndmask_b32_e64 v136, v136, v137, s[2:3]
	v_rsq_f32_e32 v136, v136
	s_nop 0
	v_mul_f32_e32 v137, 0x45800000, v136
	v_cndmask_b32_e64 v136, v136, v137, s[2:3]
	s_nop 0
	v_mov_b32_e32 v247, v136
	ds_write_b64 v244, v[246:247]

; DI float rstd_from16(const float* p, float inv_n) {
;   const f32x4 a = *(const f32x4*)p, b = *(const f32x4*)(p + 4), c = *(const f32x4*)(p + 8), d = *(const f32x4*)(p + 12);
;   const float s = ((a[0] + a[1]) + (a[2] + a[3])) + ((b[0] + b[1]) + (b[2] + b[3])) + ((c[0] + c[1]) + (c[2] + c[3])) + ((d[0] + d[1]) + (d[2] + d[3]));
;   return rsqrtf(s * inv_n + EPS_);
; template <bool SWAP> DI void inproj_tile(const Params& p, int layer, int tm, int tn, bf16_t* smem) {
;     ...
;       for (int i = 0; i < 8; ++i) {
;         const int t = trow0 + i * 16 + l15; const float rs = rstd_from16(ssq + (size_t)t * 16, 1.f / 1024.f);
.LBB0_260:
	s_or_b64 exec, exec, s[6:7]
	s_and_saveexec_b64 s[0:1], s[4:5]
	s_xor_b64 s[46:47], exec, s[0:1]
	s_cbranch_execz .LBB0_294
	v_or_b32_e32 v128, v147, v146
	v_ashrrev_i32_e32 v129, 31, v128
	v_lshlrev_b64 v[130:131], 6, v[128:129]
	v_lshl_add_u64 v[130:131], s[8:9], 0, v[130:131]
	v_bfe_u32 v244, v130, 6, 8
	v_lshlrev_b32_e32 v244, 3, v244
	v_add_u32_e32 v244, 0x24010, v244
	v_or_b32_e32 v246, 1, v130
	ds_read_b64 v[248:249], v244
	s_waitcnt lgkmcnt(0)
	v_cmp_ne_u32_e64 s[100:101], v248, v246
	s_nop 1
	s_and_saveexec_b64 s[98:99], s[100:101]
	s_cbranch_execz .LrcA0_8
	global_load_dwordx4 v[132:135], v[130:131], off
	global_load_dwordx4 v[136:139], v[130:131], off offset:16
	global_load_dwordx4 v[140:143], v[130:131], off offset:32
	global_load_dwordx4 v[146:149], v[130:131], off offset:48
	s_waitcnt vmcnt(6)
	s_waitcnt vmcnt(3)
	v_mov_b32_e32 v152, v133
	v_mov_b32_e32 v153, v134
	v_mov_b32_e32 v133, v135
	s_waitcnt vmcnt(2)
	v_mov_b32_e32 v134, v137
	v_mov_b32_e32 v135, v138
	v_mov_b32_e32 v137, v139
	v_pk_add_f32 v[132:133], v[152:153], v[132:133]
	v_pk_add_f32 v[134:135], v[134:135], v[136:137]
	v_pk_add_f32 v[132:133], v[132:133], v[132:133] op_sel:[0,1] op_sel_hi:[1,0]
	v_pk_add_f32 v[134:135], v[134:135], v[134:135] op_sel:[0,1] op_sel_hi:[1,0]
	s_waitcnt vmcnt(1)
	v_add_f32_e32 v138, v140, v141
	v_add_f32_e32 v140, v142, v143
	s_waitcnt vmcnt(0)
	v_mov_b32_e32 v139, v148
	v_mov_b32_e32 v141, v149
	v_mov_b32_e32 v133, v146
	v_mov_b32_e32 v135, v147
	v_pk_add_f32 v[136:137], v[138:139], v[140:141]
	v_pk_add_f32 v[132:133], v[132:133], v[134:135]
	s_nop 0
	v_pk_add_f32 v[132:133], v[132:133], v[136:137]
	s_nop 0
	v_add_f32_e32 v130, v132, v133
	v_fmamk_f32 v130, v130, 0x3a800000, v185
	v_mul_f32_e32 v132, 0x4b800000, v130
	v_cmp_gt_f32_e32 vcc, s60, v130
	s_nop 1
	s_nop 0
	v_cndmask_b32_e32 v130, v130, v132, vcc
	v_rsq_f32_e32 v130, v130
	s_nop 0
	v_mul_f32_e32 v134, 0x45800000, v130
	v_cndmask_b32_e32 v130, v130, v134, vcc
	s_nop 0
	v_mov_b32_e32 v247, v130
	ds_write_b64 v244, v[246:247]

; DI int TIDX() { int t = (int)threadIdx.x; asm volatile("" : "+v"(t)); return t; }
; DI float rstd_from16(const float* p, float inv_n) {
;   const f32x4 a = *(const f32x4*)p, b = *(const f32x4*)(p + 4), c = *(const f32x4*)(p + 8), d = *(const f32x4*)(p + 12);
;   const float s = ((a[0] + a[1]) + (a[2] + a[3])) + ((b[0] + b[1]) + (b[2] + b[3])) + ((c[0] + c[1]) + (c[2] + c[3])) + ((d[0] + d[1]) + (d[2] + d[3]));
;   return rsqrtf(s * inv_n + EPS_);
; DI void merge_tile(const Params& p, int layer, int tm, int tn, bf16_t* smem) {
;     ...
;     if ((sg & 1) == 0) {
;       const int t2 = TIDX(), row0 = tm * 256 + ((t2 >> 8) & 1) * 128 + (t2 & 15);
; #pragma unroll
;       for (int i = 0; i < 8; ++i) {
;         asm volatile("" ::: "memory");
;         const float rs = rstd_from16((const float*)(p.ws + O_SSQ) + (size_t)(row0 + i * 16) * 16, 1.f / 1024.f);
.LBB0_851:
	v_mov_b32_e32 v152, v220
	v_mov_b64_e32 v[214:215], v[26:27]
	v_lshrrev_b32_e32 v153, 1, v152
	v_and_b32_e32 v153, 0x80, v153
	v_and_b32_e32 v152, 15, v152
	v_or3_b32 v152, v152, v153, s37
	v_ashrrev_i32_e32 v153, 31, v152
	v_lshlrev_b64 v[154:155], 6, v[152:153]
	v_lshl_add_u64 v[166:167], s[0:1], 0, v[154:155]
	v_bfe_u32 v244, v166, 6, 8
	v_lshlrev_b32_e32 v244, 3, v244
	v_add_u32_e32 v244, 0x24010, v244
	v_or_b32_e32 v246, 1, v166
	ds_read_b64 v[248:249], v244
	s_waitcnt lgkmcnt(0)
	v_cmp_ne_u32_e64 s[100:101], v248, v246
	s_nop 1
	s_and_saveexec_b64 s[98:99], s[100:101]
	s_cbranch_execz .LrcE0_0
	global_load_dwordx4 v[154:157], v[166:167], off offset:48
	global_load_dwordx4 v[158:161], v[166:167], off offset:32
	global_load_dwordx4 v[162:165], v[166:167], off offset:16
	s_nop 0
	global_load_dwordx4 v[166:169], v[166:167], off
	s_waitcnt vmcnt(2)
	v_add_f32_e32 v158, v158, v159
	v_add_f32_e32 v160, v160, v161
	s_waitcnt vmcnt(0)
	v_mov_b32_e32 v170, v167
	v_mov_b32_e32 v171, v168
	v_mov_b32_e32 v167, v169
	v_mov_b32_e32 v168, v163
	v_mov_b32_e32 v169, v164
	v_mov_b32_e32 v163, v165
	v_pk_add_f32 v[166:167], v[170:171], v[166:167]
	v_pk_add_f32 v[162:163], v[168:169], v[162:163]
	v_pk_add_f32 v[166:167], v[166:167], v[166:167] op_sel:[0,1] op_sel_hi:[1,0]
	v_pk_add_f32 v[162:163], v[162:163], v[162:163] op_sel:[0,1] op_sel_hi:[1,0]
	v_mov_b32_e32 v167, v154
	v_mov_b32_e32 v163, v155
	v_mov_b32_e32 v159, v156
	v_mov_b32_e32 v161, v157
	v_pk_add_f32 v[154:155], v[166:167], v[162:163]
	v_pk_add_f32 v[156:157], v[158:159], v[160:161]
	v_pk_add_f32 v[154:155], v[154:155], v[156:157]
	v_add_f32_e32 v153, v154, v155
	v_fmamk_f32 v153, v153, 0x3a800000, v225
	v_cmp_gt_f32_e32 vcc, s35, v153
	v_mul_f32_e32 v154, 0x4b800000, v153
	s_nop 0
	v_cndmask_b32_e32 v153, v153, v154, vcc
	v_rsq_f32_e32 v153, v153
	s_nop 0
	v_mul_f32_e32 v154, 0x45800000, v153
	v_cndmask_b32_e32 v153, v153, v154, vcc
	s_nop 0
	v_mov_b32_e32 v247, v153
	ds_write_b64 v244, v[246:247]
; DI float sigmoidf_(float x) { return 1.f / (1.f + __expf(-x)); }
; DI float rstd_from16(const float* p, float inv_n) {
;   const f32x4 a = *(const f32x4*)p, b = *(const f32x4*)(p + 4), c = *(const f32x4*)(p + 8), d = *(const f32x4*)(p + 12);
;   const float s = ((a[0] + a[1]) + (a[2] + a[3])) + ((b[0] + b[1]) + (b[2] + b[3])) + ((c[0] + c[1]) + (c[2] + c[3])) + ((d[0] + d[1]) + (d[2] + d[3]));
;   return rsqrtf(s * inv_n + EPS_);
; DI void merge_tile(const Params& p, int layer, int tm, int tn, bf16_t* smem) {
;     ...
;         const float rs = rstd_from16((const float*)(p.ws + O_SSQ) + (size_t)(row0 + i * 16) * 16, 1.f / 1024.f);
; #pragma unroll
;         for (int j = 0; j < 2; ++j) {
;           unsigned w = 0;
; #pragma unroll
;           for (int r = 0; r < 4; ++r) w |= (unsigned)__float2int_rn(sigmoidf_(acc[i][j][r] * rs) * 255.f) << (8 * r);
;           gsp[(i * 2 + j) * NTHR] = w;
.LrcE0_0:
	s_or_b64 exec, exec, s[98:99]
	s_waitcnt vmcnt(0)
	v_cndmask_b32_e64 v153, v249, v153, s[100:101]
	v_mov_b64_e32 v[210:211], v[30:31]
	v_mov_b64_e32 v[206:207], v[34:35]
	v_mov_b64_e32 v[202:203], v[38:39]
	v_mov_b64_e32 v[198:199], v[42:43]
	v_mov_b64_e32 v[194:195], v[46:47]
	v_mov_b64_e32 v[190:191], v[50:51]
	v_mov_b64_e32 v[186:187], v[54:55]
	v_mov_b64_e32 v[182:183], v[58:59]
	v_mov_b64_e32 v[178:179], v[62:63]
	v_mov_b64_e32 v[174:175], v[66:67]
	v_mov_b64_e32 v[212:213], v[24:25]
	v_mov_b64_e32 v[208:209], v[28:29]
	v_mov_b64_e32 v[204:205], v[32:33]
	v_mov_b64_e32 v[200:201], v[36:37]
	v_mov_b64_e32 v[196:197], v[40:41]
	v_mov_b64_e32 v[192:193], v[44:45]
	v_mov_b64_e32 v[188:189], v[48:49]
	v_mov_b64_e32 v[184:185], v[52:53]
	v_mov_b64_e32 v[180:181], v[56:57]
	v_mov_b64_e32 v[176:177], v[60:61]
	v_mov_b64_e32 v[172:173], v[64:65]
	v_mov_b64_e32 v[170:171], v[70:71]
	v_mov_b64_e32 v[166:167], v[74:75]
	v_mov_b64_e32 v[168:169], v[68:69]
	v_mov_b64_e32 v[164:165], v[72:73]
	v_mul_f32_e32 v148, v148, v153
	v_mul_f32_e32 v148, 0xbfb8aa3b, v148
	v_exp_f32_e32 v148, v148
	v_mul_f32_e32 v149, v149, v153
	v_mul_f32_e32 v149, 0xbfb8aa3b, v149
	v_exp_f32_e32 v149, v149
	v_add_f32_e32 v148, 1.0, v148
	v_add_f32_e32 v149, 1.0, v149
	v_mul_f32_e32 v144, v144, v153
	v_mul_f32_e32 v144, 0xbfb8aa3b, v144
	v_rcp_f32_e32 v148, v148
	s_nop 0
	v_mul_f32_e32 v148, 0x437f0000, v148
	v_rndne_f32_e32 v148, v148
	v_cvt_i32_f32_e32 v148, v148
	v_rcp_f32_e32 v149, v149
	s_nop 0
	v_mul_f32_e32 v149, 0x437f0000, v149
	v_rndne_f32_e32 v149, v149
	v_cvt_i32_f32_e32 v149, v149
	v_exp_f32_e32 v144, v144
	v_mul_f32_e32 v145, v145, v153
	v_mul_f32_e32 v145, 0xbfb8aa3b, v145
	v_lshl_or_b32 v148, v149, 8, v148
	v_mul_f32_e32 v149, v150, v153
	v_mul_f32_e32 v149, 0xbfb8aa3b, v149
	v_exp_f32_e32 v149, v149
	v_add_f32_e32 v144, 1.0, v144
	v_exp_f32_e32 v145, v145
	v_add_f32_e32 v149, 1.0, v149
	v_add_f32_e32 v145, 1.0, v145
	v_rcp_f32_e32 v149, v149
	v_mul_f32_e32 v150, v151, v153
	v_mul_f32_e32 v150, 0xbfb8aa3b, v150
	v_exp_f32_e32 v150, v150
	v_mul_f32_e32 v149, 0x437f0000, v149
	v_rndne_f32_e32 v149, v149
	v_cvt_i32_f32_sdwa v149, v149 dst_sel:WORD_1 dst_unused:UNUSED_PAD src0_sel:DWORD
	v_add_f32_e32 v150, 1.0, v150
	s_nop 0
	v_rcp_f32_e32 v150, v150
	s_nop 0
	v_mul_f32_e32 v150, 0x437f0000, v150
	v_rndne_f32_e32 v150, v150
	v_cvt_i32_f32_sdwa v150, v150 dst_sel:BYTE_3 dst_unused:UNUSED_PAD src0_sel:DWORD
	s_nop 0
	v_or3_b32 v148, v148, v149, v150
	s_nop 0
	v_rcp_f32_e32 v144, v144
	s_nop 0
	v_mul_f32_e32 v144, 0x437f0000, v144
	v_rndne_f32_e32 v144, v144
	v_cvt_i32_f32_e32 v144, v144
	v_rcp_f32_e32 v145, v145
	s_nop 0
	v_mul_f32_e32 v145, 0x437f0000, v145
	v_rndne_f32_e32 v145, v145
	v_cvt_i32_f32_e32 v145, v145
	v_lshl_or_b32 v144, v145, 8, v144
	v_mul_f32_e32 v145, v146, v153
	v_mul_f32_e32 v145, 0xbfb8aa3b, v145
	v_exp_f32_e32 v145, v145
	s_nop 0
	v_add_f32_e32 v145, 1.0, v145
	s_nop 0
	v_rcp_f32_e32 v145, v145
	v_mul_f32_e32 v146, v147, v153
	v_mul_f32_e32 v146, 0xbfb8aa3b, v146
	v_exp_f32_e32 v146, v146
	v_mul_f32_e32 v145, 0x437f0000, v145
	v_rndne_f32_e32 v145, v145
	v_cvt_i32_f32_sdwa v145, v145 dst_sel:WORD_1 dst_unused:UNUSED_PAD src0_sel:DWORD
	v_add_f32_e32 v146, 1.0, v146
	s_nop 0
	v_rcp_f32_e32 v146, v146
	s_nop 0
	v_mul_f32_e32 v146, 0x437f0000, v146
	v_rndne_f32_e32 v146, v146
	v_cvt_i32_f32_sdwa v146, v146 dst_sel:BYTE_3 dst_unused:UNUSED_PAD src0_sel:DWORD
	s_nop 0
	v_or3_b32 v144, v144, v145, v146
	ds_write2st64_b32 v228, v148, v144 offset1:8
	v_or_b32_e32 v144, 16, v152
	v_ashrrev_i32_e32 v145, 31, v144
	v_lshlrev_b64 v[144:145], 6, v[144:145]
	v_lshl_add_u64 v[158:159], s[0:1], 0, v[144:145]
	v_bfe_u32 v244, v158, 6, 8
	v_lshlrev_b32_e32 v244, 3, v244
	v_add_u32_e32 v244, 0x24010, v244
	v_or_b32_e32 v246, 1, v158
	ds_read_b64 v[248:249], v244
	s_waitcnt lgkmcnt(0)
	v_cmp_ne_u32_e64 s[100:101], v248, v246
	s_nop 1
	s_and_saveexec_b64 s[98:99], s[100:101]
	s_cbranch_execz .LrcE0_1
	global_load_dwordx4 v[144:147], v[158:159], off offset:48
	global_load_dwordx4 v[148:151], v[158:159], off offset:32
	global_load_dwordx4 v[154:157], v[158:159], off offset:16
	s_nop 0
	global_load_dwordx4 v[158:161], v[158:159], off
	s_waitcnt vmcnt(2)
	v_add_f32_e32 v148, v148, v149
	v_add_f32_e32 v150, v150, v151
	s_waitcnt vmcnt(0)
	v_mov_b32_e32 v162, v159
	v_mov_b32_e32 v163, v160
	v_mov_b32_e32 v159, v161
	v_mov_b32_e32 v160, v155
	v_mov_b32_e32 v161, v156
	v_mov_b32_e32 v155, v157
	v_pk_add_f32 v[158:159], v[162:163], v[158:159]
	v_pk_add_f32 v[154:155], v[160:161], v[154:155]
	v_pk_add_f32 v[158:159], v[158:159], v[158:159] op_sel:[0,1] op_sel_hi:[1,0]
	v_pk_add_f32 v[154:155], v[154:155], v[154:155] op_sel:[0,1] op_sel_hi:[1,0]
	v_mov_b32_e32 v159, v144
	v_mov_b32_e32 v155, v145
	v_mov_b32_e32 v149, v146
	v_mov_b32_e32 v151, v147
	v_pk_add_f32 v[144:145], v[158:159], v[154:155]
	v_pk_add_f32 v[146:147], v[148:149], v[150:151]
	v_pk_add_f32 v[144:145], v[144:145], v[146:147]
	v_add_f32_e32 v144, v144, v145
	v_fmamk_f32 v144, v144, 0x3a800000, v225
	v_cmp_gt_f32_e32 vcc, s35, v144
	v_mul_f32_e32 v145, 0x4b800000, v144
	s_nop 0
	v_cndmask_b32_e32 v144, v144, v145, vcc
	v_rsq_f32_e32 v144, v144
	s_nop 0
	v_mul_f32_e32 v145, 0x45800000, v144
	v_cndmask_b32_e32 v144, v144, v145, vcc
	s_nop 0
	v_mov_b32_e32 v247, v144
	ds_write_b64 v244, v[246:247]

; DI float rstd_from16(const float* p, float inv_n) {
;   const f32x4 a = *(const f32x4*)p, b = *(const f32x4*)(p + 4), c = *(const f32x4*)(p + 8), d = *(const f32x4*)(p + 12);
;   const float s = ((a[0] + a[1]) + (a[2] + a[3])) + ((b[0] + b[1]) + (b[2] + b[3])) + ((c[0] + c[1]) + (c[2] + c[3])) + ((d[0] + d[1]) + (d[2] + d[3]));
;   return rsqrtf(s * inv_n + EPS_);
; DI void ffnup_tile(const Params& p, int layer, int b, int mt, int tn, bf16_t* smem) {
;     ...
; #pragma unroll
;     for (int i = 0; i < 8; ++i) {
;       const int row = wm * 128 + i * 16 + l15, s = s0 + row;
;       const float rs = (s >= 0 && s < S_) ? rstd_from16((const float*)(p.ws + O_SSQ) + ((size_t)b * S_ + s) * 16, 1.f / 1024.f) : 0.f;
.Lgm6_exit:
	v_mfma_f32_16x16x32_bf16 v[28:31], v[182:185], v[246:249], v[28:31]
	v_mfma_f32_16x16x32_bf16 v[12:15], v[182:185], v[250:253], v[12:15]
	v_mfma_f32_16x16x32_bf16 v[24:27], v[186:189], v[246:249], v[24:27]
	v_mfma_f32_16x16x32_bf16 v[8:11], v[186:189], v[250:253], v[8:11]
	v_mfma_f32_16x16x32_bf16 v[20:23], v[190:193], v[246:249], v[20:23]
	v_mfma_f32_16x16x32_bf16 v[4:7], v[190:193], v[250:253], v[4:7]
	v_mfma_f32_16x16x32_bf16 v[16:19], v[194:197], v[246:249], v[16:19]
	v_mfma_f32_16x16x32_bf16 v[0:3], v[194:197], v[250:253], v[0:3]
	s_nop 7
	s_waitcnt vmcnt(5)
	v_mov_b32_e32 v115, v220
	s_movk_i32 s0, 0xff80
	v_and_b32_e32 v113, 15, v115
	v_ashrrev_i32_e32 v112, 1, v115
	s_waitcnt vmcnt(4)
	v_and_or_b32 v118, v112, s0, v113
	v_add_u32_e32 v116, s29, v118
	s_lshl_b64 s[2:3], s[10:11], 12
	v_cmp_gt_u32_e32 vcc, s22, v116
	v_mov_b32_e32 v112, 0
	v_mov_b32_e32 v114, 0
	s_and_saveexec_b64 s[0:1], vcc
	s_cbranch_execz .LBB0_1052
	s_waitcnt vmcnt(3)
	v_or_b32_e32 v120, s2, v116
	v_mov_b32_e32 v121, s3
	v_lshlrev_b64 v[120:121], 6, v[120:121]
	s_waitcnt vmcnt(1)
	v_lshl_add_u64 v[132:133], s[8:9], 0, v[120:121]
	v_bfe_u32 v244, v132, 6, 8
	v_lshlrev_b32_e32 v244, 3, v244
	v_add_u32_e32 v244, 0x24010, v244
	v_or_b32_e32 v246, 2, v132
	ds_read_b64 v[248:249], v244
	s_waitcnt lgkmcnt(0)
	v_cmp_ne_u32_e64 s[100:101], v248, v246
	s_nop 1
	s_and_saveexec_b64 s[98:99], s[100:101]
	s_cbranch_execz .LrcG0_0
	global_load_dwordx4 v[120:123], v[132:133], off
	global_load_dwordx4 v[124:127], v[132:133], off offset:16
	global_load_dwordx4 v[128:131], v[132:133], off offset:32
	s_nop 0
	global_load_dwordx4 v[132:135], v[132:133], off offset:48
	s_waitcnt vmcnt(3)
	v_mov_b32_e32 v136, v121
	v_mov_b32_e32 v137, v122
	v_mov_b32_e32 v121, v123
	s_waitcnt vmcnt(2)
	v_mov_b32_e32 v122, v125
	v_mov_b32_e32 v123, v126
	v_mov_b32_e32 v125, v127
	v_pk_add_f32 v[120:121], v[136:137], v[120:121]
	v_pk_add_f32 v[122:123], v[122:123], v[124:125]
	v_pk_add_f32 v[120:121], v[120:121], v[120:121] op_sel:[0,1] op_sel_hi:[1,0]
	v_pk_add_f32 v[122:123], v[122:123], v[122:123] op_sel:[0,1] op_sel_hi:[1,0]
	s_waitcnt vmcnt(1)
	v_add_f32_e32 v126, v128, v129
	v_add_f32_e32 v128, v130, v131
	s_waitcnt vmcnt(0)
	v_mov_b32_e32 v127, v134
	v_mov_b32_e32 v129, v135
	v_mov_b32_e32 v121, v132
	v_mov_b32_e32 v123, v133
	v_pk_add_f32 v[124:125], v[126:127], v[128:129]
	v_pk_add_f32 v[120:121], v[120:121], v[122:123]
	s_nop 0
	v_pk_add_f32 v[120:121], v[120:121], v[124:125]
	s_nop 0
	v_add_f32_e32 v114, v120, v121
	v_fmamk_f32 v114, v114, 0x3a800000, v168
	v_mul_f32_e32 v117, 0x4b800000, v114
	v_cmp_gt_f32_e32 vcc, s24, v114
	s_nop 1
	s_nop 0
	v_cndmask_b32_e32 v114, v114, v117, vcc
	v_rsq_f32_e32 v114, v114
	s_nop 0
	v_mul_f32_e32 v117, 0x45800000, v114
	v_cndmask_b32_e32 v114, v114, v117, vcc
	s_nop 0
	v_mov_b32_e32 v247, v114
	ds_write_b64 v244, v[246:247]

; DI void store4(bf16_t* dst, const f32x4& v, float s) { *(u32x2*)dst = (u32x2){pk2(v[0] * s, v[1] * s), pk2(v[2] * s, v[3] * s)}; }
; DI float rstd_from16(const float* p, float inv_n) {
;   const f32x4 a = *(const f32x4*)p, b = *(const f32x4*)(p + 4), c = *(const f32x4*)(p + 8), d = *(const f32x4*)(p + 12);
;   const float s = ((a[0] + a[1]) + (a[2] + a[3])) + ((b[0] + b[1]) + (b[2] + b[3])) + ((c[0] + c[1]) + (c[2] + c[3])) + ((d[0] + d[1]) + (d[2] + d[3]));
;   return rsqrtf(s * inv_n + EPS_);
; DI void ffnup_tile(const Params& p, int layer, int b, int mt, int tn, bf16_t* smem) {
;     ...
;     for (int i = 0; i < 8; ++i) {
;       const int row = wm * 128 + i * 16 + l15, s = s0 + row;
;       const float rs = (s >= 0 && s < S_) ? rstd_from16((const float*)(p.ws + O_SSQ) + ((size_t)b * S_ + s) * 16, 1.f / 1024.f) : 0.f;
; #pragma unroll
;       for (int j = 0; j < 4; ++j) store4(dstb + row * LDU + j * 16, acc[i][j], rs);
.LBB0_1052:
	s_or_b64 exec, exec, s[0:1]
	v_bfe_i32 v117, v115, 7, 1
	v_and_b32_e32 v119, 64, v115
	s_waitcnt vmcnt(3)
	v_lshrrev_b32_e32 v120, 1, v115
	v_and_b32_e32 v117, 0x11000, v117
	v_lshlrev_b32_e32 v119, 1, v119
	v_and_b32_e32 v120, 24, v120
	v_or3_b32 v117, v117, v119, v120
	v_pk_mul_f32 v[120:121], v[156:157], v[114:115] op_sel_hi:[1,0]
	v_pk_mul_f32 v[122:123], v[158:159], v[114:115] op_sel_hi:[1,0]
	v_mul_lo_u32 v119, v118, s25
	v_cvt_pk_bf16_f32 v120, v120, v121
	v_cvt_pk_bf16_f32 v121, v122, v123
	v_pk_mul_f32 v[122:123], v[152:153], v[114:115] op_sel_hi:[1,0]
	v_pk_mul_f32 v[124:125], v[154:155], v[114:115] op_sel_hi:[1,0]
	v_add_u32_e32 v117, v117, v119
	v_cvt_pk_bf16_f32 v122, v122, v123
	v_cvt_pk_bf16_f32 v123, v124, v125
	ds_write2_b64 v117, v[120:121], v[122:123] offset1:4
	v_pk_mul_f32 v[120:121], v[148:149], v[114:115] op_sel_hi:[1,0]
	v_pk_mul_f32 v[122:123], v[150:151], v[114:115] op_sel_hi:[1,0]
	v_cvt_pk_bf16_f32 v120, v120, v121
	v_cvt_pk_bf16_f32 v121, v122, v123
	v_pk_mul_f32 v[122:123], v[144:145], v[114:115] op_sel_hi:[1,0]
	v_pk_mul_f32 v[124:125], v[146:147], v[114:115] op_sel_hi:[1,0]
	v_add3_u32 v114, s29, v118, 16
	v_cvt_pk_bf16_f32 v122, v122, v123
	v_cvt_pk_bf16_f32 v123, v124, v125
	v_cmp_gt_u32_e32 vcc, s22, v114
	ds_write2_b64 v117, v[120:121], v[122:123] offset0:8 offset1:12
	s_and_saveexec_b64 s[0:1], vcc
	s_cbranch_execz .LBB0_1054
	v_or_b32_e32 v120, s2, v114
	v_mov_b32_e32 v121, s3
	v_lshlrev_b64 v[120:121], 6, v[120:121]
	s_waitcnt vmcnt(1)
	v_lshl_add_u64 v[132:133], s[8:9], 0, v[120:121]
	v_bfe_u32 v244, v132, 6, 8
	v_lshlrev_b32_e32 v244, 3, v244
	v_add_u32_e32 v244, 0x24010, v244
	v_or_b32_e32 v246, 2, v132
	ds_read_b64 v[248:249], v244
	s_waitcnt lgkmcnt(0)
	v_cmp_ne_u32_e64 s[100:101], v248, v246
	s_nop 1
	s_and_saveexec_b64 s[98:99], s[100:101]
	s_cbranch_execz .LrcG0_1
	global_load_dwordx4 v[120:123], v[132:133], off
	global_load_dwordx4 v[124:127], v[132:133], off offset:16
	global_load_dwordx4 v[128:131], v[132:133], off offset:32
	s_nop 0
	global_load_dwordx4 v[132:135], v[132:133], off offset:48
	s_waitcnt vmcnt(3)
	v_mov_b32_e32 v136, v121
	v_mov_b32_e32 v137, v122
	v_mov_b32_e32 v121, v123
	s_waitcnt vmcnt(2)
	v_mov_b32_e32 v122, v125
	v_mov_b32_e32 v123, v126
	v_mov_b32_e32 v125, v127
	v_pk_add_f32 v[120:121], v[136:137], v[120:121]
	v_pk_add_f32 v[122:123], v[122:123], v[124:125]
	v_pk_add_f32 v[120:121], v[120:121], v[120:121] op_sel:[0,1] op_sel_hi:[1,0]
	v_pk_add_f32 v[122:123], v[122:123], v[122:123] op_sel:[0,1] op_sel_hi:[1,0]
	s_waitcnt vmcnt(1)
	v_add_f32_e32 v126, v128, v129
	v_add_f32_e32 v128, v130, v131
	s_waitcnt vmcnt(0)
	v_mov_b32_e32 v127, v134
	v_mov_b32_e32 v129, v135
	v_mov_b32_e32 v121, v132
	v_mov_b32_e32 v123, v133
	v_pk_add_f32 v[124:125], v[126:127], v[128:129]
	v_pk_add_f32 v[120:121], v[120:121], v[122:123]
	s_nop 0
	v_pk_add_f32 v[120:121], v[120:121], v[124:125]
	s_nop 0
	v_add_f32_e32 v112, v120, v121
	v_fmamk_f32 v112, v112, 0x3a800000, v168
	v_mul_f32_e32 v114, 0x4b800000, v112
	v_cmp_gt_f32_e32 vcc, s24, v112
	s_nop 1
	s_nop 0
	v_cndmask_b32_e32 v112, v112, v114, vcc
	v_rsq_f32_e32 v112, v112
	s_nop 0
	v_mul_f32_e32 v114, 0x45800000, v112
	v_cndmask_b32_e32 v112, v112, v114, vcc
	s_nop 0
	v_mov_b32_e32 v247, v112
	ds_write_b64 v244, v[246:247]

; DI void store4(bf16_t* dst, const f32x4& v, float s) { *(u32x2*)dst = (u32x2){pk2(v[0] * s, v[1] * s), pk2(v[2] * s, v[3] * s)}; }
; DI float rstd_from16(const float* p, float inv_n) {
;   const f32x4 a = *(const f32x4*)p, b = *(const f32x4*)(p + 4), c = *(const f32x4*)(p + 8), d = *(const f32x4*)(p + 12);
;   const float s = ((a[0] + a[1]) + (a[2] + a[3])) + ((b[0] + b[1]) + (b[2] + b[3])) + ((c[0] + c[1]) + (c[2] + c[3])) + ((d[0] + d[1]) + (d[2] + d[3]));
;   return rsqrtf(s * inv_n + EPS_);
; DI void ffnup_tile(const Params& p, int layer, int b, int mt, int tn, bf16_t* smem) {
;     ...
;     for (int i = 0; i < 8; ++i) {
;       const int row = wm * 128 + i * 16 + l15, s = s0 + row;
;       const float rs = (s >= 0 && s < S_) ? rstd_from16((const float*)(p.ws + O_SSQ) + ((size_t)b * S_ + s) * 16, 1.f / 1024.f) : 0.f;
; #pragma unroll
;       for (int j = 0; j < 4; ++j) store4(dstb + row * LDU + j * 16, acc[i][j], rs);
.LBB0_1054:
	s_or_b64 exec, exec, s[0:1]
	v_pk_mul_f32 v[104:105], v[104:105], v[112:113] op_sel_hi:[1,0]
	v_pk_mul_f32 v[106:107], v[106:107], v[112:113] op_sel_hi:[1,0]
	v_pk_mul_f32 v[100:101], v[100:101], v[112:113] op_sel_hi:[1,0]
	v_pk_mul_f32 v[102:103], v[102:103], v[112:113] op_sel_hi:[1,0]
	v_pk_mul_f32 v[96:97], v[96:97], v[112:113] op_sel_hi:[1,0]
	v_pk_mul_f32 v[98:99], v[98:99], v[112:113] op_sel_hi:[1,0]
	v_cvt_pk_bf16_f32 v104, v104, v105
	v_cvt_pk_bf16_f32 v105, v106, v107
	v_add_u32_e32 v106, 0x1000, v117
	v_cvt_pk_bf16_f32 v100, v100, v101
	v_cvt_pk_bf16_f32 v101, v102, v103
	v_cvt_pk_bf16_f32 v96, v96, v97
	v_cvt_pk_bf16_f32 v97, v98, v99
	v_pk_mul_f32 v[108:109], v[108:109], v[112:113] op_sel_hi:[1,0]
	v_pk_mul_f32 v[110:111], v[110:111], v[112:113] op_sel_hi:[1,0]
	ds_write2_b64 v106, v[100:101], v[96:97] offset0:40 offset1:44
	v_add3_u32 v97, s29, v118, 32
	v_cvt_pk_bf16_f32 v108, v108, v109
	v_cvt_pk_bf16_f32 v109, v110, v111
	v_cmp_gt_u32_e32 vcc, s22, v97
	v_mov_b32_e32 v96, 0
	v_mov_b32_e32 v98, 0
	ds_write2_b64 v106, v[108:109], v[104:105] offset0:32 offset1:36
	s_and_saveexec_b64 s[0:1], vcc
	s_cbranch_execz .LBB0_1056
	v_or_b32_e32 v98, s2, v97
	v_mov_b32_e32 v99, s3
	v_lshlrev_b64 v[98:99], 6, v[98:99]
	v_lshl_add_u64 v[110:111], s[8:9], 0, v[98:99]
	v_bfe_u32 v244, v110, 6, 8
	v_lshlrev_b32_e32 v244, 3, v244
	v_add_u32_e32 v244, 0x24010, v244
	v_or_b32_e32 v246, 2, v110
	ds_read_b64 v[248:249], v244
	s_waitcnt lgkmcnt(0)
	v_cmp_ne_u32_e64 s[100:101], v248, v246
	s_nop 1
	s_and_saveexec_b64 s[98:99], s[100:101]
	s_cbranch_execz .LrcG0_2
	global_load_dwordx4 v[98:101], v[110:111], off
	global_load_dwordx4 v[102:105], v[110:111], off offset:16
	global_load_dwordx4 v[106:109], v[110:111], off offset:32
	global_load_dwordx4 v[120:123], v[110:111], off offset:48
	s_waitcnt vmcnt(3)
	v_mov_b32_e32 v110, v99
	v_mov_b32_e32 v111, v100
	v_mov_b32_e32 v99, v101
	s_waitcnt vmcnt(2)
	v_mov_b32_e32 v100, v103
	v_mov_b32_e32 v101, v104
	v_mov_b32_e32 v103, v105
	v_pk_add_f32 v[98:99], v[110:111], v[98:99]
	v_pk_add_f32 v[100:101], v[100:101], v[102:103]
	v_pk_add_f32 v[98:99], v[98:99], v[98:99] op_sel:[0,1] op_sel_hi:[1,0]
	v_pk_add_f32 v[100:101], v[100:101], v[100:101] op_sel:[0,1] op_sel_hi:[1,0]
	s_waitcnt vmcnt(1)
	v_add_f32_e32 v104, v106, v107
	v_add_f32_e32 v106, v108, v109
	s_waitcnt vmcnt(0)
	v_mov_b32_e32 v105, v122
	v_mov_b32_e32 v107, v123
	v_mov_b32_e32 v99, v120
	v_mov_b32_e32 v101, v121
	v_pk_add_f32 v[102:103], v[104:105], v[106:107]
	v_pk_add_f32 v[98:99], v[98:99], v[100:101]
	s_nop 0
	v_pk_add_f32 v[98:99], v[98:99], v[102:103]
	s_nop 0
	v_add_f32_e32 v97, v98, v99
	v_fmamk_f32 v97, v97, 0x3a800000, v168
	v_mul_f32_e32 v98, 0x4b800000, v97
	v_cmp_gt_f32_e32 vcc, s24, v97
	s_nop 1
	s_nop 0
	v_cndmask_b32_e32 v97, v97, v98, vcc
	v_rsq_f32_e32 v97, v97
	s_nop 0
	v_mul_f32_e32 v98, 0x45800000, v97
	v_cndmask_b32_e32 v98, v97, v98, vcc
	s_nop 0
	v_mov_b32_e32 v247, v98
	ds_write_b64 v244, v[246:247]

; DI void store4(bf16_t* dst, const f32x4& v, float s) { *(u32x2*)dst = (u32x2){pk2(v[0] * s, v[1] * s), pk2(v[2] * s, v[3] * s)}; }
; DI float rstd_from16(const float* p, float inv_n) {
;   const f32x4 a = *(const f32x4*)p, b = *(const f32x4*)(p + 4), c = *(const f32x4*)(p + 8), d = *(const f32x4*)(p + 12);
;   const float s = ((a[0] + a[1]) + (a[2] + a[3])) + ((b[0] + b[1]) + (b[2] + b[3])) + ((c[0] + c[1]) + (c[2] + c[3])) + ((d[0] + d[1]) + (d[2] + d[3]));
;   return rsqrtf(s * inv_n + EPS_);
; DI void ffnup_tile(const Params& p, int layer, int b, int mt, int tn, bf16_t* smem) {
;     ...
;     for (int i = 0; i < 8; ++i) {
;       const int row = wm * 128 + i * 16 + l15, s = s0 + row;
;       const float rs = (s >= 0 && s < S_) ? rstd_from16((const float*)(p.ws + O_SSQ) + ((size_t)b * S_ + s) * 16, 1.f / 1024.f) : 0.f;
; #pragma unroll
;       for (int j = 0; j < 4; ++j) store4(dstb + row * LDU + j * 16, acc[i][j], rs);
.LBB0_1056:
	s_or_b64 exec, exec, s[0:1]
	v_pk_mul_f32 v[88:89], v[88:89], v[98:99] op_sel_hi:[1,0]
	v_pk_mul_f32 v[90:91], v[90:91], v[98:99] op_sel_hi:[1,0]
	v_pk_mul_f32 v[84:85], v[84:85], v[98:99] op_sel_hi:[1,0]
	v_pk_mul_f32 v[86:87], v[86:87], v[98:99] op_sel_hi:[1,0]
	v_pk_mul_f32 v[80:81], v[80:81], v[98:99] op_sel_hi:[1,0]
	v_pk_mul_f32 v[82:83], v[82:83], v[98:99] op_sel_hi:[1,0]
	v_cvt_pk_bf16_f32 v88, v88, v89
	v_cvt_pk_bf16_f32 v89, v90, v91
	v_add_u32_e32 v90, 0x2000, v117
	v_cvt_pk_bf16_f32 v84, v84, v85
	v_cvt_pk_bf16_f32 v85, v86, v87
	v_cvt_pk_bf16_f32 v80, v80, v81
	v_cvt_pk_bf16_f32 v81, v82, v83
	v_pk_mul_f32 v[92:93], v[92:93], v[98:99] op_sel_hi:[1,0]
	v_pk_mul_f32 v[94:95], v[94:95], v[98:99] op_sel_hi:[1,0]
	ds_write2_b64 v90, v[84:85], v[80:81] offset0:72 offset1:76
	v_add3_u32 v80, s29, v118, 48
	v_cvt_pk_bf16_f32 v92, v92, v93
	v_cvt_pk_bf16_f32 v93, v94, v95
	v_cmp_gt_u32_e32 vcc, s22, v80
	ds_write2_b64 v90, v[92:93], v[88:89] offset0:64 offset1:68
	s_and_saveexec_b64 s[0:1], vcc
	s_cbranch_execz .LBB0_1058
	v_or_b32_e32 v80, s2, v80
	v_mov_b32_e32 v81, s3
	v_lshlrev_b64 v[80:81], 6, v[80:81]
	v_lshl_add_u64 v[92:93], s[8:9], 0, v[80:81]
	v_bfe_u32 v244, v92, 6, 8
	v_lshlrev_b32_e32 v244, 3, v244
	v_add_u32_e32 v244, 0x24010, v244
	v_or_b32_e32 v246, 2, v92
	ds_read_b64 v[248:249], v244
	s_waitcnt lgkmcnt(0)
	v_cmp_ne_u32_e64 s[100:101], v248, v246
	s_nop 1
	s_and_saveexec_b64 s[98:99], s[100:101]
	s_cbranch_execz .LrcG0_3
	global_load_dwordx4 v[80:83], v[92:93], off
	global_load_dwordx4 v[84:87], v[92:93], off offset:16
	global_load_dwordx4 v[88:91], v[92:93], off offset:32
	s_nop 0
	global_load_dwordx4 v[92:95], v[92:93], off offset:48
	s_waitcnt vmcnt(3)
	v_mov_b32_e32 v96, v81
	v_mov_b32_e32 v97, v82
	v_mov_b32_e32 v81, v83
	s_waitcnt vmcnt(2)
	v_mov_b32_e32 v82, v85
	v_mov_b32_e32 v83, v86
	v_mov_b32_e32 v85, v87
	v_pk_add_f32 v[80:81], v[96:97], v[80:81]
	v_pk_add_f32 v[82:83], v[82:83], v[84:85]
	v_pk_add_f32 v[80:81], v[80:81], v[80:81] op_sel:[0,1] op_sel_hi:[1,0]
	v_pk_add_f32 v[82:83], v[82:83], v[82:83] op_sel:[0,1] op_sel_hi:[1,0]
	s_waitcnt vmcnt(1)
	v_add_f32_e32 v86, v88, v89
	v_add_f32_e32 v88, v90, v91
	s_waitcnt vmcnt(0)
	v_mov_b32_e32 v87, v94
	v_mov_b32_e32 v89, v95
	v_mov_b32_e32 v81, v92
	v_mov_b32_e32 v83, v93
	v_pk_add_f32 v[84:85], v[86:87], v[88:89]
	v_pk_add_f32 v[80:81], v[80:81], v[82:83]
	s_nop 0
	v_pk_add_f32 v[80:81], v[80:81], v[84:85]
	s_nop 0
	v_add_f32_e32 v80, v80, v81
	v_fmamk_f32 v80, v80, 0x3a800000, v168
	v_mul_f32_e32 v81, 0x4b800000, v80
	v_cmp_gt_f32_e32 vcc, s24, v80
	s_nop 1
	s_nop 0
	v_cndmask_b32_e32 v80, v80, v81, vcc
	v_rsq_f32_e32 v80, v80
	s_nop 0
	v_mul_f32_e32 v81, 0x45800000, v80
	v_cndmask_b32_e32 v96, v80, v81, vcc
	s_nop 0
	v_mov_b32_e32 v247, v96
	ds_write_b64 v244, v[246:247]

; DI void store4(bf16_t* dst, const f32x4& v, float s) { *(u32x2*)dst = (u32x2){pk2(v[0] * s, v[1] * s), pk2(v[2] * s, v[3] * s)}; }
; DI float rstd_from16(const float* p, float inv_n) {
;   const f32x4 a = *(const f32x4*)p, b = *(const f32x4*)(p + 4), c = *(const f32x4*)(p + 8), d = *(const f32x4*)(p + 12);
;   const float s = ((a[0] + a[1]) + (a[2] + a[3])) + ((b[0] + b[1]) + (b[2] + b[3])) + ((c[0] + c[1]) + (c[2] + c[3])) + ((d[0] + d[1]) + (d[2] + d[3]));
;   return rsqrtf(s * inv_n + EPS_);
; DI void ffnup_tile(const Params& p, int layer, int b, int mt, int tn, bf16_t* smem) {
;     ...
;     for (int i = 0; i < 8; ++i) {
;       const int row = wm * 128 + i * 16 + l15, s = s0 + row;
;       const float rs = (s >= 0 && s < S_) ? rstd_from16((const float*)(p.ws + O_SSQ) + ((size_t)b * S_ + s) * 16, 1.f / 1024.f) : 0.f;
; #pragma unroll
;       for (int j = 0; j < 4; ++j) store4(dstb + row * LDU + j * 16, acc[i][j], rs);
.LBB0_1058:
	s_or_b64 exec, exec, s[0:1]
	v_pk_mul_f32 v[72:73], v[72:73], v[96:97] op_sel_hi:[1,0]
	v_pk_mul_f32 v[74:75], v[74:75], v[96:97] op_sel_hi:[1,0]
	v_pk_mul_f32 v[68:69], v[68:69], v[96:97] op_sel_hi:[1,0]
	v_pk_mul_f32 v[70:71], v[70:71], v[96:97] op_sel_hi:[1,0]
	v_pk_mul_f32 v[64:65], v[64:65], v[96:97] op_sel_hi:[1,0]
	v_pk_mul_f32 v[66:67], v[66:67], v[96:97] op_sel_hi:[1,0]
	v_cvt_pk_bf16_f32 v72, v72, v73
	v_cvt_pk_bf16_f32 v73, v74, v75
	v_add_u32_e32 v74, 0x3000, v117
	v_cvt_pk_bf16_f32 v68, v68, v69
	v_cvt_pk_bf16_f32 v69, v70, v71
	v_cvt_pk_bf16_f32 v64, v64, v65
	v_cvt_pk_bf16_f32 v65, v66, v67
	v_pk_mul_f32 v[76:77], v[76:77], v[96:97] op_sel_hi:[1,0]
	v_pk_mul_f32 v[78:79], v[78:79], v[96:97] op_sel_hi:[1,0]
	ds_write2_b64 v74, v[68:69], v[64:65] offset0:104 offset1:108
	v_add3_u32 v65, s29, v118, 64
	v_cvt_pk_bf16_f32 v76, v76, v77
	v_cvt_pk_bf16_f32 v77, v78, v79
	v_cmp_gt_u32_e32 vcc, s22, v65
	v_mov_b32_e32 v64, 0
	v_mov_b32_e32 v66, 0
	ds_write2_b64 v74, v[76:77], v[72:73] offset0:96 offset1:100
	s_and_saveexec_b64 s[0:1], vcc
	s_cbranch_execz .LBB0_1060
	v_or_b32_e32 v66, s2, v65
	v_mov_b32_e32 v67, s3
	v_lshlrev_b64 v[66:67], 6, v[66:67]
	v_lshl_add_u64 v[78:79], s[8:9], 0, v[66:67]
	v_bfe_u32 v244, v78, 6, 8
	v_lshlrev_b32_e32 v244, 3, v244
	v_add_u32_e32 v244, 0x24010, v244
	v_or_b32_e32 v246, 2, v78
	ds_read_b64 v[248:249], v244
	s_waitcnt lgkmcnt(0)
	v_cmp_ne_u32_e64 s[100:101], v248, v246
	s_nop 1
	s_and_saveexec_b64 s[98:99], s[100:101]
	s_cbranch_execz .LrcG0_4
	global_load_dwordx4 v[66:69], v[78:79], off
	global_load_dwordx4 v[70:73], v[78:79], off offset:16
	global_load_dwordx4 v[74:77], v[78:79], off offset:32
	s_nop 0
	global_load_dwordx4 v[78:81], v[78:79], off offset:48
	s_waitcnt vmcnt(3)
	v_mov_b32_e32 v82, v67
	v_mov_b32_e32 v83, v68
	v_mov_b32_e32 v67, v69
	s_waitcnt vmcnt(2)
	v_mov_b32_e32 v68, v71
	v_mov_b32_e32 v69, v72
	v_mov_b32_e32 v71, v73
	v_pk_add_f32 v[66:67], v[82:83], v[66:67]
	v_pk_add_f32 v[68:69], v[68:69], v[70:71]
	v_pk_add_f32 v[66:67], v[66:67], v[66:67] op_sel:[0,1] op_sel_hi:[1,0]
	v_pk_add_f32 v[68:69], v[68:69], v[68:69] op_sel:[0,1] op_sel_hi:[1,0]
	s_waitcnt vmcnt(1)
	v_add_f32_e32 v72, v74, v75
	v_add_f32_e32 v74, v76, v77
	s_waitcnt vmcnt(0)
	v_mov_b32_e32 v73, v80
	v_mov_b32_e32 v75, v81
	v_mov_b32_e32 v67, v78
	v_mov_b32_e32 v69, v79
	v_pk_add_f32 v[70:71], v[72:73], v[74:75]
	v_pk_add_f32 v[66:67], v[66:67], v[68:69]
	s_nop 0
	v_pk_add_f32 v[66:67], v[66:67], v[70:71]
	s_nop 0
	v_add_f32_e32 v65, v66, v67
	v_fmamk_f32 v65, v65, 0x3a800000, v168
	v_mul_f32_e32 v66, 0x4b800000, v65
	v_cmp_gt_f32_e32 vcc, s24, v65
	s_nop 1
	s_nop 0
	v_cndmask_b32_e32 v65, v65, v66, vcc
	v_rsq_f32_e32 v65, v65
	s_nop 0
	v_mul_f32_e32 v66, 0x45800000, v65
	v_cndmask_b32_e32 v66, v65, v66, vcc
	s_nop 0
	v_mov_b32_e32 v247, v66
	ds_write_b64 v244, v[246:247]

; DI void store4(bf16_t* dst, const f32x4& v, float s) { *(u32x2*)dst = (u32x2){pk2(v[0] * s, v[1] * s), pk2(v[2] * s, v[3] * s)}; }
; DI float rstd_from16(const float* p, float inv_n) {
;   const f32x4 a = *(const f32x4*)p, b = *(const f32x4*)(p + 4), c = *(const f32x4*)(p + 8), d = *(const f32x4*)(p + 12);
;   const float s = ((a[0] + a[1]) + (a[2] + a[3])) + ((b[0] + b[1]) + (b[2] + b[3])) + ((c[0] + c[1]) + (c[2] + c[3])) + ((d[0] + d[1]) + (d[2] + d[3]));
;   return rsqrtf(s * inv_n + EPS_);
; DI void ffnup_tile(const Params& p, int layer, int b, int mt, int tn, bf16_t* smem) {
;     ...
;     for (int i = 0; i < 8; ++i) {
;       const int row = wm * 128 + i * 16 + l15, s = s0 + row;
;       const float rs = (s >= 0 && s < S_) ? rstd_from16((const float*)(p.ws + O_SSQ) + ((size_t)b * S_ + s) * 16, 1.f / 1024.f) : 0.f;
; #pragma unroll
;       for (int j = 0; j < 4; ++j) store4(dstb + row * LDU + j * 16, acc[i][j], rs);
.LBB0_1060:
	s_or_b64 exec, exec, s[0:1]
	v_pk_mul_f32 v[56:57], v[56:57], v[66:67] op_sel_hi:[1,0]
	v_pk_mul_f32 v[58:59], v[58:59], v[66:67] op_sel_hi:[1,0]
	v_pk_mul_f32 v[52:53], v[52:53], v[66:67] op_sel_hi:[1,0]
	v_pk_mul_f32 v[54:55], v[54:55], v[66:67] op_sel_hi:[1,0]
	v_pk_mul_f32 v[48:49], v[48:49], v[66:67] op_sel_hi:[1,0]
	v_pk_mul_f32 v[50:51], v[50:51], v[66:67] op_sel_hi:[1,0]
	v_cvt_pk_bf16_f32 v56, v56, v57
	v_cvt_pk_bf16_f32 v57, v58, v59
	v_add_u32_e32 v58, 0x4000, v117
	v_cvt_pk_bf16_f32 v52, v52, v53
	v_cvt_pk_bf16_f32 v53, v54, v55
	v_cvt_pk_bf16_f32 v48, v48, v49
	v_cvt_pk_bf16_f32 v49, v50, v51
	v_pk_mul_f32 v[60:61], v[60:61], v[66:67] op_sel_hi:[1,0]
	v_pk_mul_f32 v[62:63], v[62:63], v[66:67] op_sel_hi:[1,0]
	ds_write2_b64 v58, v[52:53], v[48:49] offset0:136 offset1:140
	v_add_u32_e32 v48, 0x50, v116
	v_cvt_pk_bf16_f32 v60, v60, v61
	v_cvt_pk_bf16_f32 v61, v62, v63
	v_cmp_gt_u32_e32 vcc, s22, v48
	ds_write2_b64 v58, v[60:61], v[56:57] offset0:128 offset1:132
	s_and_saveexec_b64 s[0:1], vcc
	s_cbranch_execz .LBB0_1062
	v_or_b32_e32 v48, s2, v48
	v_mov_b32_e32 v49, s3
	v_lshlrev_b64 v[48:49], 6, v[48:49]
	v_lshl_add_u64 v[60:61], s[8:9], 0, v[48:49]
	v_bfe_u32 v244, v60, 6, 8
	v_lshlrev_b32_e32 v244, 3, v244
	v_add_u32_e32 v244, 0x24010, v244
	v_or_b32_e32 v246, 2, v60
	ds_read_b64 v[248:249], v244
	s_waitcnt lgkmcnt(0)
	v_cmp_ne_u32_e64 s[100:101], v248, v246
	s_nop 1
	s_and_saveexec_b64 s[98:99], s[100:101]
	s_cbranch_execz .LrcG0_5
	global_load_dwordx4 v[48:51], v[60:61], off
	global_load_dwordx4 v[52:55], v[60:61], off offset:16
	global_load_dwordx4 v[56:59], v[60:61], off offset:32
	s_nop 0
	global_load_dwordx4 v[60:63], v[60:61], off offset:48
	s_waitcnt vmcnt(3)
	v_mov_b32_e32 v64, v49
	v_mov_b32_e32 v65, v50
	v_mov_b32_e32 v49, v51
	s_waitcnt vmcnt(2)
	v_mov_b32_e32 v50, v53
	v_mov_b32_e32 v51, v54
	v_mov_b32_e32 v53, v55
	v_pk_add_f32 v[48:49], v[64:65], v[48:49]
	v_pk_add_f32 v[50:51], v[50:51], v[52:53]
	v_pk_add_f32 v[48:49], v[48:49], v[48:49] op_sel:[0,1] op_sel_hi:[1,0]
	v_pk_add_f32 v[50:51], v[50:51], v[50:51] op_sel:[0,1] op_sel_hi:[1,0]
	s_waitcnt vmcnt(1)
	v_add_f32_e32 v54, v56, v57
	v_add_f32_e32 v56, v58, v59
	s_waitcnt vmcnt(0)
	v_mov_b32_e32 v55, v62
	v_mov_b32_e32 v57, v63
	v_mov_b32_e32 v49, v60
	v_mov_b32_e32 v51, v61
	v_pk_add_f32 v[52:53], v[54:55], v[56:57]
	v_pk_add_f32 v[48:49], v[48:49], v[50:51]
	s_nop 0
	v_pk_add_f32 v[48:49], v[48:49], v[52:53]
	s_nop 0
	v_add_f32_e32 v48, v48, v49
	v_fmamk_f32 v48, v48, 0x3a800000, v168
	v_mul_f32_e32 v49, 0x4b800000, v48
	v_cmp_gt_f32_e32 vcc, s24, v48
	s_nop 1
	s_nop 0
	v_cndmask_b32_e32 v48, v48, v49, vcc
	v_rsq_f32_e32 v48, v48
	s_nop 0
	v_mul_f32_e32 v49, 0x45800000, v48
	v_cndmask_b32_e32 v64, v48, v49, vcc
	s_nop 0
	v_mov_b32_e32 v247, v64
	ds_write_b64 v244, v[246:247]

; DI void store4(bf16_t* dst, const f32x4& v, float s) { *(u32x2*)dst = (u32x2){pk2(v[0] * s, v[1] * s), pk2(v[2] * s, v[3] * s)}; }
; DI float rstd_from16(const float* p, float inv_n) {
;   const f32x4 a = *(const f32x4*)p, b = *(const f32x4*)(p + 4), c = *(const f32x4*)(p + 8), d = *(const f32x4*)(p + 12);
;   const float s = ((a[0] + a[1]) + (a[2] + a[3])) + ((b[0] + b[1]) + (b[2] + b[3])) + ((c[0] + c[1]) + (c[2] + c[3])) + ((d[0] + d[1]) + (d[2] + d[3]));
;   return rsqrtf(s * inv_n + EPS_);
; DI void ffnup_tile(const Params& p, int layer, int b, int mt, int tn, bf16_t* smem) {
;     ...
;     for (int i = 0; i < 8; ++i) {
;       const int row = wm * 128 + i * 16 + l15, s = s0 + row;
;       const float rs = (s >= 0 && s < S_) ? rstd_from16((const float*)(p.ws + O_SSQ) + ((size_t)b * S_ + s) * 16, 1.f / 1024.f) : 0.f;
; #pragma unroll
;       for (int j = 0; j < 4; ++j) store4(dstb + row * LDU + j * 16, acc[i][j], rs);
.LBB0_1062:
	s_or_b64 exec, exec, s[0:1]
	v_pk_mul_f32 v[40:41], v[40:41], v[64:65] op_sel_hi:[1,0]
	v_pk_mul_f32 v[42:43], v[42:43], v[64:65] op_sel_hi:[1,0]
	v_pk_mul_f32 v[36:37], v[36:37], v[64:65] op_sel_hi:[1,0]
	v_pk_mul_f32 v[38:39], v[38:39], v[64:65] op_sel_hi:[1,0]
	v_pk_mul_f32 v[32:33], v[32:33], v[64:65] op_sel_hi:[1,0]
	v_pk_mul_f32 v[34:35], v[34:35], v[64:65] op_sel_hi:[1,0]
	v_cvt_pk_bf16_f32 v40, v40, v41
	v_cvt_pk_bf16_f32 v41, v42, v43
	v_add_u32_e32 v42, 0x5000, v117
	v_cvt_pk_bf16_f32 v36, v36, v37
	v_cvt_pk_bf16_f32 v37, v38, v39
	v_cvt_pk_bf16_f32 v32, v32, v33
	v_cvt_pk_bf16_f32 v33, v34, v35
	v_pk_mul_f32 v[44:45], v[44:45], v[64:65] op_sel_hi:[1,0]
	v_pk_mul_f32 v[46:47], v[46:47], v[64:65] op_sel_hi:[1,0]
	ds_write2_b64 v42, v[36:37], v[32:33] offset0:168 offset1:172
	v_add_u32_e32 v33, 0x60, v116
	v_cvt_pk_bf16_f32 v44, v44, v45
	v_cvt_pk_bf16_f32 v45, v46, v47
	v_cmp_gt_u32_e32 vcc, s22, v33
	v_mov_b32_e32 v32, 0
	v_mov_b32_e32 v34, 0
	ds_write2_b64 v42, v[44:45], v[40:41] offset0:160 offset1:164
	s_and_saveexec_b64 s[0:1], vcc
	s_cbranch_execz .LBB0_1064
	v_or_b32_e32 v34, s2, v33
	v_mov_b32_e32 v35, s3
	v_lshlrev_b64 v[34:35], 6, v[34:35]
	v_lshl_add_u64 v[46:47], s[8:9], 0, v[34:35]
	v_bfe_u32 v244, v46, 6, 8
	v_lshlrev_b32_e32 v244, 3, v244
	v_add_u32_e32 v244, 0x24010, v244
	v_or_b32_e32 v246, 2, v46
	ds_read_b64 v[248:249], v244
	s_waitcnt lgkmcnt(0)
	v_cmp_ne_u32_e64 s[100:101], v248, v246
	s_nop 1
	s_and_saveexec_b64 s[98:99], s[100:101]
	s_cbranch_execz .LrcG0_6
	global_load_dwordx4 v[34:37], v[46:47], off
	global_load_dwordx4 v[38:41], v[46:47], off offset:16
	global_load_dwordx4 v[42:45], v[46:47], off offset:32
	s_nop 0
	global_load_dwordx4 v[46:49], v[46:47], off offset:48
	s_waitcnt vmcnt(3)
	v_mov_b32_e32 v50, v35
	v_mov_b32_e32 v51, v36
	v_mov_b32_e32 v35, v37
	s_waitcnt vmcnt(2)
	v_mov_b32_e32 v36, v39
	v_mov_b32_e32 v37, v40
	v_mov_b32_e32 v39, v41
	v_pk_add_f32 v[34:35], v[50:51], v[34:35]
	v_pk_add_f32 v[36:37], v[36:37], v[38:39]
	v_pk_add_f32 v[34:35], v[34:35], v[34:35] op_sel:[0,1] op_sel_hi:[1,0]
	v_pk_add_f32 v[36:37], v[36:37], v[36:37] op_sel:[0,1] op_sel_hi:[1,0]
	s_waitcnt vmcnt(1)
	v_add_f32_e32 v40, v42, v43
	v_add_f32_e32 v42, v44, v45
	s_waitcnt vmcnt(0)
	v_mov_b32_e32 v41, v48
	v_mov_b32_e32 v43, v49
	v_mov_b32_e32 v35, v46
	v_mov_b32_e32 v37, v47
	v_pk_add_f32 v[38:39], v[40:41], v[42:43]
	v_pk_add_f32 v[34:35], v[34:35], v[36:37]
	s_nop 0
	v_pk_add_f32 v[34:35], v[34:35], v[38:39]
	s_nop 0
	v_add_f32_e32 v33, v34, v35
	v_fmamk_f32 v33, v33, 0x3a800000, v168
	v_mul_f32_e32 v34, 0x4b800000, v33
	v_cmp_gt_f32_e32 vcc, s24, v33
	s_nop 1
	s_nop 0
	v_cndmask_b32_e32 v33, v33, v34, vcc
	v_rsq_f32_e32 v33, v33
	s_nop 0
	v_mul_f32_e32 v34, 0x45800000, v33
	v_cndmask_b32_e32 v34, v33, v34, vcc
	s_nop 0
	v_mov_b32_e32 v247, v34
	ds_write_b64 v244, v[246:247]

; DI void store4(bf16_t* dst, const f32x4& v, float s) { *(u32x2*)dst = (u32x2){pk2(v[0] * s, v[1] * s), pk2(v[2] * s, v[3] * s)}; }
; DI float rstd_from16(const float* p, float inv_n) {
;   const f32x4 a = *(const f32x4*)p, b = *(const f32x4*)(p + 4), c = *(const f32x4*)(p + 8), d = *(const f32x4*)(p + 12);
;   const float s = ((a[0] + a[1]) + (a[2] + a[3])) + ((b[0] + b[1]) + (b[2] + b[3])) + ((c[0] + c[1]) + (c[2] + c[3])) + ((d[0] + d[1]) + (d[2] + d[3]));
;   return rsqrtf(s * inv_n + EPS_);
; DI void ffnup_tile(const Params& p, int layer, int b, int mt, int tn, bf16_t* smem) {
;     ...
;     for (int i = 0; i < 8; ++i) {
;       const int row = wm * 128 + i * 16 + l15, s = s0 + row;
;       const float rs = (s >= 0 && s < S_) ? rstd_from16((const float*)(p.ws + O_SSQ) + ((size_t)b * S_ + s) * 16, 1.f / 1024.f) : 0.f;
; #pragma unroll
;       for (int j = 0; j < 4; ++j) store4(dstb + row * LDU + j * 16, acc[i][j], rs);
.LBB0_1064:
	s_or_b64 exec, exec, s[0:1]
	v_pk_mul_f32 v[24:25], v[24:25], v[34:35] op_sel_hi:[1,0]
	v_pk_mul_f32 v[26:27], v[26:27], v[34:35] op_sel_hi:[1,0]
	v_pk_mul_f32 v[20:21], v[20:21], v[34:35] op_sel_hi:[1,0]
	v_pk_mul_f32 v[22:23], v[22:23], v[34:35] op_sel_hi:[1,0]
	v_pk_mul_f32 v[16:17], v[16:17], v[34:35] op_sel_hi:[1,0]
	v_pk_mul_f32 v[18:19], v[18:19], v[34:35] op_sel_hi:[1,0]
	v_cvt_pk_bf16_f32 v24, v24, v25
	v_cvt_pk_bf16_f32 v25, v26, v27
	v_add_u32_e32 v26, 0x6000, v117
	v_cvt_pk_bf16_f32 v20, v20, v21
	v_cvt_pk_bf16_f32 v21, v22, v23
	v_cvt_pk_bf16_f32 v16, v16, v17
	v_cvt_pk_bf16_f32 v17, v18, v19
	v_pk_mul_f32 v[28:29], v[28:29], v[34:35] op_sel_hi:[1,0]
	v_pk_mul_f32 v[30:31], v[30:31], v[34:35] op_sel_hi:[1,0]
	ds_write2_b64 v26, v[20:21], v[16:17] offset0:200 offset1:204
	v_add_u32_e32 v16, 0x70, v116
	v_cvt_pk_bf16_f32 v28, v28, v29
	v_cvt_pk_bf16_f32 v29, v30, v31
	v_cmp_gt_u32_e32 vcc, s22, v16
	ds_write2_b64 v26, v[28:29], v[24:25] offset0:192 offset1:196
	s_and_saveexec_b64 s[0:1], vcc
	s_cbranch_execz .LBB0_1066
	v_or_b32_e32 v16, s2, v16
	v_mov_b32_e32 v17, s3
	v_lshlrev_b64 v[16:17], 6, v[16:17]
	v_lshl_add_u64 v[28:29], s[8:9], 0, v[16:17]
	v_bfe_u32 v244, v28, 6, 8
	v_lshlrev_b32_e32 v244, 3, v244
	v_add_u32_e32 v244, 0x24010, v244
	v_or_b32_e32 v246, 2, v28
	ds_read_b64 v[248:249], v244
	s_waitcnt lgkmcnt(0)
	v_cmp_ne_u32_e64 s[100:101], v248, v246
	s_nop 1
	s_and_saveexec_b64 s[98:99], s[100:101]
	s_cbranch_execz .LrcG0_7
	global_load_dwordx4 v[16:19], v[28:29], off
	global_load_dwordx4 v[20:23], v[28:29], off offset:16
	global_load_dwordx4 v[24:27], v[28:29], off offset:32
	s_nop 0
	global_load_dwordx4 v[28:31], v[28:29], off offset:48
	s_waitcnt vmcnt(3)
	v_mov_b32_e32 v32, v17
	v_mov_b32_e32 v33, v18
	v_mov_b32_e32 v17, v19
	s_waitcnt vmcnt(2)
	v_mov_b32_e32 v18, v21
	v_mov_b32_e32 v19, v22
	v_mov_b32_e32 v21, v23
	v_pk_add_f32 v[16:17], v[32:33], v[16:17]
	v_pk_add_f32 v[18:19], v[18:19], v[20:21]
	v_pk_add_f32 v[16:17], v[16:17], v[16:17] op_sel:[0,1] op_sel_hi:[1,0]
	v_pk_add_f32 v[18:19], v[18:19], v[18:19] op_sel:[0,1] op_sel_hi:[1,0]
	s_waitcnt vmcnt(1)
	v_add_f32_e32 v22, v24, v25
	v_add_f32_e32 v24, v26, v27
	s_waitcnt vmcnt(0)
	v_mov_b32_e32 v23, v30
	v_mov_b32_e32 v25, v31
	v_mov_b32_e32 v17, v28
	v_mov_b32_e32 v19, v29
	v_pk_add_f32 v[20:21], v[22:23], v[24:25]
	v_pk_add_f32 v[16:17], v[16:17], v[18:19]
	s_nop 0
	v_pk_add_f32 v[16:17], v[16:17], v[20:21]
	s_nop 0
	v_add_f32_e32 v16, v16, v17
	v_fmamk_f32 v16, v16, 0x3a800000, v168
	v_mul_f32_e32 v17, 0x4b800000, v16
	v_cmp_gt_f32_e32 vcc, s24, v16
	s_nop 1
	s_nop 0
	v_cndmask_b32_e32 v16, v16, v17, vcc
	v_rsq_f32_e32 v16, v16
	s_nop 0
	v_mul_f32_e32 v17, 0x45800000, v16
	v_cndmask_b32_e32 v32, v16, v17, vcc
	s_nop 0
	v_mov_b32_e32 v247, v32
	ds_write_b64 v244, v[246:247]

; DI unsigned pk2(float lo, float hi) { f32x2 v = {lo, hi}; return __builtin_bit_cast(unsigned, __builtin_convertvector(v, bfx2)); }
; DI float sigmoidf_(float x) { return 1.f / (1.f + __expf(-x)); }
; DI float rstd_from16(const float* p, float inv_n) {
;   const f32x4 a = *(const f32x4*)p, b = *(const f32x4*)(p + 4), c = *(const f32x4*)(p + 8), d = *(const f32x4*)(p + 12);
;   const float s = ((a[0] + a[1]) + (a[2] + a[3])) + ((b[0] + b[1]) + (b[2] + b[3])) + ((c[0] + c[1]) + (c[2] + c[3])) + ((d[0] + d[1]) + (d[2] + d[3]));
;   return rsqrtf(s * inv_n + EPS_);
; template <bool SWAP> DI void inproj_tile(const Params& p, int layer, int tm, int tn, bf16_t* smem) {
;     ...
;       for (int i = 0; i < 8; ++i) {
;         const int t = trow0 + i * 16 + l15; const float rs = rstd_from16(ssq + (size_t)t * 16, 1.f / 1024.f);
;         float* gt = (float*)(p.ws + O_GATES) + (size_t)t * 24; float* lf = (float*)(p.ws + O_LOGF) + (size_t)t * 8;
; #pragma unroll
;         for (int r = 0; r < 4; ++r) gt[quad * 4 + r] = sigmoidf_(acc[i][0][r] * rs);
;         if (quad < 2) {
; #pragma unroll
;           for (int r = 0; r < 4; ++r) gt[16 + quad * 4 + r] = sigmoidf_(acc[i][1][r] * rs);
;         } else {
; #pragma unroll
;           for (int r = 0; r < 4; ++r) { const int h = (quad - 2) * 4 + r; const float xx = acc[i][1][r] * rs + p.b_forget[layer * 8 + h]; lf[h] = fminf(xx, 0.f) - log1pf(__expf(-fabsf(xx))); }
;         }
;         const float* rp = (const float*)(p.ws + O_ROPE16) + (size_t)t * 32 + quad * 8; float o1[4], o2[4];
; #pragma unroll
;         for (int r = 0; r < 4; ++r) { const float cs = rp[2 * r], sn = rp[2 * r + 1], x1 = acc[i][2][r] * rs, x2 = acc[i][3][r] * rs; o1[r] = x1 * cs - x2 * sn; o2[r] = x2 * cs + x1 * sn; }
;         bf16_t* kp = (bf16_t*)(p.ws + O_MLAKPE) + (size_t)t * 32 + quad * 4;
;         *(u32x2*)kp = (u32x2){pk2(o1[0], o1[1]), pk2(o1[2], o1[3])}; *(u32x2*)(kp + 16) = (u32x2){pk2(o2[0], o2[1]), pk2(o2[2], o2[3])};
;       }
.LBB0_1299:
	s_or_b64 exec, exec, s[2:3]
	s_nop 0
	v_lshl_add_u64 v[120:121], v[132:133], 2, s[10:11]
	v_lshlrev_b32_e32 v122, 5, v144
	v_mov_b32_e32 v123, v161
	v_lshl_add_u64 v[124:125], v[120:121], 0, v[122:123]
	global_load_dwordx4 v[120:123], v[124:125], off offset:16
	s_nop 0
	global_load_dwordx4 v[124:127], v[124:125], off
	v_pk_mul_f32 v[112:113], v[112:113], v[130:131] op_sel_hi:[1,0]
	v_pk_mul_f32 v[116:117], v[116:117], v[130:131] op_sel_hi:[1,0]
	v_readlane_b32 s2, v240, 32
	v_readlane_b32 s3, v240, 33
	s_waitcnt vmcnt(0)
	v_mov_b32_e32 v135, v126
	v_mov_b32_e32 v126, v125
	v_mov_b32_e32 v134, v124
	v_pk_mul_f32 v[124:125], v[112:113], v[126:127]
	s_nop 0
	v_pk_fma_f32 v[124:125], v[116:117], v[134:135], v[124:125] neg_lo:[0,0,1] neg_hi:[0,0,1]
	v_pk_mul_f32 v[116:117], v[116:117], v[126:127]
	v_or_b32_e32 v126, 16, v128
	v_pk_fma_f32 v[116:117], v[112:113], v[134:135], v[116:117]
	v_pk_mul_f32 v[112:113], v[114:115], v[130:131] op_sel_hi:[1,0]
	v_pk_mul_f32 v[114:115], v[118:119], v[130:131] op_sel_hi:[1,0]
	v_mov_b32_e32 v119, v122
	v_mov_b32_e32 v122, v121
	v_mov_b32_e32 v118, v120
	v_pk_mul_f32 v[120:121], v[112:113], v[122:123]
	v_ashrrev_i32_e32 v127, 31, v126
	v_pk_fma_f32 v[120:121], v[114:115], v[118:119], v[120:121] neg_lo:[0,0,1] neg_hi:[0,0,1]
	v_pk_mul_f32 v[114:115], v[114:115], v[122:123]
	v_cvt_pk_bf16_f32 v122, v124, v125
	v_pk_fma_f32 v[114:115], v[112:113], v[118:119], v[114:115]
	v_lshl_add_u64 v[118:119], v[132:133], 1, s[2:3]
	v_lshlrev_b32_e32 v112, 1, v131
	v_mov_b32_e32 v113, v161
	v_lshl_add_u64 v[118:119], v[118:119], 0, v[112:113]
	v_cvt_pk_bf16_f32 v123, v120, v121
	v_cvt_pk_bf16_f32 v116, v116, v117
	v_cvt_pk_bf16_f32 v117, v114, v115
	v_lshlrev_b64 v[114:115], 6, v[126:127]
	global_store_dwordx2 v[118:119], v[122:123], off
	global_store_dwordx2 v[118:119], v[116:117], off offset:32
	v_lshl_add_u64 v[130:131], s[6:7], 0, v[114:115]
	v_bfe_u32 v244, v130, 6, 8
	v_lshlrev_b32_e32 v244, 3, v244
	v_add_u32_e32 v244, 0x24010, v244
	v_or_b32_e32 v246, 3, v130
	ds_read_b64 v[248:249], v244
	s_waitcnt lgkmcnt(0)
	v_cmp_ne_u32_e64 s[100:101], v248, v246
	s_nop 1
	s_and_saveexec_b64 s[98:99], s[100:101]
	s_cbranch_execz .LrcA1_9
	global_load_dwordx4 v[114:117], v[130:131], off offset:48
	global_load_dwordx4 v[118:121], v[130:131], off offset:32
	global_load_dwordx4 v[122:125], v[130:131], off offset:16
	s_nop 0
	global_load_dwordx4 v[130:133], v[130:131], off
	s_waitcnt vmcnt(2)
	v_add_f32_e32 v118, v118, v119
	v_add_f32_e32 v120, v120, v121
	s_waitcnt vmcnt(0)
	v_mov_b32_e32 v134, v131
	v_mov_b32_e32 v135, v132
	v_mov_b32_e32 v131, v133
	v_mov_b32_e32 v132, v123
	v_mov_b32_e32 v133, v124
	v_mov_b32_e32 v123, v125
	v_pk_add_f32 v[130:131], v[134:135], v[130:131]
	v_pk_add_f32 v[122:123], v[132:133], v[122:123]
	v_pk_add_f32 v[130:131], v[130:131], v[130:131] op_sel:[0,1] op_sel_hi:[1,0]
	v_pk_add_f32 v[122:123], v[122:123], v[122:123] op_sel:[0,1] op_sel_hi:[1,0]
	v_mov_b32_e32 v131, v114
	v_mov_b32_e32 v123, v115
	v_mov_b32_e32 v119, v116
	v_mov_b32_e32 v121, v117
	v_pk_add_f32 v[114:115], v[130:131], v[122:123]
	v_pk_add_f32 v[116:117], v[118:119], v[120:121]
	s_nop 0
	v_pk_add_f32 v[114:115], v[114:115], v[116:117]
	v_add_f32_e32 v113, v114, v115
	v_fmamk_f32 v113, v113, 0x3a800000, v170
	v_cmp_gt_f32_e32 vcc, s43, v113
	v_mul_f32_e32 v114, 0x4b800000, v113
	s_nop 0
	v_cndmask_b32_e32 v113, v113, v114, vcc
	v_rsq_f32_e32 v113, v113
	s_nop 0
	v_mul_f32_e32 v114, 0x45800000, v113
	v_cndmask_b32_e32 v114, v113, v114, vcc
	s_nop 0
	v_mov_b32_e32 v247, v114
	ds_write_b64 v244, v[246:247]

; DI unsigned pk2(float lo, float hi) { f32x2 v = {lo, hi}; return __builtin_bit_cast(unsigned, __builtin_convertvector(v, bfx2)); }
; DI float sigmoidf_(float x) { return 1.f / (1.f + __expf(-x)); }
; DI float rstd_from16(const float* p, float inv_n) {
;   const f32x4 a = *(const f32x4*)p, b = *(const f32x4*)(p + 4), c = *(const f32x4*)(p + 8), d = *(const f32x4*)(p + 12);
;   const float s = ((a[0] + a[1]) + (a[2] + a[3])) + ((b[0] + b[1]) + (b[2] + b[3])) + ((c[0] + c[1]) + (c[2] + c[3])) + ((d[0] + d[1]) + (d[2] + d[3]));
;   return rsqrtf(s * inv_n + EPS_);
; template <bool SWAP> DI void inproj_tile(const Params& p, int layer, int tm, int tn, bf16_t* smem) {
;     ...
;       for (int i = 0; i < 8; ++i) {
;         const int t = trow0 + i * 16 + l15; const float rs = rstd_from16(ssq + (size_t)t * 16, 1.f / 1024.f);
;         float* gt = (float*)(p.ws + O_GATES) + (size_t)t * 24; float* lf = (float*)(p.ws + O_LOGF) + (size_t)t * 8;
; #pragma unroll
;         for (int r = 0; r < 4; ++r) gt[quad * 4 + r] = sigmoidf_(acc[i][0][r] * rs);
;         if (quad < 2) {
; #pragma unroll
;           for (int r = 0; r < 4; ++r) gt[16 + quad * 4 + r] = sigmoidf_(acc[i][1][r] * rs);
;         } else {
; #pragma unroll
;           for (int r = 0; r < 4; ++r) { const int h = (quad - 2) * 4 + r; const float xx = acc[i][1][r] * rs + p.b_forget[layer * 8 + h]; lf[h] = fminf(xx, 0.f) - log1pf(__expf(-fabsf(xx))); }
;         }
;         const float* rp = (const float*)(p.ws + O_ROPE16) + (size_t)t * 32 + quad * 8; float o1[4], o2[4];
; #pragma unroll
;         for (int r = 0; r < 4; ++r) { const float cs = rp[2 * r], sn = rp[2 * r + 1], x1 = acc[i][2][r] * rs, x2 = acc[i][3][r] * rs; o1[r] = x1 * cs - x2 * sn; o2[r] = x2 * cs + x1 * sn; }
;         bf16_t* kp = (bf16_t*)(p.ws + O_MLAKPE) + (size_t)t * 32 + quad * 4;
;         *(u32x2*)kp = (u32x2){pk2(o1[0], o1[1]), pk2(o1[2], o1[3])}; *(u32x2*)(kp + 16) = (u32x2){pk2(o2[0], o2[1]), pk2(o2[2], o2[3])};
;       }
.LBB0_1303:
	s_or_b64 exec, exec, s[2:3]
	s_nop 0
	v_lshlrev_b32_e32 v104, 3, v144
	v_lshl_add_u64 v[106:107], v[116:117], 2, s[10:11]
	v_lshlrev_b32_e32 v104, 2, v104
	v_mov_b32_e32 v105, v161
	v_lshl_add_u64 v[110:111], v[106:107], 0, v[104:105]
	global_load_dwordx4 v[106:109], v[110:111], off offset:16
	global_load_dwordx4 v[118:121], v[110:111], off
	v_pk_mul_f32 v[96:97], v[96:97], v[114:115] op_sel_hi:[1,0]
	v_pk_mul_f32 v[100:101], v[100:101], v[114:115] op_sel_hi:[1,0]
	v_pk_mul_f32 v[98:99], v[98:99], v[114:115] op_sel_hi:[1,0]
	v_readlane_b32 s2, v240, 32
	v_readlane_b32 s3, v240, 33
	v_mov_b32_e32 v113, v161
	s_waitcnt vmcnt(0)
	v_mov_b32_e32 v111, v120
	v_mov_b32_e32 v120, v119
	v_mov_b32_e32 v110, v118
	v_pk_mul_f32 v[118:119], v[96:97], v[120:121]
	s_nop 0
	v_pk_fma_f32 v[118:119], v[100:101], v[110:111], v[118:119] neg_lo:[0,0,1] neg_hi:[0,0,1]
	v_pk_mul_f32 v[100:101], v[100:101], v[120:121]
	s_nop 0
	v_pk_fma_f32 v[96:97], v[96:97], v[110:111], v[100:101]
	v_pk_mul_f32 v[100:101], v[102:103], v[114:115] op_sel_hi:[1,0]
	v_mov_b32_e32 v103, v108
	v_mov_b32_e32 v108, v107
	v_mov_b32_e32 v102, v106
	v_pk_mul_f32 v[106:107], v[98:99], v[108:109]
	v_or_b32_e32 v110, 32, v128
	v_pk_fma_f32 v[106:107], v[100:101], v[102:103], v[106:107] neg_lo:[0,0,1] neg_hi:[0,0,1]
	v_pk_mul_f32 v[100:101], v[100:101], v[108:109]
	v_cvt_pk_bf16_f32 v96, v96, v97
	v_pk_fma_f32 v[98:99], v[98:99], v[102:103], v[100:101]
	v_lshl_add_u64 v[100:101], v[116:117], 1, s[2:3]
	v_lshl_add_u64 v[100:101], v[100:101], 0, v[112:113]
	v_cvt_pk_bf16_f32 v97, v98, v99
	v_ashrrev_i32_e32 v111, 31, v110
	v_cvt_pk_bf16_f32 v102, v118, v119
	v_cvt_pk_bf16_f32 v103, v106, v107
	global_store_dwordx2 v[100:101], v[96:97], off offset:32
	v_lshlrev_b64 v[96:97], 6, v[110:111]
	global_store_dwordx2 v[100:101], v[102:103], off
	v_lshl_add_u64 v[114:115], s[6:7], 0, v[96:97]
	v_bfe_u32 v244, v114, 6, 8
	v_lshlrev_b32_e32 v244, 3, v244
	v_add_u32_e32 v244, 0x24010, v244
	v_or_b32_e32 v246, 3, v114
	ds_read_b64 v[248:249], v244
	s_waitcnt lgkmcnt(0)
	v_cmp_ne_u32_e64 s[100:101], v248, v246
	s_nop 1
	s_and_saveexec_b64 s[98:99], s[100:101]
	s_cbranch_execz .LrcA1_10
	global_load_dwordx4 v[96:99], v[114:115], off offset:48
	global_load_dwordx4 v[100:103], v[114:115], off offset:32
	global_load_dwordx4 v[106:109], v[114:115], off offset:16
	s_nop 0
	global_load_dwordx4 v[114:117], v[114:115], off
	s_waitcnt vmcnt(2)
	v_add_f32_e32 v100, v100, v101
	v_add_f32_e32 v102, v102, v103
	s_waitcnt vmcnt(0)
	v_mov_b32_e32 v118, v115
	v_mov_b32_e32 v119, v116
	v_mov_b32_e32 v115, v117
	v_mov_b32_e32 v116, v107
	v_mov_b32_e32 v117, v108
	v_mov_b32_e32 v107, v109
	v_pk_add_f32 v[114:115], v[118:119], v[114:115]
	v_pk_add_f32 v[106:107], v[116:117], v[106:107]
	v_pk_add_f32 v[114:115], v[114:115], v[114:115] op_sel:[0,1] op_sel_hi:[1,0]
	v_pk_add_f32 v[106:107], v[106:107], v[106:107] op_sel:[0,1] op_sel_hi:[1,0]
	v_mov_b32_e32 v115, v96
	v_mov_b32_e32 v107, v97
	v_mov_b32_e32 v101, v98
	v_mov_b32_e32 v103, v99
	v_pk_add_f32 v[96:97], v[114:115], v[106:107]
	v_pk_add_f32 v[98:99], v[100:101], v[102:103]
	s_nop 0
	v_pk_add_f32 v[96:97], v[96:97], v[98:99]
	v_add_f32_e32 v96, v96, v97
	v_fmamk_f32 v96, v96, 0x3a800000, v170
	v_cmp_gt_f32_e32 vcc, s43, v96
	v_mul_f32_e32 v97, 0x4b800000, v96
	s_nop 0
	v_cndmask_b32_e32 v96, v96, v97, vcc
	v_rsq_f32_e32 v96, v96
	s_nop 0
	v_mul_f32_e32 v97, 0x45800000, v96
	v_cndmask_b32_e32 v96, v96, v97, vcc
	s_nop 0
	v_mov_b32_e32 v247, v96
	ds_write_b64 v244, v[246:247]

; DI unsigned pk2(float lo, float hi) { f32x2 v = {lo, hi}; return __builtin_bit_cast(unsigned, __builtin_convertvector(v, bfx2)); }
; DI float sigmoidf_(float x) { return 1.f / (1.f + __expf(-x)); }
; DI float rstd_from16(const float* p, float inv_n) {
;   const f32x4 a = *(const f32x4*)p, b = *(const f32x4*)(p + 4), c = *(const f32x4*)(p + 8), d = *(const f32x4*)(p + 12);
;   const float s = ((a[0] + a[1]) + (a[2] + a[3])) + ((b[0] + b[1]) + (b[2] + b[3])) + ((c[0] + c[1]) + (c[2] + c[3])) + ((d[0] + d[1]) + (d[2] + d[3]));
;   return rsqrtf(s * inv_n + EPS_);
; template <bool SWAP> DI void inproj_tile(const Params& p, int layer, int tm, int tn, bf16_t* smem) {
;     ...
;       for (int i = 0; i < 8; ++i) {
;         const int t = trow0 + i * 16 + l15; const float rs = rstd_from16(ssq + (size_t)t * 16, 1.f / 1024.f);
;         float* gt = (float*)(p.ws + O_GATES) + (size_t)t * 24; float* lf = (float*)(p.ws + O_LOGF) + (size_t)t * 8;
; #pragma unroll
;         for (int r = 0; r < 4; ++r) gt[quad * 4 + r] = sigmoidf_(acc[i][0][r] * rs);
;         if (quad < 2) {
; #pragma unroll
;           for (int r = 0; r < 4; ++r) gt[16 + quad * 4 + r] = sigmoidf_(acc[i][1][r] * rs);
;         } else {
; #pragma unroll
;           for (int r = 0; r < 4; ++r) { const int h = (quad - 2) * 4 + r; const float xx = acc[i][1][r] * rs + p.b_forget[layer * 8 + h]; lf[h] = fminf(xx, 0.f) - log1pf(__expf(-fabsf(xx))); }
;         }
;         const float* rp = (const float*)(p.ws + O_ROPE16) + (size_t)t * 32 + quad * 8; float o1[4], o2[4];
; #pragma unroll
;         for (int r = 0; r < 4; ++r) { const float cs = rp[2 * r], sn = rp[2 * r + 1], x1 = acc[i][2][r] * rs, x2 = acc[i][3][r] * rs; o1[r] = x1 * cs - x2 * sn; o2[r] = x2 * cs + x1 * sn; }
;         bf16_t* kp = (bf16_t*)(p.ws + O_MLAKPE) + (size_t)t * 32 + quad * 4;
;         *(u32x2*)kp = (u32x2){pk2(o1[0], o1[1]), pk2(o1[2], o1[3])}; *(u32x2*)(kp + 16) = (u32x2){pk2(o2[0], o2[1]), pk2(o2[2], o2[3])};
;       }
.LBB0_1307:
	s_or_b64 exec, exec, s[2:3]
	s_nop 0
	v_lshl_add_u64 v[88:89], v[98:99], 2, s[10:11]
	v_mov_b32_e32 v105, v161
	v_lshl_add_u64 v[92:93], v[88:89], 0, v[104:105]
	global_load_dwordx4 v[88:91], v[92:93], off offset:16
	s_nop 0
	global_load_dwordx4 v[92:95], v[92:93], off
	v_pk_mul_f32 v[80:81], v[80:81], v[96:97] op_sel_hi:[1,0]
	v_pk_mul_f32 v[84:85], v[84:85], v[96:97] op_sel_hi:[1,0]
	v_pk_mul_f32 v[82:83], v[82:83], v[96:97] op_sel_hi:[1,0]
	v_readlane_b32 s2, v240, 32
	v_readlane_b32 s3, v240, 33
	v_mov_b32_e32 v113, v161
	s_waitcnt vmcnt(0)
	v_mov_b32_e32 v101, v94
	v_mov_b32_e32 v94, v93
	v_mov_b32_e32 v100, v92
	v_pk_mul_f32 v[92:93], v[80:81], v[94:95]
	s_nop 0
	v_pk_fma_f32 v[92:93], v[84:85], v[100:101], v[92:93] neg_lo:[0,0,1] neg_hi:[0,0,1]
	v_pk_mul_f32 v[84:85], v[84:85], v[94:95]
	s_nop 0
	v_pk_fma_f32 v[80:81], v[80:81], v[100:101], v[84:85]
	v_pk_mul_f32 v[84:85], v[86:87], v[96:97] op_sel_hi:[1,0]
	v_mov_b32_e32 v87, v90
	v_mov_b32_e32 v90, v89
	v_mov_b32_e32 v86, v88
	v_pk_mul_f32 v[88:89], v[82:83], v[90:91]
	v_or_b32_e32 v96, 48, v128
	v_pk_fma_f32 v[88:89], v[84:85], v[86:87], v[88:89] neg_lo:[0,0,1] neg_hi:[0,0,1]
	v_pk_mul_f32 v[84:85], v[84:85], v[90:91]
	v_cvt_pk_bf16_f32 v80, v80, v81
	v_pk_fma_f32 v[82:83], v[82:83], v[86:87], v[84:85]
	v_lshl_add_u64 v[84:85], v[98:99], 1, s[2:3]
	v_lshl_add_u64 v[84:85], v[84:85], 0, v[112:113]
	v_cvt_pk_bf16_f32 v81, v82, v83
	v_ashrrev_i32_e32 v97, 31, v96
	v_cvt_pk_bf16_f32 v86, v92, v93
	v_cvt_pk_bf16_f32 v87, v88, v89
	global_store_dwordx2 v[84:85], v[80:81], off offset:32
	v_lshlrev_b64 v[80:81], 6, v[96:97]
	global_store_dwordx2 v[84:85], v[86:87], off
	v_lshl_add_u64 v[92:93], s[6:7], 0, v[80:81]
	v_bfe_u32 v244, v92, 6, 8
	v_lshlrev_b32_e32 v244, 3, v244
	v_add_u32_e32 v244, 0x24010, v244
	v_or_b32_e32 v246, 3, v92
	ds_read_b64 v[248:249], v244
	s_waitcnt lgkmcnt(0)
	v_cmp_ne_u32_e64 s[100:101], v248, v246
	s_nop 1
	s_and_saveexec_b64 s[98:99], s[100:101]
	s_cbranch_execz .LrcA1_11
	global_load_dwordx4 v[80:83], v[92:93], off offset:48
	global_load_dwordx4 v[84:87], v[92:93], off offset:32
	global_load_dwordx4 v[88:91], v[92:93], off offset:16
	s_nop 0
	global_load_dwordx4 v[92:95], v[92:93], off
	s_waitcnt vmcnt(2)
	v_add_f32_e32 v84, v84, v85
	v_add_f32_e32 v86, v86, v87
	s_waitcnt vmcnt(0)
	v_mov_b32_e32 v98, v93
	v_mov_b32_e32 v99, v94
	v_mov_b32_e32 v93, v95
	v_mov_b32_e32 v94, v89
	v_mov_b32_e32 v95, v90
	v_mov_b32_e32 v89, v91
	v_pk_add_f32 v[92:93], v[98:99], v[92:93]
	v_pk_add_f32 v[88:89], v[94:95], v[88:89]
	v_pk_add_f32 v[92:93], v[92:93], v[92:93] op_sel:[0,1] op_sel_hi:[1,0]
	v_pk_add_f32 v[88:89], v[88:89], v[88:89] op_sel:[0,1] op_sel_hi:[1,0]
	v_mov_b32_e32 v93, v80
	v_mov_b32_e32 v89, v81
	v_mov_b32_e32 v85, v82
	v_mov_b32_e32 v87, v83
	v_pk_add_f32 v[80:81], v[92:93], v[88:89]
	v_pk_add_f32 v[82:83], v[84:85], v[86:87]
	s_nop 0
	v_pk_add_f32 v[80:81], v[80:81], v[82:83]
	v_add_f32_e32 v80, v80, v81
	v_fmamk_f32 v80, v80, 0x3a800000, v170
	v_cmp_gt_f32_e32 vcc, s43, v80
	v_mul_f32_e32 v81, 0x4b800000, v80
	s_nop 0
	v_cndmask_b32_e32 v80, v80, v81, vcc
	v_rsq_f32_e32 v80, v80
	s_nop 0
	v_mul_f32_e32 v81, 0x45800000, v80
	v_cndmask_b32_e32 v80, v80, v81, vcc
	s_nop 0
	v_mov_b32_e32 v247, v80
	ds_write_b64 v244, v[246:247]

; DI unsigned pk2(float lo, float hi) { f32x2 v = {lo, hi}; return __builtin_bit_cast(unsigned, __builtin_convertvector(v, bfx2)); }
; DI float sigmoidf_(float x) { return 1.f / (1.f + __expf(-x)); }
; DI float rstd_from16(const float* p, float inv_n) {
;   const f32x4 a = *(const f32x4*)p, b = *(const f32x4*)(p + 4), c = *(const f32x4*)(p + 8), d = *(const f32x4*)(p + 12);
;   const float s = ((a[0] + a[1]) + (a[2] + a[3])) + ((b[0] + b[1]) + (b[2] + b[3])) + ((c[0] + c[1]) + (c[2] + c[3])) + ((d[0] + d[1]) + (d[2] + d[3]));
;   return rsqrtf(s * inv_n + EPS_);
; template <bool SWAP> DI void inproj_tile(const Params& p, int layer, int tm, int tn, bf16_t* smem) {
;     ...
;       for (int i = 0; i < 8; ++i) {
;         const int t = trow0 + i * 16 + l15; const float rs = rstd_from16(ssq + (size_t)t * 16, 1.f / 1024.f);
;         float* gt = (float*)(p.ws + O_GATES) + (size_t)t * 24; float* lf = (float*)(p.ws + O_LOGF) + (size_t)t * 8;
; #pragma unroll
;         for (int r = 0; r < 4; ++r) gt[quad * 4 + r] = sigmoidf_(acc[i][0][r] * rs);
;         if (quad < 2) {
; #pragma unroll
;           for (int r = 0; r < 4; ++r) gt[16 + quad * 4 + r] = sigmoidf_(acc[i][1][r] * rs);
;         } else {
; #pragma unroll
;           for (int r = 0; r < 4; ++r) { const int h = (quad - 2) * 4 + r; const float xx = acc[i][1][r] * rs + p.b_forget[layer * 8 + h]; lf[h] = fminf(xx, 0.f) - log1pf(__expf(-fabsf(xx))); }
;         }
;         const float* rp = (const float*)(p.ws + O_ROPE16) + (size_t)t * 32 + quad * 8; float o1[4], o2[4];
; #pragma unroll
;         for (int r = 0; r < 4; ++r) { const float cs = rp[2 * r], sn = rp[2 * r + 1], x1 = acc[i][2][r] * rs, x2 = acc[i][3][r] * rs; o1[r] = x1 * cs - x2 * sn; o2[r] = x2 * cs + x1 * sn; }
;         bf16_t* kp = (bf16_t*)(p.ws + O_MLAKPE) + (size_t)t * 32 + quad * 4;
;         *(u32x2*)kp = (u32x2){pk2(o1[0], o1[1]), pk2(o1[2], o1[3])}; *(u32x2*)(kp + 16) = (u32x2){pk2(o2[0], o2[1]), pk2(o2[2], o2[3])};
;       }
.LBB0_1311:
	s_or_b64 exec, exec, s[2:3]
	s_nop 0
	v_lshl_add_u64 v[72:73], v[82:83], 2, s[10:11]
	v_mov_b32_e32 v105, v161
	v_lshl_add_u64 v[76:77], v[72:73], 0, v[104:105]
	global_load_dwordx4 v[72:75], v[76:77], off offset:16
	s_nop 0
	global_load_dwordx4 v[76:79], v[76:77], off
	v_pk_mul_f32 v[64:65], v[64:65], v[80:81] op_sel_hi:[1,0]
	v_pk_mul_f32 v[68:69], v[68:69], v[80:81] op_sel_hi:[1,0]
	v_pk_mul_f32 v[66:67], v[66:67], v[80:81] op_sel_hi:[1,0]
	v_readlane_b32 s2, v240, 32
	v_readlane_b32 s3, v240, 33
	v_mov_b32_e32 v113, v161
	s_waitcnt vmcnt(0)
	v_mov_b32_e32 v85, v78
	v_mov_b32_e32 v78, v77
	v_mov_b32_e32 v84, v76
	v_pk_mul_f32 v[76:77], v[64:65], v[78:79]
	s_nop 0
	v_pk_fma_f32 v[76:77], v[68:69], v[84:85], v[76:77] neg_lo:[0,0,1] neg_hi:[0,0,1]
	v_pk_mul_f32 v[68:69], v[68:69], v[78:79]
	s_nop 0
	v_pk_fma_f32 v[64:65], v[64:65], v[84:85], v[68:69]
	v_pk_mul_f32 v[68:69], v[70:71], v[80:81] op_sel_hi:[1,0]
	v_mov_b32_e32 v71, v74
	v_mov_b32_e32 v74, v73
	v_mov_b32_e32 v70, v72
	v_pk_mul_f32 v[72:73], v[66:67], v[74:75]
	v_or_b32_e32 v80, 64, v128
	v_pk_fma_f32 v[72:73], v[68:69], v[70:71], v[72:73] neg_lo:[0,0,1] neg_hi:[0,0,1]
	v_pk_mul_f32 v[68:69], v[68:69], v[74:75]
	v_cvt_pk_bf16_f32 v64, v64, v65
	v_pk_fma_f32 v[66:67], v[66:67], v[70:71], v[68:69]
	v_lshl_add_u64 v[68:69], v[82:83], 1, s[2:3]
	v_lshl_add_u64 v[68:69], v[68:69], 0, v[112:113]
	v_cvt_pk_bf16_f32 v65, v66, v67
	v_ashrrev_i32_e32 v81, 31, v80
	v_cvt_pk_bf16_f32 v70, v76, v77
	v_cvt_pk_bf16_f32 v71, v72, v73
	global_store_dwordx2 v[68:69], v[64:65], off offset:32
	v_lshlrev_b64 v[64:65], 6, v[80:81]
	global_store_dwordx2 v[68:69], v[70:71], off
	v_lshl_add_u64 v[76:77], s[6:7], 0, v[64:65]
	v_bfe_u32 v244, v76, 6, 8
	v_lshlrev_b32_e32 v244, 3, v244
	v_add_u32_e32 v244, 0x24010, v244
	v_or_b32_e32 v246, 3, v76
	ds_read_b64 v[248:249], v244
	s_waitcnt lgkmcnt(0)
	v_cmp_ne_u32_e64 s[100:101], v248, v246
	s_nop 1
	s_and_saveexec_b64 s[98:99], s[100:101]
	s_cbranch_execz .LrcA1_12
	global_load_dwordx4 v[64:67], v[76:77], off offset:48
	global_load_dwordx4 v[68:71], v[76:77], off offset:32
	global_load_dwordx4 v[72:75], v[76:77], off offset:16
	s_nop 0
	global_load_dwordx4 v[76:79], v[76:77], off
	s_waitcnt vmcnt(2)
	v_add_f32_e32 v68, v68, v69
	v_add_f32_e32 v70, v70, v71
	s_waitcnt vmcnt(0)
	v_mov_b32_e32 v82, v77
	v_mov_b32_e32 v83, v78
	v_mov_b32_e32 v77, v79
	v_mov_b32_e32 v78, v73
	v_mov_b32_e32 v79, v74
	v_mov_b32_e32 v73, v75
	v_pk_add_f32 v[76:77], v[82:83], v[76:77]
	v_pk_add_f32 v[72:73], v[78:79], v[72:73]
	v_pk_add_f32 v[76:77], v[76:77], v[76:77] op_sel:[0,1] op_sel_hi:[1,0]
	v_pk_add_f32 v[72:73], v[72:73], v[72:73] op_sel:[0,1] op_sel_hi:[1,0]
	v_mov_b32_e32 v77, v64
	v_mov_b32_e32 v73, v65
	v_mov_b32_e32 v69, v66
	v_mov_b32_e32 v71, v67
	v_pk_add_f32 v[64:65], v[76:77], v[72:73]
	v_pk_add_f32 v[66:67], v[68:69], v[70:71]
	s_nop 0
	v_pk_add_f32 v[64:65], v[64:65], v[66:67]
	v_add_f32_e32 v64, v64, v65
	v_fmamk_f32 v64, v64, 0x3a800000, v170
	v_cmp_gt_f32_e32 vcc, s43, v64
	v_mul_f32_e32 v65, 0x4b800000, v64
	s_nop 0
	v_cndmask_b32_e32 v64, v64, v65, vcc
	v_rsq_f32_e32 v64, v64
	s_nop 0
	v_mul_f32_e32 v65, 0x45800000, v64
	v_cndmask_b32_e32 v64, v64, v65, vcc
	s_nop 0
	v_mov_b32_e32 v247, v64
	ds_write_b64 v244, v[246:247]

; DI unsigned pk2(float lo, float hi) { f32x2 v = {lo, hi}; return __builtin_bit_cast(unsigned, __builtin_convertvector(v, bfx2)); }
; DI float sigmoidf_(float x) { return 1.f / (1.f + __expf(-x)); }
; DI float rstd_from16(const float* p, float inv_n) {
;   const f32x4 a = *(const f32x4*)p, b = *(const f32x4*)(p + 4), c = *(const f32x4*)(p + 8), d = *(const f32x4*)(p + 12);
;   const float s = ((a[0] + a[1]) + (a[2] + a[3])) + ((b[0] + b[1]) + (b[2] + b[3])) + ((c[0] + c[1]) + (c[2] + c[3])) + ((d[0] + d[1]) + (d[2] + d[3]));
;   return rsqrtf(s * inv_n + EPS_);
; template <bool SWAP> DI void inproj_tile(const Params& p, int layer, int tm, int tn, bf16_t* smem) {
;     ...
;       for (int i = 0; i < 8; ++i) {
;         const int t = trow0 + i * 16 + l15; const float rs = rstd_from16(ssq + (size_t)t * 16, 1.f / 1024.f);
;         float* gt = (float*)(p.ws + O_GATES) + (size_t)t * 24; float* lf = (float*)(p.ws + O_LOGF) + (size_t)t * 8;
; #pragma unroll
;         for (int r = 0; r < 4; ++r) gt[quad * 4 + r] = sigmoidf_(acc[i][0][r] * rs);
;         if (quad < 2) {
; #pragma unroll
;           for (int r = 0; r < 4; ++r) gt[16 + quad * 4 + r] = sigmoidf_(acc[i][1][r] * rs);
;         } else {
; #pragma unroll
;           for (int r = 0; r < 4; ++r) { const int h = (quad - 2) * 4 + r; const float xx = acc[i][1][r] * rs + p.b_forget[layer * 8 + h]; lf[h] = fminf(xx, 0.f) - log1pf(__expf(-fabsf(xx))); }
;         }
;         const float* rp = (const float*)(p.ws + O_ROPE16) + (size_t)t * 32 + quad * 8; float o1[4], o2[4];
; #pragma unroll
;         for (int r = 0; r < 4; ++r) { const float cs = rp[2 * r], sn = rp[2 * r + 1], x1 = acc[i][2][r] * rs, x2 = acc[i][3][r] * rs; o1[r] = x1 * cs - x2 * sn; o2[r] = x2 * cs + x1 * sn; }
;         bf16_t* kp = (bf16_t*)(p.ws + O_MLAKPE) + (size_t)t * 32 + quad * 4;
;         *(u32x2*)kp = (u32x2){pk2(o1[0], o1[1]), pk2(o1[2], o1[3])}; *(u32x2*)(kp + 16) = (u32x2){pk2(o2[0], o2[1]), pk2(o2[2], o2[3])};
;       }
.LBB0_1315:
	s_or_b64 exec, exec, s[2:3]
	s_nop 0
	v_lshl_add_u64 v[56:57], v[66:67], 2, s[10:11]
	v_mov_b32_e32 v105, v161
	v_lshl_add_u64 v[60:61], v[56:57], 0, v[104:105]
	global_load_dwordx4 v[56:59], v[60:61], off offset:16
	s_nop 0
	global_load_dwordx4 v[60:63], v[60:61], off
	v_pk_mul_f32 v[48:49], v[48:49], v[64:65] op_sel_hi:[1,0]
	v_pk_mul_f32 v[52:53], v[52:53], v[64:65] op_sel_hi:[1,0]
	v_pk_mul_f32 v[50:51], v[50:51], v[64:65] op_sel_hi:[1,0]
	v_readlane_b32 s2, v240, 32
	v_readlane_b32 s3, v240, 33
	v_mov_b32_e32 v113, v161
	s_waitcnt vmcnt(0)
	v_mov_b32_e32 v69, v62
	v_mov_b32_e32 v62, v61
	v_mov_b32_e32 v68, v60
	v_pk_mul_f32 v[60:61], v[48:49], v[62:63]
	s_nop 0
	v_pk_fma_f32 v[60:61], v[52:53], v[68:69], v[60:61] neg_lo:[0,0,1] neg_hi:[0,0,1]
	v_pk_mul_f32 v[52:53], v[52:53], v[62:63]
	s_nop 0
	v_pk_fma_f32 v[48:49], v[48:49], v[68:69], v[52:53]
	v_pk_mul_f32 v[52:53], v[54:55], v[64:65] op_sel_hi:[1,0]
	v_mov_b32_e32 v55, v58
	v_mov_b32_e32 v58, v57
	v_mov_b32_e32 v54, v56
	v_pk_mul_f32 v[56:57], v[50:51], v[58:59]
	v_or_b32_e32 v64, 0x50, v128
	v_pk_fma_f32 v[56:57], v[52:53], v[54:55], v[56:57] neg_lo:[0,0,1] neg_hi:[0,0,1]
	v_pk_mul_f32 v[52:53], v[52:53], v[58:59]
	v_cvt_pk_bf16_f32 v48, v48, v49
	v_pk_fma_f32 v[50:51], v[50:51], v[54:55], v[52:53]
	v_lshl_add_u64 v[52:53], v[66:67], 1, s[2:3]
	v_lshl_add_u64 v[52:53], v[52:53], 0, v[112:113]
	v_cvt_pk_bf16_f32 v49, v50, v51
	v_ashrrev_i32_e32 v65, 31, v64
	v_cvt_pk_bf16_f32 v54, v60, v61
	v_cvt_pk_bf16_f32 v55, v56, v57
	global_store_dwordx2 v[52:53], v[48:49], off offset:32
	v_lshlrev_b64 v[48:49], 6, v[64:65]
	global_store_dwordx2 v[52:53], v[54:55], off
	v_lshl_add_u64 v[60:61], s[6:7], 0, v[48:49]
	v_bfe_u32 v244, v60, 6, 8
	v_lshlrev_b32_e32 v244, 3, v244
	v_add_u32_e32 v244, 0x24010, v244
	v_or_b32_e32 v246, 3, v60
	ds_read_b64 v[248:249], v244
	s_waitcnt lgkmcnt(0)
	v_cmp_ne_u32_e64 s[100:101], v248, v246
	s_nop 1
	s_and_saveexec_b64 s[98:99], s[100:101]
	s_cbranch_execz .LrcA1_13
	global_load_dwordx4 v[48:51], v[60:61], off offset:48
	global_load_dwordx4 v[52:55], v[60:61], off offset:32
	global_load_dwordx4 v[56:59], v[60:61], off offset:16
	s_nop 0
	global_load_dwordx4 v[60:63], v[60:61], off
	s_waitcnt vmcnt(2)
	v_add_f32_e32 v52, v52, v53
	v_add_f32_e32 v54, v54, v55
	s_waitcnt vmcnt(0)
	v_mov_b32_e32 v66, v61
	v_mov_b32_e32 v67, v62
	v_mov_b32_e32 v61, v63
	v_mov_b32_e32 v62, v57
	v_mov_b32_e32 v63, v58
	v_mov_b32_e32 v57, v59
	v_pk_add_f32 v[60:61], v[66:67], v[60:61]
	v_pk_add_f32 v[56:57], v[62:63], v[56:57]
	v_pk_add_f32 v[60:61], v[60:61], v[60:61] op_sel:[0,1] op_sel_hi:[1,0]
	v_pk_add_f32 v[56:57], v[56:57], v[56:57] op_sel:[0,1] op_sel_hi:[1,0]
	v_mov_b32_e32 v61, v48
	v_mov_b32_e32 v57, v49
	v_mov_b32_e32 v53, v50
	v_mov_b32_e32 v55, v51
	v_pk_add_f32 v[48:49], v[60:61], v[56:57]
	v_pk_add_f32 v[50:51], v[52:53], v[54:55]
	s_nop 0
	v_pk_add_f32 v[48:49], v[48:49], v[50:51]
	v_add_f32_e32 v48, v48, v49
	v_fmamk_f32 v48, v48, 0x3a800000, v170
	v_cmp_gt_f32_e32 vcc, s43, v48
	v_mul_f32_e32 v49, 0x4b800000, v48
	s_nop 0
	v_cndmask_b32_e32 v48, v48, v49, vcc
	v_rsq_f32_e32 v48, v48
	s_nop 0
	v_mul_f32_e32 v49, 0x45800000, v48
	v_cndmask_b32_e32 v48, v48, v49, vcc
	s_nop 0
	v_mov_b32_e32 v247, v48
	ds_write_b64 v244, v[246:247]

; DI unsigned pk2(float lo, float hi) { f32x2 v = {lo, hi}; return __builtin_bit_cast(unsigned, __builtin_convertvector(v, bfx2)); }
; DI float sigmoidf_(float x) { return 1.f / (1.f + __expf(-x)); }
; DI float rstd_from16(const float* p, float inv_n) {
;   const f32x4 a = *(const f32x4*)p, b = *(const f32x4*)(p + 4), c = *(const f32x4*)(p + 8), d = *(const f32x4*)(p + 12);
;   const float s = ((a[0] + a[1]) + (a[2] + a[3])) + ((b[0] + b[1]) + (b[2] + b[3])) + ((c[0] + c[1]) + (c[2] + c[3])) + ((d[0] + d[1]) + (d[2] + d[3]));
;   return rsqrtf(s * inv_n + EPS_);
; template <bool SWAP> DI void inproj_tile(const Params& p, int layer, int tm, int tn, bf16_t* smem) {
;     ...
;       for (int i = 0; i < 8; ++i) {
;         const int t = trow0 + i * 16 + l15; const float rs = rstd_from16(ssq + (size_t)t * 16, 1.f / 1024.f);
;         float* gt = (float*)(p.ws + O_GATES) + (size_t)t * 24; float* lf = (float*)(p.ws + O_LOGF) + (size_t)t * 8;
; #pragma unroll
;         for (int r = 0; r < 4; ++r) gt[quad * 4 + r] = sigmoidf_(acc[i][0][r] * rs);
;         if (quad < 2) {
; #pragma unroll
;           for (int r = 0; r < 4; ++r) gt[16 + quad * 4 + r] = sigmoidf_(acc[i][1][r] * rs);
;         } else {
; #pragma unroll
;           for (int r = 0; r < 4; ++r) { const int h = (quad - 2) * 4 + r; const float xx = acc[i][1][r] * rs + p.b_forget[layer * 8 + h]; lf[h] = fminf(xx, 0.f) - log1pf(__expf(-fabsf(xx))); }
;         }
;         const float* rp = (const float*)(p.ws + O_ROPE16) + (size_t)t * 32 + quad * 8; float o1[4], o2[4];
; #pragma unroll
;         for (int r = 0; r < 4; ++r) { const float cs = rp[2 * r], sn = rp[2 * r + 1], x1 = acc[i][2][r] * rs, x2 = acc[i][3][r] * rs; o1[r] = x1 * cs - x2 * sn; o2[r] = x2 * cs + x1 * sn; }
;         bf16_t* kp = (bf16_t*)(p.ws + O_MLAKPE) + (size_t)t * 32 + quad * 4;
;         *(u32x2*)kp = (u32x2){pk2(o1[0], o1[1]), pk2(o1[2], o1[3])}; *(u32x2*)(kp + 16) = (u32x2){pk2(o2[0], o2[1]), pk2(o2[2], o2[3])};
;       }
.LBB0_1319:
	s_or_b64 exec, exec, s[2:3]
	s_nop 0
	v_lshl_add_u64 v[40:41], v[50:51], 2, s[10:11]
	v_mov_b32_e32 v105, v161
	v_lshl_add_u64 v[44:45], v[40:41], 0, v[104:105]
	global_load_dwordx4 v[40:43], v[44:45], off offset:16
	s_nop 0
	global_load_dwordx4 v[44:47], v[44:45], off
	v_pk_mul_f32 v[32:33], v[32:33], v[48:49] op_sel_hi:[1,0]
	v_pk_mul_f32 v[36:37], v[36:37], v[48:49] op_sel_hi:[1,0]
	v_pk_mul_f32 v[34:35], v[34:35], v[48:49] op_sel_hi:[1,0]
	v_readlane_b32 s2, v240, 32
	v_readlane_b32 s3, v240, 33
	v_mov_b32_e32 v113, v161
	s_waitcnt vmcnt(0)
	v_mov_b32_e32 v53, v46
	v_mov_b32_e32 v46, v45
	v_mov_b32_e32 v52, v44
	v_pk_mul_f32 v[44:45], v[32:33], v[46:47]
	s_nop 0
	v_pk_fma_f32 v[44:45], v[36:37], v[52:53], v[44:45] neg_lo:[0,0,1] neg_hi:[0,0,1]
	v_pk_mul_f32 v[36:37], v[36:37], v[46:47]
	s_nop 0
	v_pk_fma_f32 v[32:33], v[32:33], v[52:53], v[36:37]
	v_pk_mul_f32 v[36:37], v[38:39], v[48:49] op_sel_hi:[1,0]
	v_mov_b32_e32 v39, v42
	v_mov_b32_e32 v42, v41
	v_mov_b32_e32 v38, v40
	v_pk_mul_f32 v[40:41], v[34:35], v[42:43]
	v_or_b32_e32 v48, 0x60, v128
	v_pk_fma_f32 v[40:41], v[36:37], v[38:39], v[40:41] neg_lo:[0,0,1] neg_hi:[0,0,1]
	v_pk_mul_f32 v[36:37], v[36:37], v[42:43]
	v_cvt_pk_bf16_f32 v32, v32, v33
	v_pk_fma_f32 v[34:35], v[34:35], v[38:39], v[36:37]
	v_lshl_add_u64 v[36:37], v[50:51], 1, s[2:3]
	v_lshl_add_u64 v[36:37], v[36:37], 0, v[112:113]
	v_cvt_pk_bf16_f32 v33, v34, v35
	v_ashrrev_i32_e32 v49, 31, v48
	v_cvt_pk_bf16_f32 v38, v44, v45
	v_cvt_pk_bf16_f32 v39, v40, v41
	global_store_dwordx2 v[36:37], v[32:33], off offset:32
	v_lshlrev_b64 v[32:33], 6, v[48:49]
	global_store_dwordx2 v[36:37], v[38:39], off
	v_lshl_add_u64 v[44:45], s[6:7], 0, v[32:33]
	v_bfe_u32 v244, v44, 6, 8
	v_lshlrev_b32_e32 v244, 3, v244
	v_add_u32_e32 v244, 0x24010, v244
	v_or_b32_e32 v246, 3, v44
	ds_read_b64 v[248:249], v244
	s_waitcnt lgkmcnt(0)
	v_cmp_ne_u32_e64 s[100:101], v248, v246
	s_nop 1
	s_and_saveexec_b64 s[98:99], s[100:101]
	s_cbranch_execz .LrcA1_14
	global_load_dwordx4 v[32:35], v[44:45], off offset:48
	global_load_dwordx4 v[36:39], v[44:45], off offset:32
	global_load_dwordx4 v[40:43], v[44:45], off offset:16
	s_nop 0
	global_load_dwordx4 v[44:47], v[44:45], off
	s_waitcnt vmcnt(2)
	v_add_f32_e32 v36, v36, v37
	v_add_f32_e32 v38, v38, v39
	s_waitcnt vmcnt(0)
	v_mov_b32_e32 v50, v45
	v_mov_b32_e32 v51, v46
	v_mov_b32_e32 v45, v47
	v_mov_b32_e32 v46, v41
	v_mov_b32_e32 v47, v42
	v_mov_b32_e32 v41, v43
	v_pk_add_f32 v[44:45], v[50:51], v[44:45]
	v_pk_add_f32 v[40:41], v[46:47], v[40:41]
	v_pk_add_f32 v[44:45], v[44:45], v[44:45] op_sel:[0,1] op_sel_hi:[1,0]
	v_pk_add_f32 v[40:41], v[40:41], v[40:41] op_sel:[0,1] op_sel_hi:[1,0]
	v_mov_b32_e32 v45, v32
	v_mov_b32_e32 v41, v33
	v_mov_b32_e32 v37, v34
	v_mov_b32_e32 v39, v35
	v_pk_add_f32 v[32:33], v[44:45], v[40:41]
	v_pk_add_f32 v[34:35], v[36:37], v[38:39]
	s_nop 0
	v_pk_add_f32 v[32:33], v[32:33], v[34:35]
	v_add_f32_e32 v32, v32, v33
	v_fmamk_f32 v32, v32, 0x3a800000, v170
	v_cmp_gt_f32_e32 vcc, s43, v32
	v_mul_f32_e32 v33, 0x4b800000, v32
	s_nop 0
	v_cndmask_b32_e32 v32, v32, v33, vcc
	v_rsq_f32_e32 v32, v32
	s_nop 0
	v_mul_f32_e32 v33, 0x45800000, v32
	v_cndmask_b32_e32 v32, v32, v33, vcc
	s_nop 0
	v_mov_b32_e32 v247, v32
	ds_write_b64 v244, v[246:247]

; DI unsigned pk2(float lo, float hi) { f32x2 v = {lo, hi}; return __builtin_bit_cast(unsigned, __builtin_convertvector(v, bfx2)); }
; DI float sigmoidf_(float x) { return 1.f / (1.f + __expf(-x)); }
; DI float rstd_from16(const float* p, float inv_n) {
;   const f32x4 a = *(const f32x4*)p, b = *(const f32x4*)(p + 4), c = *(const f32x4*)(p + 8), d = *(const f32x4*)(p + 12);
;   const float s = ((a[0] + a[1]) + (a[2] + a[3])) + ((b[0] + b[1]) + (b[2] + b[3])) + ((c[0] + c[1]) + (c[2] + c[3])) + ((d[0] + d[1]) + (d[2] + d[3]));
;   return rsqrtf(s * inv_n + EPS_);
; template <bool SWAP> DI void inproj_tile(const Params& p, int layer, int tm, int tn, bf16_t* smem) {
;     ...
;       for (int i = 0; i < 8; ++i) {
;         const int t = trow0 + i * 16 + l15; const float rs = rstd_from16(ssq + (size_t)t * 16, 1.f / 1024.f);
;         float* gt = (float*)(p.ws + O_GATES) + (size_t)t * 24; float* lf = (float*)(p.ws + O_LOGF) + (size_t)t * 8;
; #pragma unroll
;         for (int r = 0; r < 4; ++r) gt[quad * 4 + r] = sigmoidf_(acc[i][0][r] * rs);
;         if (quad < 2) {
; #pragma unroll
;           for (int r = 0; r < 4; ++r) gt[16 + quad * 4 + r] = sigmoidf_(acc[i][1][r] * rs);
;         } else {
; #pragma unroll
;           for (int r = 0; r < 4; ++r) { const int h = (quad - 2) * 4 + r; const float xx = acc[i][1][r] * rs + p.b_forget[layer * 8 + h]; lf[h] = fminf(xx, 0.f) - log1pf(__expf(-fabsf(xx))); }
;         }
;         const float* rp = (const float*)(p.ws + O_ROPE16) + (size_t)t * 32 + quad * 8; float o1[4], o2[4];
; #pragma unroll
;         for (int r = 0; r < 4; ++r) { const float cs = rp[2 * r], sn = rp[2 * r + 1], x1 = acc[i][2][r] * rs, x2 = acc[i][3][r] * rs; o1[r] = x1 * cs - x2 * sn; o2[r] = x2 * cs + x1 * sn; }
;         bf16_t* kp = (bf16_t*)(p.ws + O_MLAKPE) + (size_t)t * 32 + quad * 4;
;         *(u32x2*)kp = (u32x2){pk2(o1[0], o1[1]), pk2(o1[2], o1[3])}; *(u32x2*)(kp + 16) = (u32x2){pk2(o2[0], o2[1]), pk2(o2[2], o2[3])};
;       }
.LBB0_1323:
	s_or_b64 exec, exec, s[2:3]
	s_nop 0
	v_lshl_add_u64 v[24:25], v[34:35], 2, s[10:11]
	v_mov_b32_e32 v105, v161
	v_lshl_add_u64 v[28:29], v[24:25], 0, v[104:105]
	global_load_dwordx4 v[24:27], v[28:29], off offset:16
	s_nop 0
	global_load_dwordx4 v[28:31], v[28:29], off
	v_pk_mul_f32 v[16:17], v[16:17], v[32:33] op_sel_hi:[1,0]
	v_pk_mul_f32 v[20:21], v[20:21], v[32:33] op_sel_hi:[1,0]
	v_pk_mul_f32 v[18:19], v[18:19], v[32:33] op_sel_hi:[1,0]
	v_readlane_b32 s2, v240, 32
	v_readlane_b32 s3, v240, 33
	v_mov_b32_e32 v113, v161
	s_waitcnt vmcnt(0)
	v_mov_b32_e32 v37, v30
	v_mov_b32_e32 v30, v29
	v_mov_b32_e32 v36, v28
	v_pk_mul_f32 v[28:29], v[16:17], v[30:31]
	s_nop 0
	v_pk_fma_f32 v[28:29], v[20:21], v[36:37], v[28:29] neg_lo:[0,0,1] neg_hi:[0,0,1]
	v_pk_mul_f32 v[20:21], v[20:21], v[30:31]
	s_nop 0
	v_pk_fma_f32 v[16:17], v[16:17], v[36:37], v[20:21]
	v_pk_mul_f32 v[20:21], v[22:23], v[32:33] op_sel_hi:[1,0]
	v_mov_b32_e32 v23, v26
	v_mov_b32_e32 v26, v25
	v_mov_b32_e32 v22, v24
	v_pk_mul_f32 v[24:25], v[18:19], v[26:27]
	v_or_b32_e32 v32, 0x70, v128
	v_pk_fma_f32 v[24:25], v[20:21], v[22:23], v[24:25] neg_lo:[0,0,1] neg_hi:[0,0,1]
	v_pk_mul_f32 v[20:21], v[20:21], v[26:27]
	v_cvt_pk_bf16_f32 v16, v16, v17
	v_pk_fma_f32 v[18:19], v[18:19], v[22:23], v[20:21]
	v_lshl_add_u64 v[20:21], v[34:35], 1, s[2:3]
	v_lshl_add_u64 v[20:21], v[20:21], 0, v[112:113]
	v_cvt_pk_bf16_f32 v17, v18, v19
	v_ashrrev_i32_e32 v33, 31, v32
	v_cvt_pk_bf16_f32 v22, v28, v29
	v_cvt_pk_bf16_f32 v23, v24, v25
	global_store_dwordx2 v[20:21], v[16:17], off offset:32
	v_lshlrev_b64 v[16:17], 6, v[32:33]
	global_store_dwordx2 v[20:21], v[22:23], off
	v_lshl_add_u64 v[28:29], s[6:7], 0, v[16:17]
	v_bfe_u32 v244, v28, 6, 8
	v_lshlrev_b32_e32 v244, 3, v244
	v_add_u32_e32 v244, 0x24010, v244
	v_or_b32_e32 v246, 3, v28
	ds_read_b64 v[248:249], v244
	s_waitcnt lgkmcnt(0)
	v_cmp_ne_u32_e64 s[100:101], v248, v246
	s_nop 1
	s_and_saveexec_b64 s[98:99], s[100:101]
	s_cbranch_execz .LrcA1_15
	global_load_dwordx4 v[16:19], v[28:29], off offset:48
	global_load_dwordx4 v[20:23], v[28:29], off offset:32
	global_load_dwordx4 v[24:27], v[28:29], off offset:16
	s_nop 0
	global_load_dwordx4 v[28:31], v[28:29], off
	s_waitcnt vmcnt(2)
	v_add_f32_e32 v20, v20, v21
	v_add_f32_e32 v22, v22, v23
	s_waitcnt vmcnt(0)
	v_mov_b32_e32 v34, v29
	v_mov_b32_e32 v35, v30
	v_mov_b32_e32 v29, v31
	v_mov_b32_e32 v30, v25
	v_mov_b32_e32 v31, v26
	v_mov_b32_e32 v25, v27
	v_pk_add_f32 v[28:29], v[34:35], v[28:29]
	v_pk_add_f32 v[24:25], v[30:31], v[24:25]
	v_pk_add_f32 v[28:29], v[28:29], v[28:29] op_sel:[0,1] op_sel_hi:[1,0]
	v_pk_add_f32 v[24:25], v[24:25], v[24:25] op_sel:[0,1] op_sel_hi:[1,0]
	v_mov_b32_e32 v29, v16
	v_mov_b32_e32 v25, v17
	v_mov_b32_e32 v21, v18
	v_mov_b32_e32 v23, v19
	v_pk_add_f32 v[16:17], v[28:29], v[24:25]
	v_pk_add_f32 v[18:19], v[20:21], v[22:23]
	s_nop 0
	v_pk_add_f32 v[16:17], v[16:17], v[18:19]
	v_add_f32_e32 v16, v16, v17
	v_fmamk_f32 v16, v16, 0x3a800000, v170
	v_cmp_gt_f32_e32 vcc, s43, v16
	v_mul_f32_e32 v17, 0x4b800000, v16
	s_nop 0
	v_cndmask_b32_e32 v16, v16, v17, vcc
	v_rsq_f32_e32 v16, v16
	s_nop 0
	v_mul_f32_e32 v17, 0x45800000, v16
	v_cndmask_b32_e32 v16, v16, v17, vcc
	s_nop 0
	v_mov_b32_e32 v247, v16
	ds_write_b64 v244, v[246:247]

; DI int TIDX() { int t = (int)threadIdx.x; asm volatile("" : "+v"(t)); return t; }
; DI float sigmoidf_(float x) { return 1.f / (1.f + __expf(-x)); }
; DI float rstd_from16(const float* p, float inv_n) {
;   const f32x4 a = *(const f32x4*)p, b = *(const f32x4*)(p + 4), c = *(const f32x4*)(p + 8), d = *(const f32x4*)(p + 12);
;   const float s = ((a[0] + a[1]) + (a[2] + a[3])) + ((b[0] + b[1]) + (b[2] + b[3])) + ((c[0] + c[1]) + (c[2] + c[3])) + ((d[0] + d[1]) + (d[2] + d[3]));
;   return rsqrtf(s * inv_n + EPS_);
; DI void merge_tile(const Params& p, int layer, int tm, int tn, bf16_t* smem) {
;     ...
;     if ((sg & 1) == 0) {
;       const int t2 = TIDX(), row0 = tm * 256 + ((t2 >> 8) & 1) * 128 + (t2 & 15);
; #pragma unroll
;       for (int i = 0; i < 8; ++i) {
;         asm volatile("" ::: "memory");
;         const float rs = rstd_from16((const float*)(p.ws + O_SSQ) + (size_t)(row0 + i * 16) * 16, 1.f / 1024.f);
; #pragma unroll
;         for (int j = 0; j < 2; ++j) {
;           unsigned w = 0;
; #pragma unroll
;           for (int r = 0; r < 4; ++r) w |= (unsigned)__float2int_rn(sigmoidf_(acc[i][j][r] * rs) * 255.f) << (8 * r);
;           gsp[(i * 2 + j) * NTHR] = w;
.LBB0_1885:
	v_mov_b32_e32 v152, v220
	v_mov_b64_e32 v[214:215], v[26:27]
	v_lshrrev_b32_e32 v153, 1, v152
	v_and_b32_e32 v153, 0x80, v153
	v_and_b32_e32 v152, 15, v152
	v_or3_b32 v152, v152, v153, s48
	v_ashrrev_i32_e32 v153, 31, v152
	v_lshlrev_b64 v[154:155], 6, v[152:153]
	v_lshl_add_u64 v[166:167], s[6:7], 0, v[154:155]
	v_mov_b64_e32 v[210:211], v[30:31]
	v_mov_b64_e32 v[206:207], v[34:35]
	v_mov_b64_e32 v[202:203], v[38:39]
	v_mov_b64_e32 v[198:199], v[42:43]
	v_mov_b64_e32 v[194:195], v[46:47]
	v_mov_b64_e32 v[190:191], v[50:51]
	v_mov_b64_e32 v[186:187], v[54:55]
	v_mov_b64_e32 v[182:183], v[58:59]
	v_mov_b64_e32 v[178:179], v[62:63]
	v_mov_b64_e32 v[212:213], v[24:25]
	v_mov_b64_e32 v[208:209], v[28:29]
	v_mov_b64_e32 v[204:205], v[32:33]
	v_mov_b64_e32 v[200:201], v[36:37]
	v_mov_b64_e32 v[196:197], v[40:41]
	v_mov_b64_e32 v[192:193], v[44:45]
	v_mov_b64_e32 v[188:189], v[48:49]
	v_mov_b64_e32 v[184:185], v[52:53]
	v_mov_b64_e32 v[180:181], v[56:57]
	v_mov_b64_e32 v[176:177], v[60:61]
	v_bfe_u32 v244, v166, 6, 8
	v_lshlrev_b32_e32 v244, 3, v244
	v_add_u32_e32 v244, 0x24010, v244
	v_or_b32_e32 v246, 3, v166
	ds_read_b64 v[248:249], v244
	s_waitcnt lgkmcnt(0)
	v_cmp_ne_u32_e64 s[100:101], v248, v246
	s_nop 1
	s_and_saveexec_b64 s[98:99], s[100:101]
	s_cbranch_execz .LrcE1_0
	global_load_dwordx4 v[154:157], v[166:167], off
	global_load_dwordx4 v[158:161], v[166:167], off offset:16
	global_load_dwordx4 v[162:165], v[166:167], off offset:32
	s_nop 0
	global_load_dwordx4 v[166:169], v[166:167], off offset:48
	s_waitcnt vmcnt(3)
	v_mov_b32_e32 v170, v155
	v_mov_b32_e32 v171, v156
	v_mov_b32_e32 v155, v157
	s_waitcnt vmcnt(2)
	v_mov_b32_e32 v156, v159
	v_mov_b32_e32 v157, v160
	v_mov_b32_e32 v159, v161
	v_pk_add_f32 v[154:155], v[170:171], v[154:155]
	v_pk_add_f32 v[156:157], v[156:157], v[158:159]
	v_pk_add_f32 v[154:155], v[154:155], v[154:155] op_sel:[0,1] op_sel_hi:[1,0]
	v_pk_add_f32 v[156:157], v[156:157], v[156:157] op_sel:[0,1] op_sel_hi:[1,0]
	s_waitcnt vmcnt(1)
	v_add_f32_e32 v160, v162, v163
	v_add_f32_e32 v162, v164, v165
	s_waitcnt vmcnt(0)
	v_mov_b32_e32 v161, v168
	v_mov_b32_e32 v163, v169
	v_mov_b32_e32 v155, v166
	v_mov_b32_e32 v157, v167
	v_pk_add_f32 v[158:159], v[160:161], v[162:163]
	v_pk_add_f32 v[154:155], v[154:155], v[156:157]
	s_nop 0
	v_pk_add_f32 v[154:155], v[154:155], v[158:159]
	s_nop 0
	v_add_f32_e32 v153, v154, v155
	v_fmamk_f32 v153, v153, 0x3a800000, v225
	v_mul_f32_e32 v154, 0x4b800000, v153
	v_cmp_gt_f32_e32 vcc, s45, v153
	s_nop 1
	s_nop 0
	v_cndmask_b32_e32 v153, v153, v154, vcc
	v_rsq_f32_e32 v153, v153
	s_nop 0
	v_mul_f32_e32 v154, 0x45800000, v153
	v_cndmask_b32_e32 v153, v153, v154, vcc
	s_nop 0
	v_mov_b32_e32 v247, v153
	ds_write_b64 v244, v[246:247]
.LrcE1_0:
	s_or_b64 exec, exec, s[98:99]
	s_waitcnt vmcnt(0)
	v_cndmask_b32_e64 v153, v249, v153, s[100:101]
	v_mul_f32_e32 v148, v148, v153
	v_mul_f32_e32 v149, v149, v153
	v_mul_f32_e32 v148, 0xbfb8aa3b, v148
	v_mul_f32_e32 v150, v150, v153
	v_mul_f32_e32 v149, 0xbfb8aa3b, v149
	v_exp_f32_e32 v148, v148
	v_mul_f32_e32 v151, v151, v153
	v_mul_f32_e32 v150, 0xbfb8aa3b, v150
	v_exp_f32_e32 v149, v149
	v_mul_f32_e32 v151, 0xbfb8aa3b, v151
	v_exp_f32_e32 v150, v150
	v_exp_f32_e32 v151, v151
	v_add_f32_e32 v148, 1.0, v148
	v_add_f32_e32 v149, 1.0, v149
	v_add_f32_e32 v150, 1.0, v150
	v_div_scale_f32 v156, s[0:1], v149, v149, 1.0
	v_add_f32_e32 v151, 1.0, v151
	v_div_scale_f32 v158, s[2:3], v150, v150, 1.0
	v_rcp_f32_e32 v164, v156
	v_mul_f32_e32 v144, v144, v153
	v_div_scale_f32 v160, s[4:5], v151, v151, 1.0
	v_rcp_f32_e32 v165, v158
	v_mul_f32_e32 v144, 0xbfb8aa3b, v144
	v_rcp_f32_e32 v166, v160
	v_exp_f32_e32 v144, v144
	v_fma_f32 v169, -v156, v164, 1.0
	v_div_scale_f32 v157, s[0:1], 1.0, v149, 1.0
	v_fma_f32 v170, -v158, v165, 1.0
	v_fmac_f32_e32 v164, v169, v164
	v_div_scale_f32 v159, s[2:3], 1.0, v150, 1.0
	v_fma_f32 v171, -v160, v166, 1.0
	v_fmac_f32_e32 v165, v170, v165
	v_mul_f32_e32 v169, v157, v164
	v_add_f32_e32 v144, 1.0, v144
	v_div_scale_f32 v161, s[4:5], 1.0, v151, 1.0
	v_fmac_f32_e32 v166, v171, v166
	v_mul_f32_e32 v170, v159, v165
	v_fma_f32 v173, -v156, v169, v157
	v_mul_f32_e32 v171, v161, v166
	v_fma_f32 v174, -v158, v170, v159
	v_fmac_f32_e32 v169, v173, v164
	v_fma_f32 v175, -v160, v171, v161
	v_fmac_f32_e32 v170, v174, v165
	v_fma_f32 v155, -v156, v169, v157
	s_mov_b64 vcc, s[0:1]
	v_fmac_f32_e32 v171, v175, v166
	v_fma_f32 v156, -v158, v170, v159
	v_rcp_f32_e32 v148, v148
	v_div_fmas_f32 v154, v155, v164, v169
	s_mov_b64 vcc, s[2:3]
	v_fma_f32 v157, -v160, v171, v161
	v_div_fixup_f32 v149, v154, v149, 1.0
	v_div_fmas_f32 v154, v156, v165, v170
	s_mov_b64 vcc, s[4:5]
	v_div_fixup_f32 v150, v154, v150, 1.0
	v_div_fmas_f32 v154, v157, v166, v171
	v_div_fixup_f32 v151, v154, v151, 1.0
	v_mul_f32_e32 v145, v145, v153
	v_mul_f32_e32 v145, 0xbfb8aa3b, v145
	v_exp_f32_e32 v145, v145
	s_nop 0
	v_add_f32_e32 v145, 1.0, v145
	v_rcp_f32_e32 v144, v144
	v_mul_f32_e32 v146, v146, v153
	v_mul_f32_e32 v146, 0xbfb8aa3b, v146
	v_exp_f32_e32 v146, v146
	s_nop 0
	v_add_f32_e32 v146, 1.0, v146
	v_rcp_f32_e32 v145, v145
	v_mul_f32_e32 v147, v147, v153
	v_mul_f32_e32 v147, 0xbfb8aa3b, v147
	v_exp_f32_e32 v147, v147
	s_nop 0
	v_add_f32_e32 v147, 1.0, v147
	v_rcp_f32_e32 v146, v146
	v_mul_f32_e32 v148, 0x437f0000, v148
	v_mul_f32_e32 v149, 0x437f0000, v149
	v_mul_f32_e32 v144, 0x437f0000, v144
	v_mul_f32_e32 v145, 0x437f0000, v145
	v_rcp_f32_e32 v147, v147
	v_rndne_f32_e32 v148, v148
	v_rndne_f32_e32 v149, v149
	v_mul_f32_e32 v150, 0x437f0000, v150
	v_mul_f32_e32 v151, 0x437f0000, v151
	v_rndne_f32_e32 v144, v144
	v_rndne_f32_e32 v145, v145
	v_mul_f32_e32 v146, 0x437f0000, v146
	v_mul_f32_e32 v147, 0x437f0000, v147
	v_cvt_i32_f32_e32 v148, v148
	v_cvt_i32_f32_e32 v149, v149
	v_rndne_f32_e32 v150, v150
	v_rndne_f32_e32 v151, v151
	v_cvt_i32_f32_e32 v144, v144
	v_cvt_i32_f32_e32 v145, v145
	v_rndne_f32_e32 v146, v146
	v_rndne_f32_e32 v147, v147
	v_cvt_i32_f32_sdwa v150, v150 dst_sel:WORD_1 dst_unused:UNUSED_PAD src0_sel:DWORD
	v_cvt_i32_f32_sdwa v151, v151 dst_sel:BYTE_3 dst_unused:UNUSED_PAD src0_sel:DWORD
	v_cvt_i32_f32_sdwa v146, v146 dst_sel:WORD_1 dst_unused:UNUSED_PAD src0_sel:DWORD
	v_cvt_i32_f32_sdwa v147, v147 dst_sel:BYTE_3 dst_unused:UNUSED_PAD src0_sel:DWORD
	v_lshl_or_b32 v148, v149, 8, v148
	v_lshl_or_b32 v144, v145, 8, v144
	v_or3_b32 v148, v148, v150, v151
	v_or3_b32 v144, v144, v146, v147
	ds_write2st64_b32 v228, v148, v144 offset1:8
	v_or_b32_e32 v144, 16, v152
	v_ashrrev_i32_e32 v145, 31, v144
	v_lshlrev_b64 v[144:145], 6, v[144:145]
	v_lshl_add_u64 v[158:159], s[6:7], 0, v[144:145]
	v_bfe_u32 v244, v158, 6, 8
	v_lshlrev_b32_e32 v244, 3, v244
	v_add_u32_e32 v244, 0x24010, v244
	v_or_b32_e32 v246, 3, v158
	ds_read_b64 v[248:249], v244
	s_waitcnt lgkmcnt(0)
	v_cmp_ne_u32_e64 s[100:101], v248, v246
	s_nop 1
	s_and_saveexec_b64 s[98:99], s[100:101]
	s_cbranch_execz .LrcE1_1
; DI float sigmoidf_(float x) { return 1.f / (1.f + __expf(-x)); }
; DI float rstd_from16(const float* p, float inv_n) {
;   const f32x4 a = *(const f32x4*)p, b = *(const f32x4*)(p + 4), c = *(const f32x4*)(p + 8), d = *(const f32x4*)(p + 12);
;   const float s = ((a[0] + a[1]) + (a[2] + a[3])) + ((b[0] + b[1]) + (b[2] + b[3])) + ((c[0] + c[1]) + (c[2] + c[3])) + ((d[0] + d[1]) + (d[2] + d[3]));
;   return rsqrtf(s * inv_n + EPS_);
; DI void merge_tile(const Params& p, int layer, int tm, int tn, bf16_t* smem) {
;     ...
;         const float rs = rstd_from16((const float*)(p.ws + O_SSQ) + (size_t)(row0 + i * 16) * 16, 1.f / 1024.f);
; #pragma unroll
;         for (int j = 0; j < 2; ++j) {
;           unsigned w = 0;
; #pragma unroll
;           for (int r = 0; r < 4; ++r) w |= (unsigned)__float2int_rn(sigmoidf_(acc[i][j][r] * rs) * 255.f) << (8 * r);
;           gsp[(i * 2 + j) * NTHR] = w;
	global_load_dwordx4 v[144:147], v[158:159], off
	global_load_dwordx4 v[148:151], v[158:159], off offset:16
	global_load_dwordx4 v[154:157], v[158:159], off offset:32
	s_nop 0
	global_load_dwordx4 v[158:161], v[158:159], off offset:48
	s_waitcnt vmcnt(3)
	v_mov_b32_e32 v162, v145
	v_mov_b32_e32 v163, v146
	v_mov_b32_e32 v145, v147
	s_waitcnt vmcnt(2)
	v_mov_b32_e32 v146, v149
	v_mov_b32_e32 v147, v150
	v_mov_b32_e32 v149, v151
	v_pk_add_f32 v[144:145], v[162:163], v[144:145]
	v_pk_add_f32 v[146:147], v[146:147], v[148:149]
	v_pk_add_f32 v[144:145], v[144:145], v[144:145] op_sel:[0,1] op_sel_hi:[1,0]
	v_pk_add_f32 v[146:147], v[146:147], v[146:147] op_sel:[0,1] op_sel_hi:[1,0]
	s_waitcnt vmcnt(1)
	v_add_f32_e32 v148, v154, v155
	v_add_f32_e32 v150, v156, v157
	s_waitcnt vmcnt(0)
	v_mov_b32_e32 v145, v158
	v_mov_b32_e32 v147, v159
	v_mov_b32_e32 v149, v160
	v_mov_b32_e32 v151, v161
	v_pk_add_f32 v[144:145], v[144:145], v[146:147]
	v_pk_add_f32 v[146:147], v[148:149], v[150:151]
	v_pk_add_f32 v[144:145], v[144:145], v[146:147]
	v_add_f32_e32 v144, v144, v145
	v_fmamk_f32 v144, v144, 0x3a800000, v225
	v_mul_f32_e32 v145, 0x4b800000, v144
	v_cmp_gt_f32_e32 vcc, s45, v144
	s_nop 1
	v_cndmask_b32_e32 v144, v144, v145, vcc
	v_rsq_f32_e32 v144, v144
	s_nop 0
	v_mul_f32_e32 v145, 0x45800000, v144
	v_cndmask_b32_e32 v144, v144, v145, vcc
	s_nop 0
	v_mov_b32_e32 v247, v144
	ds_write_b64 v244, v[246:247]
.LrcE1_1:
	s_or_b64 exec, exec, s[98:99]
	s_waitcnt vmcnt(0)
	v_cndmask_b32_e64 v144, v249, v144, s[100:101]
	v_mov_b64_e32 v[174:175], v[66:67]
	v_mov_b64_e32 v[170:171], v[70:71]
	v_mov_b64_e32 v[166:167], v[74:75]
	v_mov_b64_e32 v[172:173], v[64:65]
	v_mov_b64_e32 v[168:169], v[68:69]
	v_mov_b64_e32 v[164:165], v[72:73]
	v_mov_b64_e32 v[162:163], v[78:79]
	v_mov_b64_e32 v[158:159], v[82:83]
	v_mov_b64_e32 v[160:161], v[76:77]
	v_mov_b64_e32 v[156:157], v[80:81]
	v_mul_f32_e32 v140, v140, v144
	v_mul_f32_e32 v140, 0xbfb8aa3b, v140
	v_exp_f32_e32 v140, v140
	v_mul_f32_e32 v141, v141, v144
	v_mul_f32_e32 v141, 0xbfb8aa3b, v141
	v_exp_f32_e32 v141, v141
	v_add_f32_e32 v140, 1.0, v140
	v_add_f32_e32 v141, 1.0, v141
	v_mul_f32_e32 v142, v142, v144
	v_mul_f32_e32 v142, 0xbfb8aa3b, v142
	v_rcp_f32_e32 v140, v140
	v_exp_f32_e32 v142, v142
	v_mul_f32_e32 v143, v143, v144
	v_mul_f32_e32 v143, 0xbfb8aa3b, v143
	v_add_f32_e32 v142, 1.0, v142
	v_rcp_f32_e32 v141, v141
	v_exp_f32_e32 v143, v143
	v_mul_f32_e32 v136, v136, v144
	v_mul_f32_e32 v136, 0xbfb8aa3b, v136
	v_add_f32_e32 v143, 1.0, v143
	v_rcp_f32_e32 v142, v142
	v_exp_f32_e32 v136, v136
	v_mul_f32_e32 v137, v137, v144
	v_mul_f32_e32 v137, 0xbfb8aa3b, v137
	v_add_f32_e32 v136, 1.0, v136
	v_rcp_f32_e32 v143, v143
	v_exp_f32_e32 v137, v137
	v_mul_f32_e32 v138, v138, v144
	v_mul_f32_e32 v138, 0xbfb8aa3b, v138
	v_add_f32_e32 v137, 1.0, v137
	v_rcp_f32_e32 v136, v136
	v_exp_f32_e32 v138, v138
	v_mul_f32_e32 v139, v139, v144
	v_mul_f32_e32 v139, 0xbfb8aa3b, v139
	v_add_f32_e32 v138, 1.0, v138
	v_rcp_f32_e32 v137, v137
	v_exp_f32_e32 v139, v139
	v_mul_f32_e32 v140, 0x437f0000, v140
	v_mul_f32_e32 v141, 0x437f0000, v141
	v_add_f32_e32 v139, 1.0, v139
	v_rcp_f32_e32 v138, v138
	v_mul_f32_e32 v136, 0x437f0000, v136
	v_mul_f32_e32 v137, 0x437f0000, v137
	v_rndne_f32_e32 v140, v140
	v_rcp_f32_e32 v139, v139
	v_rndne_f32_e32 v141, v141
	v_mul_f32_e32 v142, 0x437f0000, v142
	v_mul_f32_e32 v143, 0x437f0000, v143
	v_rndne_f32_e32 v136, v136
	v_rndne_f32_e32 v137, v137
	v_mul_f32_e32 v138, 0x437f0000, v138
	v_mul_f32_e32 v139, 0x437f0000, v139
	v_cvt_i32_f32_e32 v140, v140
	v_cvt_i32_f32_e32 v141, v141
	v_rndne_f32_e32 v142, v142
	v_rndne_f32_e32 v143, v143
	v_cvt_i32_f32_e32 v136, v136
	v_cvt_i32_f32_e32 v137, v137
	v_rndne_f32_e32 v138, v138
	v_rndne_f32_e32 v139, v139
	v_cvt_i32_f32_sdwa v142, v142 dst_sel:WORD_1 dst_unused:UNUSED_PAD src0_sel:DWORD
	v_cvt_i32_f32_sdwa v143, v143 dst_sel:BYTE_3 dst_unused:UNUSED_PAD src0_sel:DWORD
	v_cvt_i32_f32_sdwa v138, v138 dst_sel:WORD_1 dst_unused:UNUSED_PAD src0_sel:DWORD
	v_cvt_i32_f32_sdwa v139, v139 dst_sel:BYTE_3 dst_unused:UNUSED_PAD src0_sel:DWORD
	v_lshl_or_b32 v140, v141, 8, v140
	v_lshl_or_b32 v136, v137, 8, v136
	v_or3_b32 v140, v140, v142, v143
	v_or3_b32 v136, v136, v138, v139
	ds_write2st64_b32 v228, v140, v136 offset0:16 offset1:24
	v_or_b32_e32 v136, 32, v152
	v_ashrrev_i32_e32 v137, 31, v136
	v_lshlrev_b64 v[136:137], 6, v[136:137]
	v_lshl_add_u64 v[148:149], s[6:7], 0, v[136:137]
	v_bfe_u32 v244, v148, 6, 8
	v_lshlrev_b32_e32 v244, 3, v244
	v_add_u32_e32 v244, 0x24010, v244
	v_or_b32_e32 v246, 3, v148
	ds_read_b64 v[248:249], v244
	s_waitcnt lgkmcnt(0)
	v_cmp_ne_u32_e64 s[100:101], v248, v246
	s_nop 1
	s_and_saveexec_b64 s[98:99], s[100:101]
	s_cbranch_execz .LrcE1_2
	global_load_dwordx4 v[136:139], v[148:149], off
	global_load_dwordx4 v[140:143], v[148:149], off offset:16
	global_load_dwordx4 v[144:147], v[148:149], off offset:32
	s_nop 0
	global_load_dwordx4 v[148:151], v[148:149], off offset:48
	s_waitcnt vmcnt(3)
	v_mov_b32_e32 v154, v137
	v_mov_b32_e32 v155, v138
	v_mov_b32_e32 v137, v139
	s_waitcnt vmcnt(2)
	v_mov_b32_e32 v138, v141
	v_mov_b32_e32 v139, v142
	v_mov_b32_e32 v141, v143
	v_pk_add_f32 v[136:137], v[154:155], v[136:137]
	v_pk_add_f32 v[138:139], v[138:139], v[140:141]
	v_pk_add_f32 v[136:137], v[136:137], v[136:137] op_sel:[0,1] op_sel_hi:[1,0]
	v_pk_add_f32 v[138:139], v[138:139], v[138:139] op_sel:[0,1] op_sel_hi:[1,0]
	s_waitcnt vmcnt(1)
	v_add_f32_e32 v140, v144, v145
	v_add_f32_e32 v142, v146, v147
	s_waitcnt vmcnt(0)
	v_mov_b32_e32 v137, v148
	v_mov_b32_e32 v139, v149
	v_mov_b32_e32 v141, v150
	v_mov_b32_e32 v143, v151
	v_pk_add_f32 v[136:137], v[136:137], v[138:139]
	v_pk_add_f32 v[138:139], v[140:141], v[142:143]
	s_nop 0
	v_pk_add_f32 v[136:137], v[136:137], v[138:139]
	s_nop 0
	v_add_f32_e32 v136, v136, v137
	v_fmamk_f32 v136, v136, 0x3a800000, v225
	v_mul_f32_e32 v137, 0x4b800000, v136
	v_cmp_gt_f32_e32 vcc, s45, v136
	s_nop 1
	s_nop 0
	v_cndmask_b32_e32 v136, v136, v137, vcc
	v_rsq_f32_e32 v136, v136
	s_nop 0
	v_mul_f32_e32 v137, 0x45800000, v136
	v_cndmask_b32_e32 v136, v136, v137, vcc
	s_nop 0
	v_mov_b32_e32 v247, v136
	ds_write_b64 v244, v[246:247]
; DI float sigmoidf_(float x) { return 1.f / (1.f + __expf(-x)); }
; DI float rstd_from16(const float* p, float inv_n) {
;   const f32x4 a = *(const f32x4*)p, b = *(const f32x4*)(p + 4), c = *(const f32x4*)(p + 8), d = *(const f32x4*)(p + 12);
;   const float s = ((a[0] + a[1]) + (a[2] + a[3])) + ((b[0] + b[1]) + (b[2] + b[3])) + ((c[0] + c[1]) + (c[2] + c[3])) + ((d[0] + d[1]) + (d[2] + d[3]));
;   return rsqrtf(s * inv_n + EPS_);
; DI void merge_tile(const Params& p, int layer, int tm, int tn, bf16_t* smem) {
;     ...
;         const float rs = rstd_from16((const float*)(p.ws + O_SSQ) + (size_t)(row0 + i * 16) * 16, 1.f / 1024.f);
; #pragma unroll
;         for (int j = 0; j < 2; ++j) {
;           unsigned w = 0;
; #pragma unroll
;           for (int r = 0; r < 4; ++r) w |= (unsigned)__float2int_rn(sigmoidf_(acc[i][j][r] * rs) * 255.f) << (8 * r);
;           gsp[(i * 2 + j) * NTHR] = w;
.LrcE1_2:
	s_or_b64 exec, exec, s[98:99]
	s_waitcnt vmcnt(0)
	v_cndmask_b32_e64 v136, v249, v136, s[100:101]
	v_mul_f32_e32 v132, v132, v136
	v_mul_f32_e32 v132, 0xbfb8aa3b, v132
	v_exp_f32_e32 v132, v132
	v_mul_f32_e32 v133, v133, v136
	v_mul_f32_e32 v133, 0xbfb8aa3b, v133
	v_exp_f32_e32 v133, v133
	v_add_f32_e32 v132, 1.0, v132
	v_add_f32_e32 v133, 1.0, v133
	v_mul_f32_e32 v134, v134, v136
	v_mul_f32_e32 v134, 0xbfb8aa3b, v134
	v_rcp_f32_e32 v132, v132
	v_exp_f32_e32 v134, v134
	v_mul_f32_e32 v135, v135, v136
	v_mul_f32_e32 v135, 0xbfb8aa3b, v135
	v_add_f32_e32 v134, 1.0, v134
	v_rcp_f32_e32 v133, v133
	v_exp_f32_e32 v135, v135
	v_mul_f32_e32 v128, v128, v136
	v_mul_f32_e32 v128, 0xbfb8aa3b, v128
	v_add_f32_e32 v135, 1.0, v135
	v_rcp_f32_e32 v134, v134
	v_exp_f32_e32 v128, v128
	v_mul_f32_e32 v129, v129, v136
	v_mul_f32_e32 v129, 0xbfb8aa3b, v129
	v_add_f32_e32 v128, 1.0, v128
	v_rcp_f32_e32 v135, v135
	v_exp_f32_e32 v129, v129
	v_mul_f32_e32 v130, v130, v136
	v_mul_f32_e32 v130, 0xbfb8aa3b, v130
	v_add_f32_e32 v129, 1.0, v129
	v_rcp_f32_e32 v128, v128
	v_exp_f32_e32 v130, v130
	v_mul_f32_e32 v131, v131, v136
	v_mul_f32_e32 v131, 0xbfb8aa3b, v131
	v_add_f32_e32 v130, 1.0, v130
	v_rcp_f32_e32 v129, v129
	v_exp_f32_e32 v131, v131
	v_mul_f32_e32 v132, 0x437f0000, v132
	v_mul_f32_e32 v133, 0x437f0000, v133
	v_add_f32_e32 v131, 1.0, v131
	v_rcp_f32_e32 v130, v130
	v_mul_f32_e32 v128, 0x437f0000, v128
	v_mul_f32_e32 v129, 0x437f0000, v129
	v_rndne_f32_e32 v132, v132
	v_rcp_f32_e32 v131, v131
	v_rndne_f32_e32 v133, v133
	v_mul_f32_e32 v134, 0x437f0000, v134
	v_mul_f32_e32 v135, 0x437f0000, v135
	v_rndne_f32_e32 v128, v128
	v_rndne_f32_e32 v129, v129
	v_mul_f32_e32 v130, 0x437f0000, v130
	v_mul_f32_e32 v131, 0x437f0000, v131
	v_cvt_i32_f32_e32 v132, v132
	v_cvt_i32_f32_e32 v133, v133
	v_rndne_f32_e32 v134, v134
	v_rndne_f32_e32 v135, v135
	v_cvt_i32_f32_e32 v128, v128
	v_cvt_i32_f32_e32 v129, v129
	v_rndne_f32_e32 v130, v130
	v_rndne_f32_e32 v131, v131
	v_cvt_i32_f32_sdwa v134, v134 dst_sel:WORD_1 dst_unused:UNUSED_PAD src0_sel:DWORD
	v_cvt_i32_f32_sdwa v135, v135 dst_sel:BYTE_3 dst_unused:UNUSED_PAD src0_sel:DWORD
	v_cvt_i32_f32_sdwa v130, v130 dst_sel:WORD_1 dst_unused:UNUSED_PAD src0_sel:DWORD
	v_cvt_i32_f32_sdwa v131, v131 dst_sel:BYTE_3 dst_unused:UNUSED_PAD src0_sel:DWORD
	v_lshl_or_b32 v132, v133, 8, v132
	v_lshl_or_b32 v128, v129, 8, v128
	v_or3_b32 v132, v132, v134, v135
	v_or3_b32 v128, v128, v130, v131
	ds_write2st64_b32 v228, v132, v128 offset0:32 offset1:40
	v_or_b32_e32 v128, 48, v152
	v_ashrrev_i32_e32 v129, 31, v128
	v_lshlrev_b64 v[128:129], 6, v[128:129]
	v_lshl_add_u64 v[140:141], s[6:7], 0, v[128:129]
	v_bfe_u32 v244, v140, 6, 8
	v_lshlrev_b32_e32 v244, 3, v244
	v_add_u32_e32 v244, 0x24010, v244
	v_or_b32_e32 v246, 3, v140
	ds_read_b64 v[248:249], v244
	s_waitcnt lgkmcnt(0)
	v_cmp_ne_u32_e64 s[100:101], v248, v246
	s_nop 1
	s_and_saveexec_b64 s[98:99], s[100:101]
	s_cbranch_execz .LrcE1_3
	global_load_dwordx4 v[128:131], v[140:141], off
	global_load_dwordx4 v[132:135], v[140:141], off offset:16
	global_load_dwordx4 v[136:139], v[140:141], off offset:32
	s_nop 0
	global_load_dwordx4 v[140:143], v[140:141], off offset:48
	s_waitcnt vmcnt(3)
	v_mov_b32_e32 v144, v129
	v_mov_b32_e32 v145, v130
	v_mov_b32_e32 v129, v131
	s_waitcnt vmcnt(2)
	v_mov_b32_e32 v130, v133
	v_mov_b32_e32 v131, v134
	v_mov_b32_e32 v133, v135
	v_pk_add_f32 v[128:129], v[144:145], v[128:129]
	v_pk_add_f32 v[130:131], v[130:131], v[132:133]
	v_pk_add_f32 v[128:129], v[128:129], v[128:129] op_sel:[0,1] op_sel_hi:[1,0]
	v_pk_add_f32 v[130:131], v[130:131], v[130:131] op_sel:[0,1] op_sel_hi:[1,0]
	s_waitcnt vmcnt(1)
	v_add_f32_e32 v132, v136, v137
	v_add_f32_e32 v134, v138, v139
	s_waitcnt vmcnt(0)
	v_mov_b32_e32 v129, v140
	v_mov_b32_e32 v131, v141
	v_mov_b32_e32 v133, v142
	v_mov_b32_e32 v135, v143
	v_pk_add_f32 v[128:129], v[128:129], v[130:131]
	v_pk_add_f32 v[130:131], v[132:133], v[134:135]
	s_nop 0
	v_pk_add_f32 v[128:129], v[128:129], v[130:131]
	s_nop 0
	v_add_f32_e32 v128, v128, v129
	v_fmamk_f32 v128, v128, 0x3a800000, v225
	v_mul_f32_e32 v129, 0x4b800000, v128
	v_cmp_gt_f32_e32 vcc, s45, v128
	s_nop 1
	s_nop 0
	v_cndmask_b32_e32 v128, v128, v129, vcc
	v_rsq_f32_e32 v128, v128
	s_nop 0
	v_mul_f32_e32 v129, 0x45800000, v128
	v_cndmask_b32_e32 v128, v128, v129, vcc
	s_nop 0
	v_mov_b32_e32 v247, v128
	ds_write_b64 v244, v[246:247]
; DI float sigmoidf_(float x) { return 1.f / (1.f + __expf(-x)); }
; DI float rstd_from16(const float* p, float inv_n) {
;   const f32x4 a = *(const f32x4*)p, b = *(const f32x4*)(p + 4), c = *(const f32x4*)(p + 8), d = *(const f32x4*)(p + 12);
;   const float s = ((a[0] + a[1]) + (a[2] + a[3])) + ((b[0] + b[1]) + (b[2] + b[3])) + ((c[0] + c[1]) + (c[2] + c[3])) + ((d[0] + d[1]) + (d[2] + d[3]));
;   return rsqrtf(s * inv_n + EPS_);
; DI void merge_tile(const Params& p, int layer, int tm, int tn, bf16_t* smem) {
;     ...
;         const float rs = rstd_from16((const float*)(p.ws + O_SSQ) + (size_t)(row0 + i * 16) * 16, 1.f / 1024.f);
; #pragma unroll
;         for (int j = 0; j < 2; ++j) {
;           unsigned w = 0;
; #pragma unroll
;           for (int r = 0; r < 4; ++r) w |= (unsigned)__float2int_rn(sigmoidf_(acc[i][j][r] * rs) * 255.f) << (8 * r);
;           gsp[(i * 2 + j) * NTHR] = w;
.LrcE1_3:
	s_or_b64 exec, exec, s[98:99]
	s_waitcnt vmcnt(0)
	v_cndmask_b32_e64 v128, v249, v128, s[100:101]
	v_mul_f32_e32 v124, v124, v128
	v_mul_f32_e32 v124, 0xbfb8aa3b, v124
	v_exp_f32_e32 v124, v124
	v_mul_f32_e32 v125, v125, v128
	v_mul_f32_e32 v125, 0xbfb8aa3b, v125
	v_exp_f32_e32 v125, v125
	v_add_f32_e32 v124, 1.0, v124
	v_add_f32_e32 v125, 1.0, v125
	v_mul_f32_e32 v126, v126, v128
	v_mul_f32_e32 v126, 0xbfb8aa3b, v126
	v_rcp_f32_e32 v124, v124
	v_exp_f32_e32 v126, v126
	v_mul_f32_e32 v127, v127, v128
	v_mul_f32_e32 v127, 0xbfb8aa3b, v127
	v_add_f32_e32 v126, 1.0, v126
	v_rcp_f32_e32 v125, v125
	v_exp_f32_e32 v127, v127
	v_mul_f32_e32 v120, v120, v128
	v_mul_f32_e32 v120, 0xbfb8aa3b, v120
	v_add_f32_e32 v127, 1.0, v127
	v_rcp_f32_e32 v126, v126
	v_exp_f32_e32 v120, v120
	v_mul_f32_e32 v121, v121, v128
	v_mul_f32_e32 v121, 0xbfb8aa3b, v121
	v_add_f32_e32 v120, 1.0, v120
	v_rcp_f32_e32 v127, v127
	v_exp_f32_e32 v121, v121
	v_mul_f32_e32 v122, v122, v128
	v_mul_f32_e32 v122, 0xbfb8aa3b, v122
	v_add_f32_e32 v121, 1.0, v121
	v_rcp_f32_e32 v120, v120
	v_exp_f32_e32 v122, v122
	v_mul_f32_e32 v123, v123, v128
	v_mul_f32_e32 v123, 0xbfb8aa3b, v123
	v_add_f32_e32 v122, 1.0, v122
	v_rcp_f32_e32 v121, v121
	v_exp_f32_e32 v123, v123
	v_mul_f32_e32 v124, 0x437f0000, v124
	v_mul_f32_e32 v125, 0x437f0000, v125
	v_add_f32_e32 v123, 1.0, v123
	v_rcp_f32_e32 v122, v122
	v_mul_f32_e32 v120, 0x437f0000, v120
	v_mul_f32_e32 v121, 0x437f0000, v121
	v_rndne_f32_e32 v124, v124
	v_rcp_f32_e32 v123, v123
	v_rndne_f32_e32 v125, v125
	v_mul_f32_e32 v126, 0x437f0000, v126
	v_mul_f32_e32 v127, 0x437f0000, v127
	v_rndne_f32_e32 v120, v120
	v_rndne_f32_e32 v121, v121
	v_mul_f32_e32 v122, 0x437f0000, v122
	v_mul_f32_e32 v123, 0x437f0000, v123
	v_cvt_i32_f32_e32 v124, v124
	v_cvt_i32_f32_e32 v125, v125
	v_rndne_f32_e32 v126, v126
	v_rndne_f32_e32 v127, v127
	v_cvt_i32_f32_e32 v120, v120
	v_cvt_i32_f32_e32 v121, v121
	v_rndne_f32_e32 v122, v122
	v_rndne_f32_e32 v123, v123
	v_cvt_i32_f32_sdwa v126, v126 dst_sel:WORD_1 dst_unused:UNUSED_PAD src0_sel:DWORD
	v_cvt_i32_f32_sdwa v127, v127 dst_sel:BYTE_3 dst_unused:UNUSED_PAD src0_sel:DWORD
	v_cvt_i32_f32_sdwa v122, v122 dst_sel:WORD_1 dst_unused:UNUSED_PAD src0_sel:DWORD
	v_cvt_i32_f32_sdwa v123, v123 dst_sel:BYTE_3 dst_unused:UNUSED_PAD src0_sel:DWORD
	v_lshl_or_b32 v124, v125, 8, v124
	v_lshl_or_b32 v120, v121, 8, v120
	v_or3_b32 v124, v124, v126, v127
	v_or3_b32 v120, v120, v122, v123
	ds_write2st64_b32 v228, v124, v120 offset0:48 offset1:56
	v_or_b32_e32 v120, 64, v152
	v_ashrrev_i32_e32 v121, 31, v120
	v_lshlrev_b64 v[120:121], 6, v[120:121]
	v_lshl_add_u64 v[132:133], s[6:7], 0, v[120:121]
	v_bfe_u32 v244, v132, 6, 8
	v_lshlrev_b32_e32 v244, 3, v244
	v_add_u32_e32 v244, 0x24010, v244
	v_or_b32_e32 v246, 3, v132
	ds_read_b64 v[248:249], v244
	s_waitcnt lgkmcnt(0)
	v_cmp_ne_u32_e64 s[100:101], v248, v246
	s_nop 1
	s_and_saveexec_b64 s[98:99], s[100:101]
	s_cbranch_execz .LrcE1_4
	global_load_dwordx4 v[120:123], v[132:133], off
	global_load_dwordx4 v[124:127], v[132:133], off offset:16
	global_load_dwordx4 v[128:131], v[132:133], off offset:32
	s_nop 0
	global_load_dwordx4 v[132:135], v[132:133], off offset:48
	s_waitcnt vmcnt(3)
	v_mov_b32_e32 v136, v121
	v_mov_b32_e32 v137, v122
	v_mov_b32_e32 v121, v123
	s_waitcnt vmcnt(2)
	v_mov_b32_e32 v122, v125
	v_mov_b32_e32 v123, v126
	v_mov_b32_e32 v125, v127
	v_pk_add_f32 v[120:121], v[136:137], v[120:121]
	v_pk_add_f32 v[122:123], v[122:123], v[124:125]
	v_pk_add_f32 v[120:121], v[120:121], v[120:121] op_sel:[0,1] op_sel_hi:[1,0]
	v_pk_add_f32 v[122:123], v[122:123], v[122:123] op_sel:[0,1] op_sel_hi:[1,0]
	s_waitcnt vmcnt(1)
	v_add_f32_e32 v124, v128, v129
	v_add_f32_e32 v126, v130, v131
	s_waitcnt vmcnt(0)
	v_mov_b32_e32 v121, v132
	v_mov_b32_e32 v123, v133
	v_mov_b32_e32 v125, v134
	v_mov_b32_e32 v127, v135
	v_pk_add_f32 v[120:121], v[120:121], v[122:123]
	v_pk_add_f32 v[122:123], v[124:125], v[126:127]
	s_nop 0
	v_pk_add_f32 v[120:121], v[120:121], v[122:123]
	s_nop 0
	v_add_f32_e32 v120, v120, v121
	v_fmamk_f32 v120, v120, 0x3a800000, v225
	v_mul_f32_e32 v121, 0x4b800000, v120
	v_cmp_gt_f32_e32 vcc, s45, v120
	s_nop 1
	s_nop 0
	v_cndmask_b32_e32 v120, v120, v121, vcc
	v_rsq_f32_e32 v120, v120
	s_nop 0
	v_mul_f32_e32 v121, 0x45800000, v120
	v_cndmask_b32_e32 v120, v120, v121, vcc
	s_nop 0
	v_mov_b32_e32 v247, v120
	ds_write_b64 v244, v[246:247]
; DI float sigmoidf_(float x) { return 1.f / (1.f + __expf(-x)); }
; DI float rstd_from16(const float* p, float inv_n) {
;   const f32x4 a = *(const f32x4*)p, b = *(const f32x4*)(p + 4), c = *(const f32x4*)(p + 8), d = *(const f32x4*)(p + 12);
;   const float s = ((a[0] + a[1]) + (a[2] + a[3])) + ((b[0] + b[1]) + (b[2] + b[3])) + ((c[0] + c[1]) + (c[2] + c[3])) + ((d[0] + d[1]) + (d[2] + d[3]));
;   return rsqrtf(s * inv_n + EPS_);
; DI void merge_tile(const Params& p, int layer, int tm, int tn, bf16_t* smem) {
;     ...
;         const float rs = rstd_from16((const float*)(p.ws + O_SSQ) + (size_t)(row0 + i * 16) * 16, 1.f / 1024.f);
; #pragma unroll
;         for (int j = 0; j < 2; ++j) {
;           unsigned w = 0;
; #pragma unroll
;           for (int r = 0; r < 4; ++r) w |= (unsigned)__float2int_rn(sigmoidf_(acc[i][j][r] * rs) * 255.f) << (8 * r);
;           gsp[(i * 2 + j) * NTHR] = w;
.LrcE1_4:
	s_or_b64 exec, exec, s[98:99]
	s_waitcnt vmcnt(0)
	v_cndmask_b32_e64 v120, v249, v120, s[100:101]
	v_mul_f32_e32 v116, v116, v120
	v_mul_f32_e32 v116, 0xbfb8aa3b, v116
	v_exp_f32_e32 v116, v116
	v_mul_f32_e32 v117, v117, v120
	v_mul_f32_e32 v117, 0xbfb8aa3b, v117
	v_exp_f32_e32 v117, v117
	v_add_f32_e32 v116, 1.0, v116
	v_add_f32_e32 v117, 1.0, v117
	v_mul_f32_e32 v118, v118, v120
	v_mul_f32_e32 v118, 0xbfb8aa3b, v118
	v_rcp_f32_e32 v116, v116
	v_exp_f32_e32 v118, v118
	v_mul_f32_e32 v119, v119, v120
	v_mul_f32_e32 v119, 0xbfb8aa3b, v119
	v_add_f32_e32 v118, 1.0, v118
	v_rcp_f32_e32 v117, v117
	v_exp_f32_e32 v119, v119
	v_mul_f32_e32 v112, v112, v120
	v_mul_f32_e32 v112, 0xbfb8aa3b, v112
	v_add_f32_e32 v119, 1.0, v119
	v_rcp_f32_e32 v118, v118
	v_exp_f32_e32 v112, v112
	v_mul_f32_e32 v113, v113, v120
	v_mul_f32_e32 v113, 0xbfb8aa3b, v113
	v_add_f32_e32 v112, 1.0, v112
	v_rcp_f32_e32 v119, v119
	v_exp_f32_e32 v113, v113
	v_mul_f32_e32 v114, v114, v120
	v_mul_f32_e32 v114, 0xbfb8aa3b, v114
	v_add_f32_e32 v113, 1.0, v113
	v_rcp_f32_e32 v112, v112
	v_exp_f32_e32 v114, v114
	v_mul_f32_e32 v115, v115, v120
	v_mul_f32_e32 v115, 0xbfb8aa3b, v115
	v_add_f32_e32 v114, 1.0, v114
	v_rcp_f32_e32 v113, v113
	v_exp_f32_e32 v115, v115
	v_mul_f32_e32 v116, 0x437f0000, v116
	v_mul_f32_e32 v117, 0x437f0000, v117
	v_add_f32_e32 v115, 1.0, v115
	v_rcp_f32_e32 v114, v114
	v_mul_f32_e32 v112, 0x437f0000, v112
	v_mul_f32_e32 v113, 0x437f0000, v113
	v_rndne_f32_e32 v116, v116
	v_rcp_f32_e32 v115, v115
	v_rndne_f32_e32 v117, v117
	v_mul_f32_e32 v118, 0x437f0000, v118
	v_mul_f32_e32 v119, 0x437f0000, v119
	v_rndne_f32_e32 v112, v112
	v_rndne_f32_e32 v113, v113
	v_mul_f32_e32 v114, 0x437f0000, v114
	v_mul_f32_e32 v115, 0x437f0000, v115
	v_cvt_i32_f32_e32 v116, v116
	v_cvt_i32_f32_e32 v117, v117
	v_rndne_f32_e32 v118, v118
	v_rndne_f32_e32 v119, v119
	v_cvt_i32_f32_e32 v112, v112
	v_cvt_i32_f32_e32 v113, v113
	v_rndne_f32_e32 v114, v114
	v_rndne_f32_e32 v115, v115
	v_cvt_i32_f32_sdwa v118, v118 dst_sel:WORD_1 dst_unused:UNUSED_PAD src0_sel:DWORD
	v_cvt_i32_f32_sdwa v119, v119 dst_sel:BYTE_3 dst_unused:UNUSED_PAD src0_sel:DWORD
	v_cvt_i32_f32_sdwa v114, v114 dst_sel:WORD_1 dst_unused:UNUSED_PAD src0_sel:DWORD
	v_cvt_i32_f32_sdwa v115, v115 dst_sel:BYTE_3 dst_unused:UNUSED_PAD src0_sel:DWORD
	v_lshl_or_b32 v116, v117, 8, v116
	v_lshl_or_b32 v112, v113, 8, v112
	v_or3_b32 v116, v116, v118, v119
	v_or3_b32 v112, v112, v114, v115
	ds_write2st64_b32 v228, v116, v112 offset0:64 offset1:72
	v_or_b32_e32 v112, 0x50, v152
	v_ashrrev_i32_e32 v113, 31, v112
	v_lshlrev_b64 v[112:113], 6, v[112:113]
	v_lshl_add_u64 v[124:125], s[6:7], 0, v[112:113]
	v_bfe_u32 v244, v124, 6, 8
	v_lshlrev_b32_e32 v244, 3, v244
	v_add_u32_e32 v244, 0x24010, v244
	v_or_b32_e32 v246, 3, v124
	ds_read_b64 v[248:249], v244
	s_waitcnt lgkmcnt(0)
	v_cmp_ne_u32_e64 s[100:101], v248, v246
	s_nop 1
	s_and_saveexec_b64 s[98:99], s[100:101]
	s_cbranch_execz .LrcE1_5
	global_load_dwordx4 v[112:115], v[124:125], off
	global_load_dwordx4 v[116:119], v[124:125], off offset:16
	global_load_dwordx4 v[120:123], v[124:125], off offset:32
	s_nop 0
	global_load_dwordx4 v[124:127], v[124:125], off offset:48
	s_waitcnt vmcnt(3)
	v_mov_b32_e32 v128, v113
	v_mov_b32_e32 v129, v114
	v_mov_b32_e32 v113, v115
	s_waitcnt vmcnt(2)
	v_mov_b32_e32 v114, v117
	v_mov_b32_e32 v115, v118
	v_mov_b32_e32 v117, v119
	v_pk_add_f32 v[112:113], v[128:129], v[112:113]
	v_pk_add_f32 v[114:115], v[114:115], v[116:117]
	v_pk_add_f32 v[112:113], v[112:113], v[112:113] op_sel:[0,1] op_sel_hi:[1,0]
	v_pk_add_f32 v[114:115], v[114:115], v[114:115] op_sel:[0,1] op_sel_hi:[1,0]
	s_waitcnt vmcnt(1)
	v_add_f32_e32 v116, v120, v121
	v_add_f32_e32 v118, v122, v123
	s_waitcnt vmcnt(0)
	v_mov_b32_e32 v113, v124
	v_mov_b32_e32 v115, v125
	v_mov_b32_e32 v117, v126
	v_mov_b32_e32 v119, v127
	v_pk_add_f32 v[112:113], v[112:113], v[114:115]
	v_pk_add_f32 v[114:115], v[116:117], v[118:119]
	s_nop 0
	v_pk_add_f32 v[112:113], v[112:113], v[114:115]
	s_nop 0
	v_add_f32_e32 v112, v112, v113
	v_fmamk_f32 v112, v112, 0x3a800000, v225
	v_mul_f32_e32 v113, 0x4b800000, v112
	v_cmp_gt_f32_e32 vcc, s45, v112
	s_nop 1
	s_nop 0
	v_cndmask_b32_e32 v112, v112, v113, vcc
	v_rsq_f32_e32 v112, v112
	s_nop 0
	v_mul_f32_e32 v113, 0x45800000, v112
	v_cndmask_b32_e32 v112, v112, v113, vcc
	s_nop 0
	v_mov_b32_e32 v247, v112
	ds_write_b64 v244, v[246:247]
; DI float sigmoidf_(float x) { return 1.f / (1.f + __expf(-x)); }
; DI float rstd_from16(const float* p, float inv_n) {
;   const f32x4 a = *(const f32x4*)p, b = *(const f32x4*)(p + 4), c = *(const f32x4*)(p + 8), d = *(const f32x4*)(p + 12);
;   const float s = ((a[0] + a[1]) + (a[2] + a[3])) + ((b[0] + b[1]) + (b[2] + b[3])) + ((c[0] + c[1]) + (c[2] + c[3])) + ((d[0] + d[1]) + (d[2] + d[3]));
;   return rsqrtf(s * inv_n + EPS_);
; DI void merge_tile(const Params& p, int layer, int tm, int tn, bf16_t* smem) {
;     ...
;         const float rs = rstd_from16((const float*)(p.ws + O_SSQ) + (size_t)(row0 + i * 16) * 16, 1.f / 1024.f);
; #pragma unroll
;         for (int j = 0; j < 2; ++j) {
;           unsigned w = 0;
; #pragma unroll
;           for (int r = 0; r < 4; ++r) w |= (unsigned)__float2int_rn(sigmoidf_(acc[i][j][r] * rs) * 255.f) << (8 * r);
;           gsp[(i * 2 + j) * NTHR] = w;
.LrcE1_5:
	s_or_b64 exec, exec, s[98:99]
	s_waitcnt vmcnt(0)
	v_cndmask_b32_e64 v112, v249, v112, s[100:101]
	v_mul_f32_e32 v108, v108, v112
	v_mul_f32_e32 v108, 0xbfb8aa3b, v108
	v_exp_f32_e32 v108, v108
	v_mul_f32_e32 v109, v109, v112
	v_mul_f32_e32 v109, 0xbfb8aa3b, v109
	v_exp_f32_e32 v109, v109
	v_add_f32_e32 v108, 1.0, v108
	v_add_f32_e32 v109, 1.0, v109
	v_mul_f32_e32 v110, v110, v112
	v_mul_f32_e32 v110, 0xbfb8aa3b, v110
	v_rcp_f32_e32 v108, v108
	v_exp_f32_e32 v110, v110
	v_mul_f32_e32 v111, v111, v112
	v_mul_f32_e32 v111, 0xbfb8aa3b, v111
	v_add_f32_e32 v110, 1.0, v110
	v_rcp_f32_e32 v109, v109
	v_exp_f32_e32 v111, v111
	v_mul_f32_e32 v104, v104, v112
	v_mul_f32_e32 v104, 0xbfb8aa3b, v104
	v_add_f32_e32 v111, 1.0, v111
	v_rcp_f32_e32 v110, v110
	v_exp_f32_e32 v104, v104
	v_mul_f32_e32 v105, v105, v112
	v_mul_f32_e32 v105, 0xbfb8aa3b, v105
	v_add_f32_e32 v104, 1.0, v104
	v_rcp_f32_e32 v111, v111
	v_exp_f32_e32 v105, v105
	v_mul_f32_e32 v106, v106, v112
	v_mul_f32_e32 v106, 0xbfb8aa3b, v106
	v_add_f32_e32 v105, 1.0, v105
	v_rcp_f32_e32 v104, v104
	v_exp_f32_e32 v106, v106
	v_mul_f32_e32 v107, v107, v112
	v_mul_f32_e32 v107, 0xbfb8aa3b, v107
	v_add_f32_e32 v106, 1.0, v106
	v_rcp_f32_e32 v105, v105
	v_exp_f32_e32 v107, v107
	v_mul_f32_e32 v108, 0x437f0000, v108
	v_mul_f32_e32 v109, 0x437f0000, v109
	v_add_f32_e32 v107, 1.0, v107
	v_rcp_f32_e32 v106, v106
	v_mul_f32_e32 v104, 0x437f0000, v104
	v_mul_f32_e32 v105, 0x437f0000, v105
	v_rndne_f32_e32 v108, v108
	v_rcp_f32_e32 v107, v107
	v_rndne_f32_e32 v109, v109
	v_mul_f32_e32 v110, 0x437f0000, v110
	v_mul_f32_e32 v111, 0x437f0000, v111
	v_rndne_f32_e32 v104, v104
	v_rndne_f32_e32 v105, v105
	v_mul_f32_e32 v106, 0x437f0000, v106
	v_mul_f32_e32 v107, 0x437f0000, v107
	v_cvt_i32_f32_e32 v108, v108
	v_cvt_i32_f32_e32 v109, v109
	v_rndne_f32_e32 v110, v110
	v_rndne_f32_e32 v111, v111
	v_cvt_i32_f32_e32 v104, v104
	v_cvt_i32_f32_e32 v105, v105
	v_rndne_f32_e32 v106, v106
	v_rndne_f32_e32 v107, v107
	v_cvt_i32_f32_sdwa v110, v110 dst_sel:WORD_1 dst_unused:UNUSED_PAD src0_sel:DWORD
	v_cvt_i32_f32_sdwa v111, v111 dst_sel:BYTE_3 dst_unused:UNUSED_PAD src0_sel:DWORD
	v_cvt_i32_f32_sdwa v106, v106 dst_sel:WORD_1 dst_unused:UNUSED_PAD src0_sel:DWORD
	v_cvt_i32_f32_sdwa v107, v107 dst_sel:BYTE_3 dst_unused:UNUSED_PAD src0_sel:DWORD
	v_lshl_or_b32 v108, v109, 8, v108
	v_lshl_or_b32 v104, v105, 8, v104
	v_or3_b32 v108, v108, v110, v111
	v_or3_b32 v104, v104, v106, v107
	ds_write2st64_b32 v228, v108, v104 offset0:80 offset1:88
	v_or_b32_e32 v104, 0x60, v152
	v_ashrrev_i32_e32 v105, 31, v104
	v_lshlrev_b64 v[104:105], 6, v[104:105]
	v_lshl_add_u64 v[116:117], s[6:7], 0, v[104:105]
	v_bfe_u32 v244, v116, 6, 8
	v_lshlrev_b32_e32 v244, 3, v244
	v_add_u32_e32 v244, 0x24010, v244
	v_or_b32_e32 v246, 3, v116
	ds_read_b64 v[248:249], v244
	s_waitcnt lgkmcnt(0)
	v_cmp_ne_u32_e64 s[100:101], v248, v246
	s_nop 1
	s_and_saveexec_b64 s[98:99], s[100:101]
	s_cbranch_execz .LrcE1_6
	global_load_dwordx4 v[104:107], v[116:117], off
	global_load_dwordx4 v[108:111], v[116:117], off offset:16
	global_load_dwordx4 v[112:115], v[116:117], off offset:32
	s_nop 0
	global_load_dwordx4 v[116:119], v[116:117], off offset:48
	s_waitcnt vmcnt(3)
	v_mov_b32_e32 v120, v105
	v_mov_b32_e32 v121, v106
	v_mov_b32_e32 v105, v107
	s_waitcnt vmcnt(2)
	v_mov_b32_e32 v106, v109
	v_mov_b32_e32 v107, v110
	v_mov_b32_e32 v109, v111
	v_pk_add_f32 v[104:105], v[120:121], v[104:105]
	v_pk_add_f32 v[106:107], v[106:107], v[108:109]
	v_pk_add_f32 v[104:105], v[104:105], v[104:105] op_sel:[0,1] op_sel_hi:[1,0]
	v_pk_add_f32 v[106:107], v[106:107], v[106:107] op_sel:[0,1] op_sel_hi:[1,0]
	s_waitcnt vmcnt(1)
	v_add_f32_e32 v108, v112, v113
	v_add_f32_e32 v110, v114, v115
	s_waitcnt vmcnt(0)
	v_mov_b32_e32 v105, v116
	v_mov_b32_e32 v107, v117
	v_mov_b32_e32 v109, v118
	v_mov_b32_e32 v111, v119
	v_pk_add_f32 v[104:105], v[104:105], v[106:107]
	v_pk_add_f32 v[106:107], v[108:109], v[110:111]
	s_nop 0
	v_pk_add_f32 v[104:105], v[104:105], v[106:107]
	s_nop 0
	v_add_f32_e32 v104, v104, v105
	v_fmamk_f32 v104, v104, 0x3a800000, v225
	v_mul_f32_e32 v105, 0x4b800000, v104
	v_cmp_gt_f32_e32 vcc, s45, v104
	s_nop 1
	s_nop 0
	v_cndmask_b32_e32 v104, v104, v105, vcc
	v_rsq_f32_e32 v104, v104
	s_nop 0
	v_mul_f32_e32 v105, 0x45800000, v104
	v_cndmask_b32_e32 v104, v104, v105, vcc
	s_nop 0
	v_mov_b32_e32 v247, v104
	ds_write_b64 v244, v[246:247]
; DI float sigmoidf_(float x) { return 1.f / (1.f + __expf(-x)); }
; DI float rstd_from16(const float* p, float inv_n) {
;   const f32x4 a = *(const f32x4*)p, b = *(const f32x4*)(p + 4), c = *(const f32x4*)(p + 8), d = *(const f32x4*)(p + 12);
;   const float s = ((a[0] + a[1]) + (a[2] + a[3])) + ((b[0] + b[1]) + (b[2] + b[3])) + ((c[0] + c[1]) + (c[2] + c[3])) + ((d[0] + d[1]) + (d[2] + d[3]));
;   return rsqrtf(s * inv_n + EPS_);
; DI void merge_tile(const Params& p, int layer, int tm, int tn, bf16_t* smem) {
;     ...
;         const float rs = rstd_from16((const float*)(p.ws + O_SSQ) + (size_t)(row0 + i * 16) * 16, 1.f / 1024.f);
; #pragma unroll
;         for (int j = 0; j < 2; ++j) {
;           unsigned w = 0;
; #pragma unroll
;           for (int r = 0; r < 4; ++r) w |= (unsigned)__float2int_rn(sigmoidf_(acc[i][j][r] * rs) * 255.f) << (8 * r);
;           gsp[(i * 2 + j) * NTHR] = w;
.LrcE1_6:
	s_or_b64 exec, exec, s[98:99]
	s_waitcnt vmcnt(0)
	v_cndmask_b32_e64 v104, v249, v104, s[100:101]
	v_mul_f32_e32 v100, v100, v104
	v_mul_f32_e32 v100, 0xbfb8aa3b, v100
	v_exp_f32_e32 v100, v100
	v_mul_f32_e32 v101, v101, v104
	v_mul_f32_e32 v101, 0xbfb8aa3b, v101
	v_exp_f32_e32 v101, v101
	v_add_f32_e32 v100, 1.0, v100
	v_add_f32_e32 v101, 1.0, v101
	v_mul_f32_e32 v102, v102, v104
	v_mul_f32_e32 v102, 0xbfb8aa3b, v102
	v_rcp_f32_e32 v100, v100
	v_exp_f32_e32 v102, v102
	v_mul_f32_e32 v103, v103, v104
	v_mul_f32_e32 v103, 0xbfb8aa3b, v103
	v_add_f32_e32 v102, 1.0, v102
	v_rcp_f32_e32 v101, v101
	v_exp_f32_e32 v103, v103
	v_mul_f32_e32 v96, v96, v104
	v_mul_f32_e32 v96, 0xbfb8aa3b, v96
	v_add_f32_e32 v103, 1.0, v103
	v_rcp_f32_e32 v102, v102
	v_exp_f32_e32 v96, v96
	v_mul_f32_e32 v97, v97, v104
	v_mul_f32_e32 v97, 0xbfb8aa3b, v97
	v_add_f32_e32 v96, 1.0, v96
	v_rcp_f32_e32 v103, v103
	v_exp_f32_e32 v97, v97
	v_mul_f32_e32 v98, v98, v104
	v_mul_f32_e32 v98, 0xbfb8aa3b, v98
	v_add_f32_e32 v97, 1.0, v97
	v_rcp_f32_e32 v96, v96
	v_exp_f32_e32 v98, v98
	v_mul_f32_e32 v99, v99, v104
	v_mul_f32_e32 v99, 0xbfb8aa3b, v99
	v_add_f32_e32 v98, 1.0, v98
	v_rcp_f32_e32 v97, v97
	v_exp_f32_e32 v99, v99
	v_mul_f32_e32 v100, 0x437f0000, v100
	v_mul_f32_e32 v101, 0x437f0000, v101
	v_add_f32_e32 v99, 1.0, v99
	v_rcp_f32_e32 v98, v98
	v_mul_f32_e32 v96, 0x437f0000, v96
	v_mul_f32_e32 v97, 0x437f0000, v97
	v_rndne_f32_e32 v100, v100
	v_rcp_f32_e32 v99, v99
	v_rndne_f32_e32 v101, v101
	v_mul_f32_e32 v102, 0x437f0000, v102
	v_mul_f32_e32 v103, 0x437f0000, v103
	v_rndne_f32_e32 v96, v96
	v_rndne_f32_e32 v97, v97
	v_mul_f32_e32 v98, 0x437f0000, v98
	v_mul_f32_e32 v99, 0x437f0000, v99
	v_cvt_i32_f32_e32 v100, v100
	v_cvt_i32_f32_e32 v101, v101
	v_rndne_f32_e32 v102, v102
	v_rndne_f32_e32 v103, v103
	v_cvt_i32_f32_e32 v96, v96
	v_cvt_i32_f32_e32 v97, v97
	v_rndne_f32_e32 v98, v98
	v_rndne_f32_e32 v99, v99
	v_cvt_i32_f32_sdwa v102, v102 dst_sel:WORD_1 dst_unused:UNUSED_PAD src0_sel:DWORD
	v_cvt_i32_f32_sdwa v103, v103 dst_sel:BYTE_3 dst_unused:UNUSED_PAD src0_sel:DWORD
	v_cvt_i32_f32_sdwa v98, v98 dst_sel:WORD_1 dst_unused:UNUSED_PAD src0_sel:DWORD
	v_cvt_i32_f32_sdwa v99, v99 dst_sel:BYTE_3 dst_unused:UNUSED_PAD src0_sel:DWORD
	v_lshl_or_b32 v100, v101, 8, v100
	v_lshl_or_b32 v96, v97, 8, v96
	v_or3_b32 v100, v100, v102, v103
	v_or3_b32 v96, v96, v98, v99
	ds_write2st64_b32 v228, v100, v96 offset0:96 offset1:104
	v_or_b32_e32 v96, 0x70, v152
	v_ashrrev_i32_e32 v97, 31, v96
	v_lshlrev_b64 v[96:97], 6, v[96:97]
	v_lshl_add_u64 v[108:109], s[6:7], 0, v[96:97]
	v_mov_b64_e32 v[154:155], v[86:87]
	v_mov_b64_e32 v[152:153], v[84:85]
	v_bfe_u32 v244, v108, 6, 8
	v_lshlrev_b32_e32 v244, 3, v244
	v_add_u32_e32 v244, 0x24010, v244
	v_or_b32_e32 v246, 3, v108
	ds_read_b64 v[248:249], v244
	s_waitcnt lgkmcnt(0)
	v_cmp_ne_u32_e64 s[100:101], v248, v246
	s_nop 1
	s_and_saveexec_b64 s[98:99], s[100:101]
	s_cbranch_execz .LrcE1_7
	global_load_dwordx4 v[96:99], v[108:109], off
	global_load_dwordx4 v[100:103], v[108:109], off offset:16
	global_load_dwordx4 v[104:107], v[108:109], off offset:32
	s_nop 0
	global_load_dwordx4 v[108:111], v[108:109], off offset:48
	s_waitcnt vmcnt(3)
	v_mov_b32_e32 v112, v97
	v_mov_b32_e32 v113, v98
	v_mov_b32_e32 v97, v99
	s_waitcnt vmcnt(2)
	v_mov_b32_e32 v98, v101
	v_mov_b32_e32 v99, v102
	v_mov_b32_e32 v101, v103
	v_pk_add_f32 v[96:97], v[112:113], v[96:97]
	v_pk_add_f32 v[98:99], v[98:99], v[100:101]
	v_pk_add_f32 v[96:97], v[96:97], v[96:97] op_sel:[0,1] op_sel_hi:[1,0]
	v_pk_add_f32 v[98:99], v[98:99], v[98:99] op_sel:[0,1] op_sel_hi:[1,0]
	s_waitcnt vmcnt(1)
	v_add_f32_e32 v100, v104, v105
	v_add_f32_e32 v102, v106, v107
	s_waitcnt vmcnt(0)
	v_mov_b32_e32 v97, v108
	v_mov_b32_e32 v99, v109
	v_mov_b32_e32 v101, v110
	v_mov_b32_e32 v103, v111
	v_pk_add_f32 v[96:97], v[96:97], v[98:99]
	v_pk_add_f32 v[98:99], v[100:101], v[102:103]
	s_nop 0
	v_pk_add_f32 v[96:97], v[96:97], v[98:99]
	s_nop 0
	v_add_f32_e32 v96, v96, v97
	v_fmamk_f32 v96, v96, 0x3a800000, v225
	v_mul_f32_e32 v97, 0x4b800000, v96
	v_cmp_gt_f32_e32 vcc, s45, v96
	s_nop 1
	s_nop 0
	v_cndmask_b32_e32 v96, v96, v97, vcc
	v_rsq_f32_e32 v96, v96
	s_nop 0
	v_mul_f32_e32 v97, 0x45800000, v96
	v_cndmask_b32_e32 v96, v96, v97, vcc
	s_nop 0
	v_mov_b32_e32 v247, v96
	ds_write_b64 v244, v[246:247]

; DI float rstd_from16(const float* p, float inv_n) {
;   const f32x4 a = *(const f32x4*)p, b = *(const f32x4*)(p + 4), c = *(const f32x4*)(p + 8), d = *(const f32x4*)(p + 12);
;   const float s = ((a[0] + a[1]) + (a[2] + a[3])) + ((b[0] + b[1]) + (b[2] + b[3])) + ((c[0] + c[1]) + (c[2] + c[3])) + ((d[0] + d[1]) + (d[2] + d[3]));
;   return rsqrtf(s * inv_n + EPS_);
; DI void ffnup_tile(const Params& p, int layer, int b, int mt, int tn, bf16_t* smem) {
;     ...
;     bf16_t* dstb = (wn < 2 ? U : V) + (wn & 1) * 64 + quad * 4;
; #pragma unroll
;     for (int i = 0; i < 8; ++i) {
;       const int row = wm * 128 + i * 16 + l15, s = s0 + row;
;       const float rs = (s >= 0 && s < S_) ? rstd_from16((const float*)(p.ws + O_SSQ) + ((size_t)b * S_ + s) * 16, 1.f / 1024.f) : 0.f;
.Lgm14_exit:
	v_mfma_f32_16x16x32_bf16 v[28:31], v[182:185], v[242:245], v[28:31]
	v_mfma_f32_16x16x32_bf16 v[8:11], v[182:185], v[246:249], v[8:11]
	v_mfma_f32_16x16x32_bf16 v[24:27], v[186:189], v[242:245], v[24:27]
	v_mfma_f32_16x16x32_bf16 v[4:7], v[186:189], v[246:249], v[4:7]
	v_mfma_f32_16x16x32_bf16 v[20:23], v[190:193], v[242:245], v[20:23]
	v_mfma_f32_16x16x32_bf16 v[0:3], v[190:193], v[246:249], v[0:3]
	v_mfma_f32_16x16x32_bf16 v[12:15], v[194:197], v[242:245], v[12:15]
	v_mfma_f32_16x16x32_bf16 v[16:19], v[194:197], v[246:249], v[16:19]
	s_nop 7
	s_waitcnt vmcnt(5)
	v_mov_b32_e32 v115, v220
	s_lshl_b64 s[2:3], s[16:17], 12
	v_and_b32_e32 v113, 15, v115
	v_ashrrev_i32_e32 v112, 1, v115
	s_waitcnt vmcnt(3)
	v_and_or_b32 v118, v112, s33, v113
	v_add_u32_e32 v117, s42, v118
	v_cmp_gt_u32_e32 vcc, s28, v117
	v_mov_b32_e32 v112, 0
	v_mov_b32_e32 v114, 0
	s_and_saveexec_b64 s[0:1], vcc
	s_cbranch_execz .LBB0_2086
	s_waitcnt vmcnt(2)
	v_or_b32_e32 v120, s2, v117
	v_mov_b32_e32 v121, s3
	v_lshlrev_b64 v[120:121], 6, v[120:121]
	v_lshl_add_u64 v[132:133], s[6:7], 0, v[120:121]
	v_bfe_u32 v244, v132, 6, 8
	v_lshlrev_b32_e32 v244, 3, v244
	v_add_u32_e32 v244, 0x24010, v244
	v_or_b32_e32 v246, 4, v132
	ds_read_b64 v[248:249], v244
	s_waitcnt lgkmcnt(0)
	v_cmp_ne_u32_e64 s[100:101], v248, v246
	s_nop 1
	s_and_saveexec_b64 s[98:99], s[100:101]
	s_cbranch_execz .LrcG1_0
	global_load_dwordx4 v[120:123], v[132:133], off
	global_load_dwordx4 v[124:127], v[132:133], off offset:16
	global_load_dwordx4 v[128:131], v[132:133], off offset:32
	s_nop 0
	global_load_dwordx4 v[132:135], v[132:133], off offset:48
	s_waitcnt vmcnt(3)
	v_mov_b32_e32 v136, v121
	v_mov_b32_e32 v137, v122
	v_mov_b32_e32 v121, v123
	s_waitcnt vmcnt(2)
	v_mov_b32_e32 v122, v125
	v_mov_b32_e32 v123, v126
	v_mov_b32_e32 v125, v127
	v_pk_add_f32 v[120:121], v[136:137], v[120:121]
	v_pk_add_f32 v[122:123], v[122:123], v[124:125]
	v_pk_add_f32 v[120:121], v[120:121], v[120:121] op_sel:[0,1] op_sel_hi:[1,0]
	v_pk_add_f32 v[122:123], v[122:123], v[122:123] op_sel:[0,1] op_sel_hi:[1,0]
	s_waitcnt vmcnt(1)
	v_add_f32_e32 v126, v128, v129
	v_add_f32_e32 v128, v130, v131
	s_waitcnt vmcnt(0)
	v_mov_b32_e32 v127, v134
	v_mov_b32_e32 v129, v135
	v_mov_b32_e32 v121, v132
	v_mov_b32_e32 v123, v133
	v_pk_add_f32 v[124:125], v[126:127], v[128:129]
	v_pk_add_f32 v[120:121], v[120:121], v[122:123]
	s_nop 0
	v_pk_add_f32 v[120:121], v[120:121], v[124:125]
	s_nop 0
	v_add_f32_e32 v114, v120, v121
	v_fmamk_f32 v114, v114, 0x3a800000, v168
	v_mul_f32_e32 v116, 0x4b800000, v114
	v_cmp_gt_f32_e32 vcc, s34, v114
	s_nop 1
	s_nop 0
	v_cndmask_b32_e32 v114, v114, v116, vcc
	v_rsq_f32_e32 v114, v114
	s_nop 0
	v_mul_f32_e32 v116, 0x45800000, v114
	v_cndmask_b32_e32 v114, v114, v116, vcc
	s_nop 0
	v_mov_b32_e32 v247, v114
	ds_write_b64 v244, v[246:247]

; DI void store4(bf16_t* dst, const f32x4& v, float s) { *(u32x2*)dst = (u32x2){pk2(v[0] * s, v[1] * s), pk2(v[2] * s, v[3] * s)}; }
; DI float rstd_from16(const float* p, float inv_n) {
;   const f32x4 a = *(const f32x4*)p, b = *(const f32x4*)(p + 4), c = *(const f32x4*)(p + 8), d = *(const f32x4*)(p + 12);
;   const float s = ((a[0] + a[1]) + (a[2] + a[3])) + ((b[0] + b[1]) + (b[2] + b[3])) + ((c[0] + c[1]) + (c[2] + c[3])) + ((d[0] + d[1]) + (d[2] + d[3]));
;   return rsqrtf(s * inv_n + EPS_);
; DI void ffnup_tile(const Params& p, int layer, int b, int mt, int tn, bf16_t* smem) {
;     ...
;     for (int i = 0; i < 8; ++i) {
;       const int row = wm * 128 + i * 16 + l15, s = s0 + row;
;       const float rs = (s >= 0 && s < S_) ? rstd_from16((const float*)(p.ws + O_SSQ) + ((size_t)b * S_ + s) * 16, 1.f / 1024.f) : 0.f;
; #pragma unroll
;       for (int j = 0; j < 4; ++j) store4(dstb + row * LDU + j * 16, acc[i][j], rs);
.LBB0_2086:
	s_or_b64 exec, exec, s[0:1]
	v_bfe_i32 v116, v115, 7, 1
	v_and_b32_e32 v119, 64, v115
	s_waitcnt vmcnt(2)
	v_lshrrev_b32_e32 v120, 1, v115
	v_and_b32_e32 v116, 0x11000, v116
	v_lshlrev_b32_e32 v119, 1, v119
	v_and_b32_e32 v120, 24, v120
	v_or3_b32 v116, v116, v119, v120
	v_pk_mul_f32 v[120:121], v[156:157], v[114:115] op_sel_hi:[1,0]
	v_pk_mul_f32 v[122:123], v[158:159], v[114:115] op_sel_hi:[1,0]
	v_mul_lo_u32 v119, v118, s35
	v_cvt_pk_bf16_f32 v120, v120, v121
	v_cvt_pk_bf16_f32 v121, v122, v123
	v_pk_mul_f32 v[122:123], v[152:153], v[114:115] op_sel_hi:[1,0]
	s_waitcnt vmcnt(1)
	v_pk_mul_f32 v[124:125], v[154:155], v[114:115] op_sel_hi:[1,0]
	v_add_u32_e32 v116, v116, v119
	v_cvt_pk_bf16_f32 v122, v122, v123
	v_cvt_pk_bf16_f32 v123, v124, v125
	ds_write2_b64 v116, v[120:121], v[122:123] offset1:4
	v_pk_mul_f32 v[120:121], v[148:149], v[114:115] op_sel_hi:[1,0]
	v_pk_mul_f32 v[122:123], v[150:151], v[114:115] op_sel_hi:[1,0]
	v_cvt_pk_bf16_f32 v120, v120, v121
	v_cvt_pk_bf16_f32 v121, v122, v123
	v_pk_mul_f32 v[122:123], v[144:145], v[114:115] op_sel_hi:[1,0]
	v_pk_mul_f32 v[124:125], v[146:147], v[114:115] op_sel_hi:[1,0]
	v_add3_u32 v114, s42, v118, 16
	v_cvt_pk_bf16_f32 v122, v122, v123
	v_cvt_pk_bf16_f32 v123, v124, v125
	v_cmp_gt_u32_e32 vcc, s28, v114
	ds_write2_b64 v116, v[120:121], v[122:123] offset0:8 offset1:12
	s_and_saveexec_b64 s[0:1], vcc
	s_cbranch_execz .LBB0_2088
	v_or_b32_e32 v120, s2, v114
	v_mov_b32_e32 v121, s3
	v_lshlrev_b64 v[120:121], 6, v[120:121]
	v_lshl_add_u64 v[132:133], s[6:7], 0, v[120:121]
	v_bfe_u32 v244, v132, 6, 8
	v_lshlrev_b32_e32 v244, 3, v244
	v_add_u32_e32 v244, 0x24010, v244
	v_or_b32_e32 v246, 4, v132
	ds_read_b64 v[248:249], v244
	s_waitcnt lgkmcnt(0)
	v_cmp_ne_u32_e64 s[100:101], v248, v246
	s_nop 1
	s_and_saveexec_b64 s[98:99], s[100:101]
	s_cbranch_execz .LrcG1_1
	global_load_dwordx4 v[120:123], v[132:133], off
	global_load_dwordx4 v[124:127], v[132:133], off offset:16
	global_load_dwordx4 v[128:131], v[132:133], off offset:32
	s_nop 0
	global_load_dwordx4 v[132:135], v[132:133], off offset:48
	s_waitcnt vmcnt(3)
	v_mov_b32_e32 v136, v121
	v_mov_b32_e32 v137, v122
	v_mov_b32_e32 v121, v123
	s_waitcnt vmcnt(2)
	v_mov_b32_e32 v122, v125
	v_mov_b32_e32 v123, v126
	v_mov_b32_e32 v125, v127
	v_pk_add_f32 v[120:121], v[136:137], v[120:121]
	v_pk_add_f32 v[122:123], v[122:123], v[124:125]
	v_pk_add_f32 v[120:121], v[120:121], v[120:121] op_sel:[0,1] op_sel_hi:[1,0]
	v_pk_add_f32 v[122:123], v[122:123], v[122:123] op_sel:[0,1] op_sel_hi:[1,0]
	s_waitcnt vmcnt(1)
	v_add_f32_e32 v126, v128, v129
	v_add_f32_e32 v128, v130, v131
	s_waitcnt vmcnt(0)
	v_mov_b32_e32 v127, v134
	v_mov_b32_e32 v129, v135
	v_mov_b32_e32 v121, v132
	v_mov_b32_e32 v123, v133
	v_pk_add_f32 v[124:125], v[126:127], v[128:129]
	v_pk_add_f32 v[120:121], v[120:121], v[122:123]
	s_nop 0
	v_pk_add_f32 v[120:121], v[120:121], v[124:125]
	s_nop 0
	v_add_f32_e32 v112, v120, v121
	v_fmamk_f32 v112, v112, 0x3a800000, v168
	v_mul_f32_e32 v114, 0x4b800000, v112
	v_cmp_gt_f32_e32 vcc, s34, v112
	s_nop 1
	s_nop 0
	v_cndmask_b32_e32 v112, v112, v114, vcc
	v_rsq_f32_e32 v112, v112
	s_nop 0
	v_mul_f32_e32 v114, 0x45800000, v112
	v_cndmask_b32_e32 v112, v112, v114, vcc
	s_nop 0
	v_mov_b32_e32 v247, v112
	ds_write_b64 v244, v[246:247]

; DI void store4(bf16_t* dst, const f32x4& v, float s) { *(u32x2*)dst = (u32x2){pk2(v[0] * s, v[1] * s), pk2(v[2] * s, v[3] * s)}; }
; DI float rstd_from16(const float* p, float inv_n) {
;   const f32x4 a = *(const f32x4*)p, b = *(const f32x4*)(p + 4), c = *(const f32x4*)(p + 8), d = *(const f32x4*)(p + 12);
;   const float s = ((a[0] + a[1]) + (a[2] + a[3])) + ((b[0] + b[1]) + (b[2] + b[3])) + ((c[0] + c[1]) + (c[2] + c[3])) + ((d[0] + d[1]) + (d[2] + d[3]));
;   return rsqrtf(s * inv_n + EPS_);
; DI void ffnup_tile(const Params& p, int layer, int b, int mt, int tn, bf16_t* smem) {
;     ...
;     for (int i = 0; i < 8; ++i) {
;       const int row = wm * 128 + i * 16 + l15, s = s0 + row;
;       const float rs = (s >= 0 && s < S_) ? rstd_from16((const float*)(p.ws + O_SSQ) + ((size_t)b * S_ + s) * 16, 1.f / 1024.f) : 0.f;
; #pragma unroll
;       for (int j = 0; j < 4; ++j) store4(dstb + row * LDU + j * 16, acc[i][j], rs);
.LBB0_2088:
	s_or_b64 exec, exec, s[0:1]
	v_pk_mul_f32 v[104:105], v[104:105], v[112:113] op_sel_hi:[1,0]
	v_pk_mul_f32 v[106:107], v[106:107], v[112:113] op_sel_hi:[1,0]
	v_pk_mul_f32 v[100:101], v[100:101], v[112:113] op_sel_hi:[1,0]
	v_pk_mul_f32 v[102:103], v[102:103], v[112:113] op_sel_hi:[1,0]
	v_pk_mul_f32 v[96:97], v[96:97], v[112:113] op_sel_hi:[1,0]
	v_pk_mul_f32 v[98:99], v[98:99], v[112:113] op_sel_hi:[1,0]
	v_cvt_pk_bf16_f32 v104, v104, v105
	v_cvt_pk_bf16_f32 v105, v106, v107
	v_add_u32_e32 v106, 0x1000, v116
	v_cvt_pk_bf16_f32 v100, v100, v101
	v_cvt_pk_bf16_f32 v101, v102, v103
	v_cvt_pk_bf16_f32 v96, v96, v97
	v_cvt_pk_bf16_f32 v97, v98, v99
	v_pk_mul_f32 v[108:109], v[108:109], v[112:113] op_sel_hi:[1,0]
	v_pk_mul_f32 v[110:111], v[110:111], v[112:113] op_sel_hi:[1,0]
	ds_write2_b64 v106, v[100:101], v[96:97] offset0:40 offset1:44
	v_add3_u32 v97, s42, v118, 32
	v_cvt_pk_bf16_f32 v108, v108, v109
	v_cvt_pk_bf16_f32 v109, v110, v111
	v_cmp_gt_u32_e32 vcc, s28, v97
	v_mov_b32_e32 v96, 0
	v_mov_b32_e32 v98, 0
	ds_write2_b64 v106, v[108:109], v[104:105] offset0:32 offset1:36
	s_and_saveexec_b64 s[0:1], vcc
	s_cbranch_execz .LBB0_2090
	v_or_b32_e32 v98, s2, v97
	v_mov_b32_e32 v99, s3
	v_lshlrev_b64 v[98:99], 6, v[98:99]
	v_lshl_add_u64 v[110:111], s[6:7], 0, v[98:99]
	v_bfe_u32 v244, v110, 6, 8
	v_lshlrev_b32_e32 v244, 3, v244
	v_add_u32_e32 v244, 0x24010, v244
	v_or_b32_e32 v246, 4, v110
	ds_read_b64 v[248:249], v244
	s_waitcnt lgkmcnt(0)
	v_cmp_ne_u32_e64 s[100:101], v248, v246
	s_nop 1
	s_and_saveexec_b64 s[98:99], s[100:101]
	s_cbranch_execz .LrcG1_2
	global_load_dwordx4 v[98:101], v[110:111], off
	global_load_dwordx4 v[102:105], v[110:111], off offset:16
	global_load_dwordx4 v[106:109], v[110:111], off offset:32
	global_load_dwordx4 v[120:123], v[110:111], off offset:48
	s_waitcnt vmcnt(3)
	v_mov_b32_e32 v110, v99
	v_mov_b32_e32 v111, v100
	v_mov_b32_e32 v99, v101
	s_waitcnt vmcnt(2)
	v_mov_b32_e32 v100, v103
	v_mov_b32_e32 v101, v104
	v_mov_b32_e32 v103, v105
	v_pk_add_f32 v[98:99], v[110:111], v[98:99]
	v_pk_add_f32 v[100:101], v[100:101], v[102:103]
	v_pk_add_f32 v[98:99], v[98:99], v[98:99] op_sel:[0,1] op_sel_hi:[1,0]
	v_pk_add_f32 v[100:101], v[100:101], v[100:101] op_sel:[0,1] op_sel_hi:[1,0]
	s_waitcnt vmcnt(1)
	v_add_f32_e32 v104, v106, v107
	v_add_f32_e32 v106, v108, v109
	s_waitcnt vmcnt(0)
	v_mov_b32_e32 v105, v122
	v_mov_b32_e32 v107, v123
	v_mov_b32_e32 v99, v120
	v_mov_b32_e32 v101, v121
	v_pk_add_f32 v[102:103], v[104:105], v[106:107]
	v_pk_add_f32 v[98:99], v[98:99], v[100:101]
	s_nop 0
	v_pk_add_f32 v[98:99], v[98:99], v[102:103]
	s_nop 0
	v_add_f32_e32 v97, v98, v99
	v_fmamk_f32 v97, v97, 0x3a800000, v168
	v_mul_f32_e32 v98, 0x4b800000, v97
	v_cmp_gt_f32_e32 vcc, s34, v97
	s_nop 1
	s_nop 0
	v_cndmask_b32_e32 v97, v97, v98, vcc
	v_rsq_f32_e32 v97, v97
	s_nop 0
	v_mul_f32_e32 v98, 0x45800000, v97
	v_cndmask_b32_e32 v98, v97, v98, vcc
	s_nop 0
	v_mov_b32_e32 v247, v98
	ds_write_b64 v244, v[246:247]

; DI void store4(bf16_t* dst, const f32x4& v, float s) { *(u32x2*)dst = (u32x2){pk2(v[0] * s, v[1] * s), pk2(v[2] * s, v[3] * s)}; }
; DI float rstd_from16(const float* p, float inv_n) {
;   const f32x4 a = *(const f32x4*)p, b = *(const f32x4*)(p + 4), c = *(const f32x4*)(p + 8), d = *(const f32x4*)(p + 12);
;   const float s = ((a[0] + a[1]) + (a[2] + a[3])) + ((b[0] + b[1]) + (b[2] + b[3])) + ((c[0] + c[1]) + (c[2] + c[3])) + ((d[0] + d[1]) + (d[2] + d[3]));
;   return rsqrtf(s * inv_n + EPS_);
; DI void ffnup_tile(const Params& p, int layer, int b, int mt, int tn, bf16_t* smem) {
;     ...
;     for (int i = 0; i < 8; ++i) {
;       const int row = wm * 128 + i * 16 + l15, s = s0 + row;
;       const float rs = (s >= 0 && s < S_) ? rstd_from16((const float*)(p.ws + O_SSQ) + ((size_t)b * S_ + s) * 16, 1.f / 1024.f) : 0.f;
; #pragma unroll
;       for (int j = 0; j < 4; ++j) store4(dstb + row * LDU + j * 16, acc[i][j], rs);
.LBB0_2090:
	s_or_b64 exec, exec, s[0:1]
	v_pk_mul_f32 v[88:89], v[88:89], v[98:99] op_sel_hi:[1,0]
	v_pk_mul_f32 v[90:91], v[90:91], v[98:99] op_sel_hi:[1,0]
	v_pk_mul_f32 v[84:85], v[84:85], v[98:99] op_sel_hi:[1,0]
	v_pk_mul_f32 v[86:87], v[86:87], v[98:99] op_sel_hi:[1,0]
	v_pk_mul_f32 v[80:81], v[80:81], v[98:99] op_sel_hi:[1,0]
	v_pk_mul_f32 v[82:83], v[82:83], v[98:99] op_sel_hi:[1,0]
	v_cvt_pk_bf16_f32 v88, v88, v89
	v_cvt_pk_bf16_f32 v89, v90, v91
	v_add_u32_e32 v90, 0x2000, v116
	v_cvt_pk_bf16_f32 v84, v84, v85
	v_cvt_pk_bf16_f32 v85, v86, v87
	v_cvt_pk_bf16_f32 v80, v80, v81
	v_cvt_pk_bf16_f32 v81, v82, v83
	v_pk_mul_f32 v[92:93], v[92:93], v[98:99] op_sel_hi:[1,0]
	v_pk_mul_f32 v[94:95], v[94:95], v[98:99] op_sel_hi:[1,0]
	ds_write2_b64 v90, v[84:85], v[80:81] offset0:72 offset1:76
	v_add3_u32 v80, s42, v118, 48
	v_cvt_pk_bf16_f32 v92, v92, v93
	v_cvt_pk_bf16_f32 v93, v94, v95
	v_cmp_gt_u32_e32 vcc, s28, v80
	ds_write2_b64 v90, v[92:93], v[88:89] offset0:64 offset1:68
	s_and_saveexec_b64 s[0:1], vcc
	s_cbranch_execz .LBB0_2092
	v_or_b32_e32 v80, s2, v80
	v_mov_b32_e32 v81, s3
	v_lshlrev_b64 v[80:81], 6, v[80:81]
	v_lshl_add_u64 v[92:93], s[6:7], 0, v[80:81]
	v_bfe_u32 v244, v92, 6, 8
	v_lshlrev_b32_e32 v244, 3, v244
	v_add_u32_e32 v244, 0x24010, v244
	v_or_b32_e32 v246, 4, v92
	ds_read_b64 v[248:249], v244
	s_waitcnt lgkmcnt(0)
	v_cmp_ne_u32_e64 s[100:101], v248, v246
	s_nop 1
	s_and_saveexec_b64 s[98:99], s[100:101]
	s_cbranch_execz .LrcG1_3
	global_load_dwordx4 v[80:83], v[92:93], off
	global_load_dwordx4 v[84:87], v[92:93], off offset:16
	global_load_dwordx4 v[88:91], v[92:93], off offset:32
	s_nop 0
	global_load_dwordx4 v[92:95], v[92:93], off offset:48
	s_waitcnt vmcnt(3)
	v_mov_b32_e32 v96, v81
	v_mov_b32_e32 v97, v82
	v_mov_b32_e32 v81, v83
	s_waitcnt vmcnt(2)
	v_mov_b32_e32 v82, v85
	v_mov_b32_e32 v83, v86
	v_mov_b32_e32 v85, v87
	v_pk_add_f32 v[80:81], v[96:97], v[80:81]
	v_pk_add_f32 v[82:83], v[82:83], v[84:85]
	v_pk_add_f32 v[80:81], v[80:81], v[80:81] op_sel:[0,1] op_sel_hi:[1,0]
	v_pk_add_f32 v[82:83], v[82:83], v[82:83] op_sel:[0,1] op_sel_hi:[1,0]
	s_waitcnt vmcnt(1)
	v_add_f32_e32 v86, v88, v89
	v_add_f32_e32 v88, v90, v91
	s_waitcnt vmcnt(0)
	v_mov_b32_e32 v87, v94
	v_mov_b32_e32 v89, v95
	v_mov_b32_e32 v81, v92
	v_mov_b32_e32 v83, v93
	v_pk_add_f32 v[84:85], v[86:87], v[88:89]
	v_pk_add_f32 v[80:81], v[80:81], v[82:83]
	s_nop 0
	v_pk_add_f32 v[80:81], v[80:81], v[84:85]
	s_nop 0
	v_add_f32_e32 v80, v80, v81
	v_fmamk_f32 v80, v80, 0x3a800000, v168
	v_mul_f32_e32 v81, 0x4b800000, v80
	v_cmp_gt_f32_e32 vcc, s34, v80
	s_nop 1
	s_nop 0
	v_cndmask_b32_e32 v80, v80, v81, vcc
	v_rsq_f32_e32 v80, v80
	s_nop 0
	v_mul_f32_e32 v81, 0x45800000, v80
	v_cndmask_b32_e32 v96, v80, v81, vcc
	s_nop 0
	v_mov_b32_e32 v247, v96
	ds_write_b64 v244, v[246:247]

; DI void store4(bf16_t* dst, const f32x4& v, float s) { *(u32x2*)dst = (u32x2){pk2(v[0] * s, v[1] * s), pk2(v[2] * s, v[3] * s)}; }
; DI float rstd_from16(const float* p, float inv_n) {
;   const f32x4 a = *(const f32x4*)p, b = *(const f32x4*)(p + 4), c = *(const f32x4*)(p + 8), d = *(const f32x4*)(p + 12);
;   const float s = ((a[0] + a[1]) + (a[2] + a[3])) + ((b[0] + b[1]) + (b[2] + b[3])) + ((c[0] + c[1]) + (c[2] + c[3])) + ((d[0] + d[1]) + (d[2] + d[3]));
;   return rsqrtf(s * inv_n + EPS_);
; DI void ffnup_tile(const Params& p, int layer, int b, int mt, int tn, bf16_t* smem) {
;     ...
;     for (int i = 0; i < 8; ++i) {
;       const int row = wm * 128 + i * 16 + l15, s = s0 + row;
;       const float rs = (s >= 0 && s < S_) ? rstd_from16((const float*)(p.ws + O_SSQ) + ((size_t)b * S_ + s) * 16, 1.f / 1024.f) : 0.f;
; #pragma unroll
;       for (int j = 0; j < 4; ++j) store4(dstb + row * LDU + j * 16, acc[i][j], rs);
.LBB0_2092:
	s_or_b64 exec, exec, s[0:1]
	v_pk_mul_f32 v[72:73], v[72:73], v[96:97] op_sel_hi:[1,0]
	v_pk_mul_f32 v[74:75], v[74:75], v[96:97] op_sel_hi:[1,0]
	v_pk_mul_f32 v[68:69], v[68:69], v[96:97] op_sel_hi:[1,0]
	v_pk_mul_f32 v[70:71], v[70:71], v[96:97] op_sel_hi:[1,0]
	v_pk_mul_f32 v[64:65], v[64:65], v[96:97] op_sel_hi:[1,0]
	v_pk_mul_f32 v[66:67], v[66:67], v[96:97] op_sel_hi:[1,0]
	v_cvt_pk_bf16_f32 v72, v72, v73
	v_cvt_pk_bf16_f32 v73, v74, v75
	v_add_u32_e32 v74, 0x3000, v116
	v_cvt_pk_bf16_f32 v68, v68, v69
	v_cvt_pk_bf16_f32 v69, v70, v71
	v_cvt_pk_bf16_f32 v64, v64, v65
	v_cvt_pk_bf16_f32 v65, v66, v67
	v_pk_mul_f32 v[76:77], v[76:77], v[96:97] op_sel_hi:[1,0]
	v_pk_mul_f32 v[78:79], v[78:79], v[96:97] op_sel_hi:[1,0]
	ds_write2_b64 v74, v[68:69], v[64:65] offset0:104 offset1:108
	v_add3_u32 v65, s42, v118, 64
	v_cvt_pk_bf16_f32 v76, v76, v77
	v_cvt_pk_bf16_f32 v77, v78, v79
	v_cmp_gt_u32_e32 vcc, s28, v65
	v_mov_b32_e32 v64, 0
	v_mov_b32_e32 v66, 0
	ds_write2_b64 v74, v[76:77], v[72:73] offset0:96 offset1:100
	s_and_saveexec_b64 s[0:1], vcc
	s_cbranch_execz .LBB0_2094
	v_or_b32_e32 v66, s2, v65
	v_mov_b32_e32 v67, s3
	v_lshlrev_b64 v[66:67], 6, v[66:67]
	v_lshl_add_u64 v[78:79], s[6:7], 0, v[66:67]
	v_bfe_u32 v244, v78, 6, 8
	v_lshlrev_b32_e32 v244, 3, v244
	v_add_u32_e32 v244, 0x24010, v244
	v_or_b32_e32 v246, 4, v78
	ds_read_b64 v[248:249], v244
	s_waitcnt lgkmcnt(0)
	v_cmp_ne_u32_e64 s[100:101], v248, v246
	s_nop 1
	s_and_saveexec_b64 s[98:99], s[100:101]
	s_cbranch_execz .LrcG1_4
	global_load_dwordx4 v[66:69], v[78:79], off
	global_load_dwordx4 v[70:73], v[78:79], off offset:16
	global_load_dwordx4 v[74:77], v[78:79], off offset:32
	s_nop 0
	global_load_dwordx4 v[78:81], v[78:79], off offset:48
	s_waitcnt vmcnt(3)
	v_mov_b32_e32 v82, v67
	v_mov_b32_e32 v83, v68
	v_mov_b32_e32 v67, v69
	s_waitcnt vmcnt(2)
	v_mov_b32_e32 v68, v71
	v_mov_b32_e32 v69, v72
	v_mov_b32_e32 v71, v73
	v_pk_add_f32 v[66:67], v[82:83], v[66:67]
	v_pk_add_f32 v[68:69], v[68:69], v[70:71]
	v_pk_add_f32 v[66:67], v[66:67], v[66:67] op_sel:[0,1] op_sel_hi:[1,0]
	v_pk_add_f32 v[68:69], v[68:69], v[68:69] op_sel:[0,1] op_sel_hi:[1,0]
	s_waitcnt vmcnt(1)
	v_add_f32_e32 v72, v74, v75
	v_add_f32_e32 v74, v76, v77
	s_waitcnt vmcnt(0)
	v_mov_b32_e32 v73, v80
	v_mov_b32_e32 v75, v81
	v_mov_b32_e32 v67, v78
	v_mov_b32_e32 v69, v79
	v_pk_add_f32 v[70:71], v[72:73], v[74:75]
	v_pk_add_f32 v[66:67], v[66:67], v[68:69]
	s_nop 0
	v_pk_add_f32 v[66:67], v[66:67], v[70:71]
	s_nop 0
	v_add_f32_e32 v65, v66, v67
	v_fmamk_f32 v65, v65, 0x3a800000, v168
	v_mul_f32_e32 v66, 0x4b800000, v65
	v_cmp_gt_f32_e32 vcc, s34, v65
	s_nop 1
	s_nop 0
	v_cndmask_b32_e32 v65, v65, v66, vcc
	v_rsq_f32_e32 v65, v65
	s_nop 0
	v_mul_f32_e32 v66, 0x45800000, v65
	v_cndmask_b32_e32 v66, v65, v66, vcc
	s_nop 0
	v_mov_b32_e32 v247, v66
	ds_write_b64 v244, v[246:247]

; DI void store4(bf16_t* dst, const f32x4& v, float s) { *(u32x2*)dst = (u32x2){pk2(v[0] * s, v[1] * s), pk2(v[2] * s, v[3] * s)}; }
; DI float rstd_from16(const float* p, float inv_n) {
;   const f32x4 a = *(const f32x4*)p, b = *(const f32x4*)(p + 4), c = *(const f32x4*)(p + 8), d = *(const f32x4*)(p + 12);
;   const float s = ((a[0] + a[1]) + (a[2] + a[3])) + ((b[0] + b[1]) + (b[2] + b[3])) + ((c[0] + c[1]) + (c[2] + c[3])) + ((d[0] + d[1]) + (d[2] + d[3]));
;   return rsqrtf(s * inv_n + EPS_);
; DI void ffnup_tile(const Params& p, int layer, int b, int mt, int tn, bf16_t* smem) {
;     ...
;     for (int i = 0; i < 8; ++i) {
;       const int row = wm * 128 + i * 16 + l15, s = s0 + row;
;       const float rs = (s >= 0 && s < S_) ? rstd_from16((const float*)(p.ws + O_SSQ) + ((size_t)b * S_ + s) * 16, 1.f / 1024.f) : 0.f;
; #pragma unroll
;       for (int j = 0; j < 4; ++j) store4(dstb + row * LDU + j * 16, acc[i][j], rs);
.LBB0_2094:
	s_or_b64 exec, exec, s[0:1]
	v_pk_mul_f32 v[56:57], v[56:57], v[66:67] op_sel_hi:[1,0]
	v_pk_mul_f32 v[58:59], v[58:59], v[66:67] op_sel_hi:[1,0]
	v_pk_mul_f32 v[52:53], v[52:53], v[66:67] op_sel_hi:[1,0]
	v_pk_mul_f32 v[54:55], v[54:55], v[66:67] op_sel_hi:[1,0]
	v_pk_mul_f32 v[48:49], v[48:49], v[66:67] op_sel_hi:[1,0]
	v_pk_mul_f32 v[50:51], v[50:51], v[66:67] op_sel_hi:[1,0]
	v_cvt_pk_bf16_f32 v56, v56, v57
	v_cvt_pk_bf16_f32 v57, v58, v59
	v_add_u32_e32 v58, 0x4000, v116
	v_cvt_pk_bf16_f32 v52, v52, v53
	v_cvt_pk_bf16_f32 v53, v54, v55
	v_cvt_pk_bf16_f32 v48, v48, v49
	v_cvt_pk_bf16_f32 v49, v50, v51
	v_pk_mul_f32 v[60:61], v[60:61], v[66:67] op_sel_hi:[1,0]
	v_pk_mul_f32 v[62:63], v[62:63], v[66:67] op_sel_hi:[1,0]
	ds_write2_b64 v58, v[52:53], v[48:49] offset0:136 offset1:140
	v_add_u32_e32 v48, 0x50, v117
	v_cvt_pk_bf16_f32 v60, v60, v61
	v_cvt_pk_bf16_f32 v61, v62, v63
	v_cmp_gt_u32_e32 vcc, s28, v48
	ds_write2_b64 v58, v[60:61], v[56:57] offset0:128 offset1:132
	s_and_saveexec_b64 s[0:1], vcc
	s_cbranch_execz .LBB0_2096
	v_or_b32_e32 v48, s2, v48
	v_mov_b32_e32 v49, s3
	v_lshlrev_b64 v[48:49], 6, v[48:49]
	v_lshl_add_u64 v[60:61], s[6:7], 0, v[48:49]
	v_bfe_u32 v244, v60, 6, 8
	v_lshlrev_b32_e32 v244, 3, v244
	v_add_u32_e32 v244, 0x24010, v244
	v_or_b32_e32 v246, 4, v60
	ds_read_b64 v[248:249], v244
	s_waitcnt lgkmcnt(0)
	v_cmp_ne_u32_e64 s[100:101], v248, v246
	s_nop 1
	s_and_saveexec_b64 s[98:99], s[100:101]
	s_cbranch_execz .LrcG1_5
	global_load_dwordx4 v[48:51], v[60:61], off
	global_load_dwordx4 v[52:55], v[60:61], off offset:16
	global_load_dwordx4 v[56:59], v[60:61], off offset:32
	s_nop 0
	global_load_dwordx4 v[60:63], v[60:61], off offset:48
	s_waitcnt vmcnt(3)
	v_mov_b32_e32 v64, v49
	v_mov_b32_e32 v65, v50
	v_mov_b32_e32 v49, v51
	s_waitcnt vmcnt(2)
	v_mov_b32_e32 v50, v53
	v_mov_b32_e32 v51, v54
	v_mov_b32_e32 v53, v55
	v_pk_add_f32 v[48:49], v[64:65], v[48:49]
	v_pk_add_f32 v[50:51], v[50:51], v[52:53]
	v_pk_add_f32 v[48:49], v[48:49], v[48:49] op_sel:[0,1] op_sel_hi:[1,0]
	v_pk_add_f32 v[50:51], v[50:51], v[50:51] op_sel:[0,1] op_sel_hi:[1,0]
	s_waitcnt vmcnt(1)
	v_add_f32_e32 v54, v56, v57
	v_add_f32_e32 v56, v58, v59
	s_waitcnt vmcnt(0)
	v_mov_b32_e32 v55, v62
	v_mov_b32_e32 v57, v63
	v_mov_b32_e32 v49, v60
	v_mov_b32_e32 v51, v61
	v_pk_add_f32 v[52:53], v[54:55], v[56:57]
	v_pk_add_f32 v[48:49], v[48:49], v[50:51]
	s_nop 0
	v_pk_add_f32 v[48:49], v[48:49], v[52:53]
	s_nop 0
	v_add_f32_e32 v48, v48, v49
	v_fmamk_f32 v48, v48, 0x3a800000, v168
	v_mul_f32_e32 v49, 0x4b800000, v48
	v_cmp_gt_f32_e32 vcc, s34, v48
	s_nop 1
	s_nop 0
	v_cndmask_b32_e32 v48, v48, v49, vcc
	v_rsq_f32_e32 v48, v48
	s_nop 0
	v_mul_f32_e32 v49, 0x45800000, v48
	v_cndmask_b32_e32 v64, v48, v49, vcc
	s_nop 0
	v_mov_b32_e32 v247, v64
	ds_write_b64 v244, v[246:247]

; DI void store4(bf16_t* dst, const f32x4& v, float s) { *(u32x2*)dst = (u32x2){pk2(v[0] * s, v[1] * s), pk2(v[2] * s, v[3] * s)}; }
; DI float rstd_from16(const float* p, float inv_n) {
;   const f32x4 a = *(const f32x4*)p, b = *(const f32x4*)(p + 4), c = *(const f32x4*)(p + 8), d = *(const f32x4*)(p + 12);
;   const float s = ((a[0] + a[1]) + (a[2] + a[3])) + ((b[0] + b[1]) + (b[2] + b[3])) + ((c[0] + c[1]) + (c[2] + c[3])) + ((d[0] + d[1]) + (d[2] + d[3]));
;   return rsqrtf(s * inv_n + EPS_);
; DI void ffnup_tile(const Params& p, int layer, int b, int mt, int tn, bf16_t* smem) {
;     ...
;     for (int i = 0; i < 8; ++i) {
;       const int row = wm * 128 + i * 16 + l15, s = s0 + row;
;       const float rs = (s >= 0 && s < S_) ? rstd_from16((const float*)(p.ws + O_SSQ) + ((size_t)b * S_ + s) * 16, 1.f / 1024.f) : 0.f;
; #pragma unroll
;       for (int j = 0; j < 4; ++j) store4(dstb + row * LDU + j * 16, acc[i][j], rs);
.LBB0_2096:
	s_or_b64 exec, exec, s[0:1]
	v_pk_mul_f32 v[40:41], v[40:41], v[64:65] op_sel_hi:[1,0]
	v_pk_mul_f32 v[42:43], v[42:43], v[64:65] op_sel_hi:[1,0]
	v_pk_mul_f32 v[36:37], v[36:37], v[64:65] op_sel_hi:[1,0]
	v_pk_mul_f32 v[38:39], v[38:39], v[64:65] op_sel_hi:[1,0]
	v_pk_mul_f32 v[32:33], v[32:33], v[64:65] op_sel_hi:[1,0]
	v_pk_mul_f32 v[34:35], v[34:35], v[64:65] op_sel_hi:[1,0]
	v_cvt_pk_bf16_f32 v40, v40, v41
	v_cvt_pk_bf16_f32 v41, v42, v43
	v_add_u32_e32 v42, 0x5000, v116
	v_cvt_pk_bf16_f32 v36, v36, v37
	v_cvt_pk_bf16_f32 v37, v38, v39
	v_cvt_pk_bf16_f32 v32, v32, v33
	v_cvt_pk_bf16_f32 v33, v34, v35
	v_pk_mul_f32 v[44:45], v[44:45], v[64:65] op_sel_hi:[1,0]
	v_pk_mul_f32 v[46:47], v[46:47], v[64:65] op_sel_hi:[1,0]
	ds_write2_b64 v42, v[36:37], v[32:33] offset0:168 offset1:172
	v_add_u32_e32 v33, 0x60, v117
	v_cvt_pk_bf16_f32 v44, v44, v45
	v_cvt_pk_bf16_f32 v45, v46, v47
	v_cmp_gt_u32_e32 vcc, s28, v33
	v_mov_b32_e32 v32, 0
	v_mov_b32_e32 v34, 0
	ds_write2_b64 v42, v[44:45], v[40:41] offset0:160 offset1:164
	s_and_saveexec_b64 s[0:1], vcc
	s_cbranch_execz .LBB0_2098
	v_or_b32_e32 v34, s2, v33
	v_mov_b32_e32 v35, s3
	v_lshlrev_b64 v[34:35], 6, v[34:35]
	v_lshl_add_u64 v[46:47], s[6:7], 0, v[34:35]
	v_bfe_u32 v244, v46, 6, 8
	v_lshlrev_b32_e32 v244, 3, v244
	v_add_u32_e32 v244, 0x24010, v244
	v_or_b32_e32 v246, 4, v46
	ds_read_b64 v[248:249], v244
	s_waitcnt lgkmcnt(0)
	v_cmp_ne_u32_e64 s[100:101], v248, v246
	s_nop 1
	s_and_saveexec_b64 s[98:99], s[100:101]
	s_cbranch_execz .LrcG1_6
	global_load_dwordx4 v[34:37], v[46:47], off
	global_load_dwordx4 v[38:41], v[46:47], off offset:16
	global_load_dwordx4 v[42:45], v[46:47], off offset:32
	s_nop 0
	global_load_dwordx4 v[46:49], v[46:47], off offset:48
	s_waitcnt vmcnt(3)
	v_mov_b32_e32 v50, v35
	v_mov_b32_e32 v51, v36
	v_mov_b32_e32 v35, v37
	s_waitcnt vmcnt(2)
	v_mov_b32_e32 v36, v39
	v_mov_b32_e32 v37, v40
	v_mov_b32_e32 v39, v41
	v_pk_add_f32 v[34:35], v[50:51], v[34:35]
	v_pk_add_f32 v[36:37], v[36:37], v[38:39]
	v_pk_add_f32 v[34:35], v[34:35], v[34:35] op_sel:[0,1] op_sel_hi:[1,0]
	v_pk_add_f32 v[36:37], v[36:37], v[36:37] op_sel:[0,1] op_sel_hi:[1,0]
	s_waitcnt vmcnt(1)
	v_add_f32_e32 v40, v42, v43
	v_add_f32_e32 v42, v44, v45
	s_waitcnt vmcnt(0)
	v_mov_b32_e32 v41, v48
	v_mov_b32_e32 v43, v49
	v_mov_b32_e32 v35, v46
	v_mov_b32_e32 v37, v47
	v_pk_add_f32 v[38:39], v[40:41], v[42:43]
	v_pk_add_f32 v[34:35], v[34:35], v[36:37]
	s_nop 0
	v_pk_add_f32 v[34:35], v[34:35], v[38:39]
	s_nop 0
	v_add_f32_e32 v33, v34, v35
	v_fmamk_f32 v33, v33, 0x3a800000, v168
	v_mul_f32_e32 v34, 0x4b800000, v33
	v_cmp_gt_f32_e32 vcc, s34, v33
	s_nop 1
	s_nop 0
	v_cndmask_b32_e32 v33, v33, v34, vcc
	v_rsq_f32_e32 v33, v33
	s_nop 0
	v_mul_f32_e32 v34, 0x45800000, v33
	v_cndmask_b32_e32 v34, v33, v34, vcc
	s_nop 0
	v_mov_b32_e32 v247, v34
	ds_write_b64 v244, v[246:247]

; DI void store4(bf16_t* dst, const f32x4& v, float s) { *(u32x2*)dst = (u32x2){pk2(v[0] * s, v[1] * s), pk2(v[2] * s, v[3] * s)}; }
; DI float rstd_from16(const float* p, float inv_n) {
;   const f32x4 a = *(const f32x4*)p, b = *(const f32x4*)(p + 4), c = *(const f32x4*)(p + 8), d = *(const f32x4*)(p + 12);
;   const float s = ((a[0] + a[1]) + (a[2] + a[3])) + ((b[0] + b[1]) + (b[2] + b[3])) + ((c[0] + c[1]) + (c[2] + c[3])) + ((d[0] + d[1]) + (d[2] + d[3]));
;   return rsqrtf(s * inv_n + EPS_);
; DI void ffnup_tile(const Params& p, int layer, int b, int mt, int tn, bf16_t* smem) {
;     ...
;     for (int i = 0; i < 8; ++i) {
;       const int row = wm * 128 + i * 16 + l15, s = s0 + row;
;       const float rs = (s >= 0 && s < S_) ? rstd_from16((const float*)(p.ws + O_SSQ) + ((size_t)b * S_ + s) * 16, 1.f / 1024.f) : 0.f;
; #pragma unroll
;       for (int j = 0; j < 4; ++j) store4(dstb + row * LDU + j * 16, acc[i][j], rs);
.LBB0_2098:
	s_or_b64 exec, exec, s[0:1]
	v_pk_mul_f32 v[24:25], v[24:25], v[34:35] op_sel_hi:[1,0]
	v_pk_mul_f32 v[26:27], v[26:27], v[34:35] op_sel_hi:[1,0]
	v_pk_mul_f32 v[20:21], v[20:21], v[34:35] op_sel_hi:[1,0]
	v_pk_mul_f32 v[22:23], v[22:23], v[34:35] op_sel_hi:[1,0]
	v_pk_mul_f32 v[12:13], v[12:13], v[34:35] op_sel_hi:[1,0]
	v_pk_mul_f32 v[14:15], v[14:15], v[34:35] op_sel_hi:[1,0]
	v_cvt_pk_bf16_f32 v24, v24, v25
	v_cvt_pk_bf16_f32 v25, v26, v27
	v_add_u32_e32 v26, 0x6000, v116
	v_cvt_pk_bf16_f32 v20, v20, v21
	v_cvt_pk_bf16_f32 v21, v22, v23
	v_cvt_pk_bf16_f32 v12, v12, v13
	v_cvt_pk_bf16_f32 v13, v14, v15
	v_pk_mul_f32 v[28:29], v[28:29], v[34:35] op_sel_hi:[1,0]
	v_pk_mul_f32 v[30:31], v[30:31], v[34:35] op_sel_hi:[1,0]
	ds_write2_b64 v26, v[20:21], v[12:13] offset0:200 offset1:204
	v_add_u32_e32 v12, 0x70, v117
	v_cvt_pk_bf16_f32 v28, v28, v29
	v_cvt_pk_bf16_f32 v29, v30, v31
	v_cmp_gt_u32_e32 vcc, s28, v12
	ds_write2_b64 v26, v[28:29], v[24:25] offset0:192 offset1:196
	s_and_saveexec_b64 s[0:1], vcc
	s_cbranch_execz .LBB0_2100
	v_or_b32_e32 v12, s2, v12
	v_mov_b32_e32 v13, s3
	v_lshlrev_b64 v[12:13], 6, v[12:13]
	v_lshl_add_u64 v[28:29], s[6:7], 0, v[12:13]
	v_bfe_u32 v244, v28, 6, 8
	v_lshlrev_b32_e32 v244, 3, v244
	v_add_u32_e32 v244, 0x24010, v244
	v_or_b32_e32 v246, 4, v28
	ds_read_b64 v[248:249], v244
	s_waitcnt lgkmcnt(0)
	v_cmp_ne_u32_e64 s[100:101], v248, v246
	s_nop 1
	s_and_saveexec_b64 s[98:99], s[100:101]
	s_cbranch_execz .LrcG1_7
	global_load_dwordx4 v[12:15], v[28:29], off
	global_load_dwordx4 v[20:23], v[28:29], off offset:16
	global_load_dwordx4 v[24:27], v[28:29], off offset:32
	s_nop 0
	global_load_dwordx4 v[28:31], v[28:29], off offset:48
	s_waitcnt vmcnt(3)
	v_mov_b32_e32 v32, v13
	v_mov_b32_e32 v33, v14
	v_mov_b32_e32 v13, v15
	s_waitcnt vmcnt(2)
	v_mov_b32_e32 v14, v21
	v_mov_b32_e32 v15, v22
	v_mov_b32_e32 v21, v23
	v_pk_add_f32 v[12:13], v[32:33], v[12:13]
	v_pk_add_f32 v[14:15], v[14:15], v[20:21]
	v_pk_add_f32 v[12:13], v[12:13], v[12:13] op_sel:[0,1] op_sel_hi:[1,0]
	v_pk_add_f32 v[14:15], v[14:15], v[14:15] op_sel:[0,1] op_sel_hi:[1,0]
	s_waitcnt vmcnt(1)
	v_add_f32_e32 v22, v24, v25
	v_add_f32_e32 v24, v26, v27
	s_waitcnt vmcnt(0)
	v_mov_b32_e32 v23, v30
	v_mov_b32_e32 v25, v31
	v_mov_b32_e32 v13, v28
	v_mov_b32_e32 v15, v29
	v_pk_add_f32 v[20:21], v[22:23], v[24:25]
	v_pk_add_f32 v[12:13], v[12:13], v[14:15]
	s_nop 0
	v_pk_add_f32 v[12:13], v[12:13], v[20:21]
	s_nop 0
	v_add_f32_e32 v12, v12, v13
	v_fmamk_f32 v12, v12, 0x3a800000, v168
	v_mul_f32_e32 v13, 0x4b800000, v12
	v_cmp_gt_f32_e32 vcc, s34, v12
	s_nop 1
	s_nop 0
	v_cndmask_b32_e32 v12, v12, v13, vcc
	v_rsq_f32_e32 v12, v12
	s_nop 0
	v_mul_f32_e32 v13, 0x45800000, v12
	v_cndmask_b32_e32 v32, v12, v13, vcc
	s_nop 0
	v_mov_b32_e32 v247, v32
	ds_write_b64 v244, v[246:247]
